# GEMM K loops, loop-edge edit (7.11): counter/pointer/exit-test SALU block hoisted from behind the last MFMA segment's barrier into the slack of the last loader segment; plus reads-first loader order a
# speedup vs baseline: 1.0102x; 1.0093x over previous
.LBB0_311:
	v_add_u32_e32 v164, 0x10000, v143
	v_add_u32_e32 v180, 0x14000, v143
	ds_read_b128 v[138:141], v164
	ds_read_b128 v[156:159], v164 offset:1024
	ds_read_b128 v[160:163], v164 offset:2048
	ds_read_b128 v[164:167], v164 offset:3072
	ds_read_b128 v[168:171], v180
	ds_read_b128 v[172:175], v180 offset:1024
	ds_read_b128 v[176:179], v180 offset:2048
	ds_read_b128 v[204:207], v180 offset:3072
	ds_read_b128 v[208:211], v155
	ds_read_b128 v[212:215], v155 offset:1024
	ds_read_b128 v[216:219], v155 offset:2048
	ds_read_b128 v[220:223], v155 offset:3072
	ds_read_b128 v[224:227], v155 offset:4096
	ds_read_b128 v[228:231], v155 offset:5120
	ds_read_b128 v[232:235], v155 offset:6144
	ds_read_b128 v[236:239], v155 offset:7168
	s_add_u32 s4, s62, 0xfffc0080
	s_addc_u32 s5, s63, -1
	s_add_i32 s84, 0, 0x10000
	s_cmp_eq_u32 s82, 12
	s_cselect_b32 s65, s33, s5
	s_cselect_b32 s64, s36, s4
	s_cselect_b32 s35, s53, s79
	s_cselect_b32 s34, s55, s75
	s_add_i32 s4, 0, 0x14000
	v_lshl_add_u64 v[180:181], s[62:63], 0, v[134:135]
	s_add_i32 m0, s68, 0xc000
	s_nop 0
	global_load_lds_dwordx4 v[180:181], off
	v_lshl_add_u64 v[180:181], s[62:63], 0, v[136:137]
	s_add_i32 m0, s68, 0xe000
	s_nop 0
	global_load_lds_dwordx4 v[180:181], off
	s_waitcnt vmcnt(8)
	s_waitcnt lgkmcnt(0)
	s_barrier
	v_mfma_f32_16x16x32_bf16 v[124:127], v[138:141], v[208:211], v[124:127]
	v_mfma_f32_16x16x32_bf16 v[120:123], v[160:163], v[208:211], v[120:123]
	v_mfma_f32_16x16x32_bf16 v[108:111], v[138:141], v[216:219], v[108:111]
	v_mfma_f32_16x16x32_bf16 v[104:107], v[160:163], v[216:219], v[104:107]
	v_mfma_f32_16x16x32_bf16 v[92:95], v[138:141], v[224:227], v[92:95]
	v_mfma_f32_16x16x32_bf16 v[88:91], v[160:163], v[224:227], v[88:91]
	v_mfma_f32_16x16x32_bf16 v[76:79], v[138:141], v[232:235], v[76:79]
	v_mfma_f32_16x16x32_bf16 v[72:75], v[160:163], v[232:235], v[72:75]
	v_mfma_f32_16x16x32_bf16 v[124:127], v[156:159], v[212:215], v[124:127]
	v_mfma_f32_16x16x32_bf16 v[120:123], v[164:167], v[212:215], v[120:123]
	v_mfma_f32_16x16x32_bf16 v[108:111], v[156:159], v[220:223], v[108:111]
	v_mfma_f32_16x16x32_bf16 v[104:107], v[164:167], v[220:223], v[104:107]
	v_mfma_f32_16x16x32_bf16 v[92:95], v[156:159], v[228:231], v[92:95]
	v_mfma_f32_16x16x32_bf16 v[88:91], v[164:167], v[228:231], v[88:91]
	v_mfma_f32_16x16x32_bf16 v[76:79], v[156:159], v[236:239], v[76:79]
	v_mfma_f32_16x16x32_bf16 v[72:75], v[164:167], v[236:239], v[72:75]
	v_mfma_f32_16x16x32_bf16 v[116:119], v[168:171], v[208:211], v[116:119]
	v_mfma_f32_16x16x32_bf16 v[112:115], v[176:179], v[208:211], v[112:115]
	v_mfma_f32_16x16x32_bf16 v[100:103], v[168:171], v[216:219], v[100:103]
	v_mfma_f32_16x16x32_bf16 v[96:99], v[176:179], v[216:219], v[96:99]
	v_mfma_f32_16x16x32_bf16 v[84:87], v[168:171], v[224:227], v[84:87]
	v_mfma_f32_16x16x32_bf16 v[80:83], v[176:179], v[224:227], v[80:83]
	v_mfma_f32_16x16x32_bf16 v[68:71], v[168:171], v[232:235], v[68:71]
	v_mfma_f32_16x16x32_bf16 v[64:67], v[176:179], v[232:235], v[64:67]
	v_mfma_f32_16x16x32_bf16 v[116:119], v[172:175], v[212:215], v[116:119]
	v_mfma_f32_16x16x32_bf16 v[112:115], v[204:207], v[212:215], v[112:115]
	v_mfma_f32_16x16x32_bf16 v[100:103], v[172:175], v[220:223], v[100:103]
	v_mfma_f32_16x16x32_bf16 v[96:99], v[204:207], v[220:223], v[96:99]
	v_mfma_f32_16x16x32_bf16 v[84:87], v[172:175], v[228:231], v[84:87]
	v_mfma_f32_16x16x32_bf16 v[80:83], v[204:207], v[228:231], v[80:83]
	v_mfma_f32_16x16x32_bf16 v[68:71], v[172:175], v[236:239], v[68:71]
	v_mfma_f32_16x16x32_bf16 v[64:67], v[204:207], v[236:239], v[64:67]
	s_barrier
	s_add_i32 s5, s84, s28
	v_lshl_add_u64 v[180:181], s[34:35], 0, v[144:145]
	s_mov_b32 m0, s5
	ds_read_b128 v[208:211], v155 offset:16384
	ds_read_b128 v[212:215], v155 offset:17408
	ds_read_b128 v[216:219], v155 offset:18432
	ds_read_b128 v[220:223], v155 offset:19456
	ds_read_b128 v[224:227], v155 offset:20480
	ds_read_b128 v[228:231], v155 offset:21504
	ds_read_b128 v[232:235], v155 offset:22528
	ds_read_b128 v[236:239], v155 offset:23552
	global_load_lds_dwordx4 v[180:181], off
	s_add_i32 m0, s5, 0x2000
	s_add_u32 s88, s34, 0x40000
	v_lshl_add_u64 v[240:241], s[34:35], 0, v[128:129]
	s_addc_u32 s89, s35, 0
	s_add_i32 s4, s4, s28
	global_load_lds_dwordx4 v[240:241], off
	v_lshl_add_u64 v[242:243], s[88:89], 0, v[144:145]
	s_mov_b32 m0, s4
	v_lshl_add_u64 v[244:245], s[64:65], 0, v[130:131]
	global_load_lds_dwordx4 v[242:243], off
	v_lshl_add_u64 v[242:243], s[88:89], 0, v[128:129]
	s_add_i32 m0, s4, 0x2000
	s_nop 0
	global_load_lds_dwordx4 v[242:243], off
	v_lshl_add_u64 v[242:243], s[64:65], 0, v[132:133]
	s_mov_b32 m0, s68
	s_nop 0
	global_load_lds_dwordx4 v[242:243], off
	s_mov_b32 m0, s69
	s_nop 0
	global_load_lds_dwordx4 v[244:245], off
	s_waitcnt vmcnt(8)
	s_waitcnt lgkmcnt(0)
	s_barrier
	v_mfma_f32_16x16x32_bf16 v[60:63], v[138:141], v[208:211], v[60:63]
	v_mfma_f32_16x16x32_bf16 v[56:59], v[160:163], v[208:211], v[56:59]
	v_mfma_f32_16x16x32_bf16 v[44:47], v[138:141], v[216:219], v[44:47]
	v_mfma_f32_16x16x32_bf16 v[40:43], v[160:163], v[216:219], v[40:43]
	v_mfma_f32_16x16x32_bf16 v[28:31], v[138:141], v[224:227], v[28:31]
	v_mfma_f32_16x16x32_bf16 v[24:27], v[160:163], v[224:227], v[24:27]
	v_mfma_f32_16x16x32_bf16 v[12:15], v[138:141], v[232:235], v[12:15]
	v_mfma_f32_16x16x32_bf16 v[8:11], v[160:163], v[232:235], v[8:11]
	v_mfma_f32_16x16x32_bf16 v[60:63], v[156:159], v[212:215], v[60:63]
	v_mfma_f32_16x16x32_bf16 v[56:59], v[164:167], v[212:215], v[56:59]
	v_mfma_f32_16x16x32_bf16 v[44:47], v[156:159], v[220:223], v[44:47]
	v_mfma_f32_16x16x32_bf16 v[40:43], v[164:167], v[220:223], v[40:43]
	v_mfma_f32_16x16x32_bf16 v[28:31], v[156:159], v[228:231], v[28:31]
	v_mfma_f32_16x16x32_bf16 v[24:27], v[164:167], v[228:231], v[24:27]
	v_mfma_f32_16x16x32_bf16 v[12:15], v[156:159], v[236:239], v[12:15]
	v_mfma_f32_16x16x32_bf16 v[8:11], v[164:167], v[236:239], v[8:11]
	v_mfma_f32_16x16x32_bf16 v[52:55], v[168:171], v[208:211], v[52:55]
	v_mfma_f32_16x16x32_bf16 v[48:51], v[176:179], v[208:211], v[48:51]
	v_mfma_f32_16x16x32_bf16 v[36:39], v[168:171], v[216:219], v[36:39]
	v_mfma_f32_16x16x32_bf16 v[32:35], v[176:179], v[216:219], v[32:35]
	v_mfma_f32_16x16x32_bf16 v[20:23], v[168:171], v[224:227], v[20:23]
	v_mfma_f32_16x16x32_bf16 v[16:19], v[176:179], v[224:227], v[16:19]
	v_mfma_f32_16x16x32_bf16 v[4:7], v[168:171], v[232:235], v[4:7]
	v_mfma_f32_16x16x32_bf16 v[0:3], v[176:179], v[232:235], v[0:3]
	v_mfma_f32_16x16x32_bf16 v[52:55], v[172:175], v[212:215], v[52:55]
	v_mfma_f32_16x16x32_bf16 v[48:51], v[204:207], v[212:215], v[48:51]
	v_mfma_f32_16x16x32_bf16 v[36:39], v[172:175], v[220:223], v[36:39]
	v_mfma_f32_16x16x32_bf16 v[32:35], v[204:207], v[220:223], v[32:35]
	v_mfma_f32_16x16x32_bf16 v[20:23], v[172:175], v[228:231], v[20:23]
	v_mfma_f32_16x16x32_bf16 v[16:19], v[204:207], v[228:231], v[16:19]
	v_mfma_f32_16x16x32_bf16 v[4:7], v[172:175], v[236:239], v[4:7]
	v_mfma_f32_16x16x32_bf16 v[0:3], v[204:207], v[236:239], v[0:3]
	s_barrier
	v_add_u32_e32 v164, 0x18000, v143
	v_add_u32_e32 v202, 0x1c000, v143
	ds_read_b128 v[138:141], v164
	ds_read_b128 v[156:159], v164 offset:1024
	ds_read_b128 v[160:163], v164 offset:2048
	ds_read_b128 v[164:167], v164 offset:3072
	ds_read_b128 v[168:171], v202
	ds_read_b128 v[172:175], v202 offset:1024
	ds_read_b128 v[176:179], v202 offset:2048
	ds_read_b128 v[204:207], v202 offset:3072
	ds_read_b128 v[208:211], v155 offset:32768
	ds_read_b128 v[212:215], v155 offset:33792
	ds_read_b128 v[216:219], v155 offset:34816
	ds_read_b128 v[220:223], v155 offset:35840
	ds_read_b128 v[224:227], v155 offset:36864
	ds_read_b128 v[228:231], v155 offset:37888
	ds_read_b128 v[232:235], v155 offset:38912
	ds_read_b128 v[236:239], v155 offset:39936
	s_add_i32 s4, 0, 0x18000
	s_add_i32 s5, 0, 0x1c000
	s_add_u32 s64, s64, 0x40000
	s_addc_u32 s65, s65, 0
	s_mov_b32 m0, s70
	v_lshl_add_u64 v[246:247], s[64:65], 0, v[132:133]
	global_load_lds_dwordx4 v[246:247], off
	v_lshl_add_u64 v[246:247], s[64:65], 0, v[130:131]
	s_mov_b32 m0, s71
	s_nop 0
	global_load_lds_dwordx4 v[246:247], off
	s_waitcnt vmcnt(8)
	s_waitcnt lgkmcnt(0)
	s_barrier
	v_mfma_f32_16x16x32_bf16 v[124:127], v[138:141], v[208:211], v[124:127]
	v_mfma_f32_16x16x32_bf16 v[120:123], v[160:163], v[208:211], v[120:123]
	v_mfma_f32_16x16x32_bf16 v[108:111], v[138:141], v[216:219], v[108:111]
	v_mfma_f32_16x16x32_bf16 v[104:107], v[160:163], v[216:219], v[104:107]
	v_mfma_f32_16x16x32_bf16 v[92:95], v[138:141], v[224:227], v[92:95]
	v_mfma_f32_16x16x32_bf16 v[88:91], v[160:163], v[224:227], v[88:91]
	v_mfma_f32_16x16x32_bf16 v[76:79], v[138:141], v[232:235], v[76:79]
	v_mfma_f32_16x16x32_bf16 v[72:75], v[160:163], v[232:235], v[72:75]
	v_mfma_f32_16x16x32_bf16 v[124:127], v[156:159], v[212:215], v[124:127]
	v_mfma_f32_16x16x32_bf16 v[120:123], v[164:167], v[212:215], v[120:123]
	v_mfma_f32_16x16x32_bf16 v[108:111], v[156:159], v[220:223], v[108:111]
	v_mfma_f32_16x16x32_bf16 v[104:107], v[164:167], v[220:223], v[104:107]
	v_mfma_f32_16x16x32_bf16 v[92:95], v[156:159], v[228:231], v[92:95]
	v_mfma_f32_16x16x32_bf16 v[88:91], v[164:167], v[228:231], v[88:91]
	v_mfma_f32_16x16x32_bf16 v[76:79], v[156:159], v[236:239], v[76:79]
	v_mfma_f32_16x16x32_bf16 v[72:75], v[164:167], v[236:239], v[72:75]
	v_mfma_f32_16x16x32_bf16 v[116:119], v[168:171], v[208:211], v[116:119]
	v_mfma_f32_16x16x32_bf16 v[112:115], v[176:179], v[208:211], v[112:115]
	v_mfma_f32_16x16x32_bf16 v[100:103], v[168:171], v[216:219], v[100:103]
	v_mfma_f32_16x16x32_bf16 v[96:99], v[176:179], v[216:219], v[96:99]
	v_mfma_f32_16x16x32_bf16 v[84:87], v[168:171], v[224:227], v[84:87]
	v_mfma_f32_16x16x32_bf16 v[80:83], v[176:179], v[224:227], v[80:83]
	v_mfma_f32_16x16x32_bf16 v[68:71], v[168:171], v[232:235], v[68:71]
	v_mfma_f32_16x16x32_bf16 v[64:67], v[176:179], v[232:235], v[64:67]
	v_mfma_f32_16x16x32_bf16 v[116:119], v[172:175], v[212:215], v[116:119]
	v_mfma_f32_16x16x32_bf16 v[112:115], v[204:207], v[212:215], v[112:115]
	v_mfma_f32_16x16x32_bf16 v[100:103], v[172:175], v[220:223], v[100:103]
	v_mfma_f32_16x16x32_bf16 v[96:99], v[204:207], v[220:223], v[96:99]
	v_mfma_f32_16x16x32_bf16 v[84:87], v[172:175], v[228:231], v[84:87]
	v_mfma_f32_16x16x32_bf16 v[80:83], v[204:207], v[228:231], v[80:83]
	v_mfma_f32_16x16x32_bf16 v[68:71], v[172:175], v[236:239], v[68:71]
	v_mfma_f32_16x16x32_bf16 v[64:67], v[204:207], v[236:239], v[64:67]
	s_barrier
	s_add_i32 s4, s4, s28
	v_lshl_add_u64 v[180:181], v[180:181], 0, s[26:27]
	s_mov_b32 m0, s4
	ds_read_b128 v[208:211], v155 offset:49152
	ds_read_b128 v[212:215], v155 offset:50176
	ds_read_b128 v[216:219], v155 offset:51200
	ds_read_b128 v[220:223], v155 offset:52224
	ds_read_b128 v[224:227], v155 offset:53248
	ds_read_b128 v[228:231], v155 offset:54272
	ds_read_b128 v[232:235], v155 offset:55296
	ds_read_b128 v[236:239], v155 offset:56320
	global_load_lds_dwordx4 v[180:181], off
	s_add_i32 m0, s4, 0x2000
	s_add_u32 s34, s34, 0x40080
	v_lshl_add_u64 v[180:181], v[240:241], 0, s[26:27]
	s_addc_u32 s35, s35, 0
	s_add_i32 s4, s5, s28
	global_load_lds_dwordx4 v[180:181], off
	v_lshl_add_u64 v[180:181], s[34:35], 0, v[144:145]
	s_mov_b32 m0, s4
	s_nop 0
	global_load_lds_dwordx4 v[180:181], off
	v_lshl_add_u64 v[180:181], s[34:35], 0, v[128:129]
	s_add_i32 m0, s4, 0x2000
	s_nop 0
	global_load_lds_dwordx4 v[180:181], off
	v_lshl_add_u64 v[180:181], v[242:243], 0, s[26:27]
	s_mov_b32 m0, s72
	s_nop 0
	global_load_lds_dwordx4 v[180:181], off
	v_lshl_add_u64 v[180:181], v[244:245], 0, s[26:27]
	s_mov_b32 m0, s73
	s_nop 0
	global_load_lds_dwordx4 v[180:181], off
	s_add_i32 s82, s82, 2
	s_add_u32 s62, s62, 0x100
	s_addc_u32 s63, s63, 0
	s_add_u32 s75, s75, 0x100
	s_addc_u32 s79, s79, 0
	s_cmp_gt_u32 s82, 13
	s_waitcnt vmcnt(8)
	s_waitcnt lgkmcnt(0)
	s_barrier
	v_mfma_f32_16x16x32_bf16 v[60:63], v[138:141], v[208:211], v[60:63]
	v_mfma_f32_16x16x32_bf16 v[56:59], v[160:163], v[208:211], v[56:59]
	v_mfma_f32_16x16x32_bf16 v[44:47], v[138:141], v[216:219], v[44:47]
	v_mfma_f32_16x16x32_bf16 v[40:43], v[160:163], v[216:219], v[40:43]
	v_mfma_f32_16x16x32_bf16 v[28:31], v[138:141], v[224:227], v[28:31]
	v_mfma_f32_16x16x32_bf16 v[24:27], v[160:163], v[224:227], v[24:27]
	v_mfma_f32_16x16x32_bf16 v[12:15], v[138:141], v[232:235], v[12:15]
	v_mfma_f32_16x16x32_bf16 v[8:11], v[160:163], v[232:235], v[8:11]
	v_mfma_f32_16x16x32_bf16 v[60:63], v[156:159], v[212:215], v[60:63]
	v_mfma_f32_16x16x32_bf16 v[56:59], v[164:167], v[212:215], v[56:59]
	v_mfma_f32_16x16x32_bf16 v[44:47], v[156:159], v[220:223], v[44:47]
	v_mfma_f32_16x16x32_bf16 v[40:43], v[164:167], v[220:223], v[40:43]
	v_mfma_f32_16x16x32_bf16 v[28:31], v[156:159], v[228:231], v[28:31]
	v_mfma_f32_16x16x32_bf16 v[24:27], v[164:167], v[228:231], v[24:27]
	v_mfma_f32_16x16x32_bf16 v[12:15], v[156:159], v[236:239], v[12:15]
	v_mfma_f32_16x16x32_bf16 v[8:11], v[164:167], v[236:239], v[8:11]
	v_mfma_f32_16x16x32_bf16 v[52:55], v[168:171], v[208:211], v[52:55]
	v_mfma_f32_16x16x32_bf16 v[48:51], v[176:179], v[208:211], v[48:51]
	v_mfma_f32_16x16x32_bf16 v[36:39], v[168:171], v[216:219], v[36:39]
	v_mfma_f32_16x16x32_bf16 v[32:35], v[176:179], v[216:219], v[32:35]
	v_mfma_f32_16x16x32_bf16 v[20:23], v[168:171], v[224:227], v[20:23]
	v_mfma_f32_16x16x32_bf16 v[16:19], v[176:179], v[224:227], v[16:19]
	v_mfma_f32_16x16x32_bf16 v[4:7], v[168:171], v[232:235], v[4:7]
	v_mfma_f32_16x16x32_bf16 v[0:3], v[176:179], v[232:235], v[0:3]
	v_mfma_f32_16x16x32_bf16 v[52:55], v[172:175], v[212:215], v[52:55]
	v_mfma_f32_16x16x32_bf16 v[48:51], v[204:207], v[212:215], v[48:51]
	v_mfma_f32_16x16x32_bf16 v[36:39], v[172:175], v[220:223], v[36:39]
	v_mfma_f32_16x16x32_bf16 v[32:35], v[204:207], v[220:223], v[32:35]
	v_mfma_f32_16x16x32_bf16 v[20:23], v[172:175], v[228:231], v[20:23]
	v_mfma_f32_16x16x32_bf16 v[16:19], v[204:207], v[228:231], v[16:19]
	v_mfma_f32_16x16x32_bf16 v[4:7], v[172:175], v[236:239], v[4:7]
	v_mfma_f32_16x16x32_bf16 v[0:3], v[204:207], v[236:239], v[0:3]
	s_barrier
	s_cbranch_scc0 .LBB0_311
	v_lshl_add_u32 v140, s2, 8, v142
	v_ashrrev_i32_e32 v141, 31, v140
	v_lshl_add_u64 v[156:157], v[140:141], 4, s[48:49]
	global_load_dwordx4 v[208:211], v[156:157], off
	global_load_dwordx4 v[212:215], v[156:157], off offset:256
	global_load_dwordx4 v[216:219], v[156:157], off offset:512
	global_load_dwordx4 v[220:223], v[156:157], off offset:768
	global_load_dwordx4 v[224:227], v[156:157], off offset:2048
	global_load_dwordx4 v[228:231], v[156:157], off offset:2304
	global_load_dwordx4 v[232:235], v[156:157], off offset:2560
	global_load_dwordx4 v[236:239], v[156:157], off offset:2816
	s_and_b64 vcc, exec, s[50:51]
	s_cbranch_vccz .LBB0_314
	s_barrier

.LBB0_406:
	v_add_u32_e32 v142, 0x10000, v160
	ds_read_b128 v[138:141], v142
	ds_read_b128 v[154:157], v142 offset:1024
	ds_read_b128 v[172:175], v142 offset:2048
	ds_read_b128 v[176:179], v142 offset:3072
	v_add_u32_e32 v142, 0x14000, v160
	ds_read_b128 v[204:207], v142
	ds_read_b128 v[208:211], v142 offset:1024
	ds_read_b128 v[212:215], v142 offset:2048
	ds_read_b128 v[216:219], v142 offset:3072
	ds_read_b128 v[220:223], v170
	ds_read_b128 v[224:227], v170 offset:1024
	ds_read_b128 v[228:231], v170 offset:2048
	ds_read_b128 v[232:235], v170 offset:3072
	ds_read_b128 v[236:239], v170 offset:4096
	ds_read_b128 v[240:243], v170 offset:5120
	ds_read_b128 v[244:247], v170 offset:6144
	ds_read_b128 v[248:251], v170 offset:7168
	s_add_u32 s62, s60, 0x100
	s_addc_u32 s63, s61, 0
	s_add_i32 s4, 0, 0x10000
	s_cmp_eq_u32 s29, 40
	s_cselect_b32 s65, s45, s63
	s_cselect_b32 s64, s44, s62
	s_cselect_b32 s35, s59, s28
	s_cselect_b32 s34, s58, s3
	s_add_i32 s5, 0, 0x14000
	v_lshl_add_u64 v[142:143], s[60:61], 0, v[134:135]
	s_add_i32 m0, s36, 0xc000
	s_nop 0
	global_load_lds_dwordx4 v[142:143], off
	v_lshl_add_u64 v[142:143], s[60:61], 0, v[136:137]
	s_add_i32 m0, s36, 0xe000
	s_nop 0
	global_load_lds_dwordx4 v[142:143], off
	s_waitcnt vmcnt(8)
	s_waitcnt lgkmcnt(0)
	s_barrier
	v_mfma_f32_16x16x32_bf16 v[124:127], v[138:141], v[220:223], v[124:127]
	v_mfma_f32_16x16x32_bf16 v[120:123], v[172:175], v[220:223], v[120:123]
	v_mfma_f32_16x16x32_bf16 v[108:111], v[138:141], v[228:231], v[108:111]
	v_mfma_f32_16x16x32_bf16 v[104:107], v[172:175], v[228:231], v[104:107]
	v_mfma_f32_16x16x32_bf16 v[92:95], v[138:141], v[236:239], v[92:95]
	v_mfma_f32_16x16x32_bf16 v[88:91], v[172:175], v[236:239], v[88:91]
	v_mfma_f32_16x16x32_bf16 v[76:79], v[138:141], v[244:247], v[76:79]
	v_mfma_f32_16x16x32_bf16 v[72:75], v[172:175], v[244:247], v[72:75]
	v_mfma_f32_16x16x32_bf16 v[124:127], v[154:157], v[224:227], v[124:127]
	v_mfma_f32_16x16x32_bf16 v[120:123], v[176:179], v[224:227], v[120:123]
	v_mfma_f32_16x16x32_bf16 v[108:111], v[154:157], v[232:235], v[108:111]
	v_mfma_f32_16x16x32_bf16 v[104:107], v[176:179], v[232:235], v[104:107]
	v_mfma_f32_16x16x32_bf16 v[92:95], v[154:157], v[240:243], v[92:95]
	v_mfma_f32_16x16x32_bf16 v[88:91], v[176:179], v[240:243], v[88:91]
	v_mfma_f32_16x16x32_bf16 v[76:79], v[154:157], v[248:251], v[76:79]
	v_mfma_f32_16x16x32_bf16 v[72:75], v[176:179], v[248:251], v[72:75]
	v_mfma_f32_16x16x32_bf16 v[116:119], v[204:207], v[220:223], v[116:119]
	v_mfma_f32_16x16x32_bf16 v[112:115], v[212:215], v[220:223], v[112:115]
	v_mfma_f32_16x16x32_bf16 v[100:103], v[204:207], v[228:231], v[100:103]
	v_mfma_f32_16x16x32_bf16 v[96:99], v[212:215], v[228:231], v[96:99]
	v_mfma_f32_16x16x32_bf16 v[84:87], v[204:207], v[236:239], v[84:87]
	v_mfma_f32_16x16x32_bf16 v[80:83], v[212:215], v[236:239], v[80:83]
	v_mfma_f32_16x16x32_bf16 v[68:71], v[204:207], v[244:247], v[68:71]
	v_mfma_f32_16x16x32_bf16 v[64:67], v[212:215], v[244:247], v[64:67]
	v_mfma_f32_16x16x32_bf16 v[116:119], v[208:211], v[224:227], v[116:119]
	v_mfma_f32_16x16x32_bf16 v[112:115], v[216:219], v[224:227], v[112:115]
	v_mfma_f32_16x16x32_bf16 v[100:103], v[208:211], v[232:235], v[100:103]
	v_mfma_f32_16x16x32_bf16 v[96:99], v[216:219], v[232:235], v[96:99]
	v_mfma_f32_16x16x32_bf16 v[84:87], v[208:211], v[240:243], v[84:87]
	v_mfma_f32_16x16x32_bf16 v[80:83], v[216:219], v[240:243], v[80:83]
	v_mfma_f32_16x16x32_bf16 v[68:71], v[208:211], v[248:251], v[68:71]
	v_mfma_f32_16x16x32_bf16 v[64:67], v[216:219], v[248:251], v[64:67]
	s_barrier
	s_add_i32 s4, s4, s33
	v_lshl_add_u64 v[142:143], s[34:35], 0, v[128:129]
	s_mov_b32 m0, s4
	ds_read_b128 v[220:223], v170 offset:16384
	ds_read_b128 v[224:227], v170 offset:17408
	ds_read_b128 v[228:231], v170 offset:18432
	ds_read_b128 v[232:235], v170 offset:19456
	ds_read_b128 v[236:239], v170 offset:20480
	ds_read_b128 v[240:243], v170 offset:21504
	ds_read_b128 v[244:247], v170 offset:22528
	ds_read_b128 v[248:251], v170 offset:23552
	global_load_lds_dwordx4 v[142:143], off
	s_add_i32 m0, s4, 0x2000
	s_add_u32 s60, s34, 0xb0000
	v_lshl_add_u64 v[158:159], s[34:35], 0, v[130:131]
	s_addc_u32 s61, s35, 0
	s_add_i32 s4, s5, s33
	global_load_lds_dwordx4 v[158:159], off
	v_lshl_add_u64 v[180:181], s[60:61], 0, v[128:129]
	s_mov_b32 m0, s4
	v_lshl_add_u64 v[202:203], s[64:65], 0, v[130:131]
	global_load_lds_dwordx4 v[180:181], off
	v_lshl_add_u64 v[180:181], s[60:61], 0, v[130:131]
	s_add_i32 m0, s4, 0x2000
	s_nop 0
	global_load_lds_dwordx4 v[180:181], off
	v_lshl_add_u64 v[180:181], s[64:65], 0, v[128:129]
	s_mov_b32 m0, s36
	s_nop 0
	global_load_lds_dwordx4 v[180:181], off
	s_mov_b32 m0, s70
	s_nop 0
	global_load_lds_dwordx4 v[202:203], off
	s_waitcnt vmcnt(8)
	s_waitcnt lgkmcnt(0)
	s_barrier
	v_mfma_f32_16x16x32_bf16 v[60:63], v[138:141], v[220:223], v[60:63]
	v_mfma_f32_16x16x32_bf16 v[56:59], v[172:175], v[220:223], v[56:59]
	v_mfma_f32_16x16x32_bf16 v[44:47], v[138:141], v[228:231], v[44:47]
	v_mfma_f32_16x16x32_bf16 v[40:43], v[172:175], v[228:231], v[40:43]
	v_mfma_f32_16x16x32_bf16 v[28:31], v[138:141], v[236:239], v[28:31]
	v_mfma_f32_16x16x32_bf16 v[24:27], v[172:175], v[236:239], v[24:27]
	v_mfma_f32_16x16x32_bf16 v[12:15], v[138:141], v[244:247], v[12:15]
	v_mfma_f32_16x16x32_bf16 v[8:11], v[172:175], v[244:247], v[8:11]
	v_mfma_f32_16x16x32_bf16 v[60:63], v[154:157], v[224:227], v[60:63]
	v_mfma_f32_16x16x32_bf16 v[56:59], v[176:179], v[224:227], v[56:59]
	v_mfma_f32_16x16x32_bf16 v[44:47], v[154:157], v[232:235], v[44:47]
	v_mfma_f32_16x16x32_bf16 v[40:43], v[176:179], v[232:235], v[40:43]
	v_mfma_f32_16x16x32_bf16 v[28:31], v[154:157], v[240:243], v[28:31]
	v_mfma_f32_16x16x32_bf16 v[24:27], v[176:179], v[240:243], v[24:27]
	v_mfma_f32_16x16x32_bf16 v[12:15], v[154:157], v[248:251], v[12:15]
	v_mfma_f32_16x16x32_bf16 v[8:11], v[176:179], v[248:251], v[8:11]
	v_mfma_f32_16x16x32_bf16 v[52:55], v[204:207], v[220:223], v[52:55]
	v_mfma_f32_16x16x32_bf16 v[48:51], v[212:215], v[220:223], v[48:51]
	v_mfma_f32_16x16x32_bf16 v[36:39], v[204:207], v[228:231], v[36:39]
	v_mfma_f32_16x16x32_bf16 v[32:35], v[212:215], v[228:231], v[32:35]
	v_mfma_f32_16x16x32_bf16 v[20:23], v[204:207], v[236:239], v[20:23]
	v_mfma_f32_16x16x32_bf16 v[16:19], v[212:215], v[236:239], v[16:19]
	v_mfma_f32_16x16x32_bf16 v[4:7], v[204:207], v[244:247], v[4:7]
	v_mfma_f32_16x16x32_bf16 v[0:3], v[212:215], v[244:247], v[0:3]
	v_mfma_f32_16x16x32_bf16 v[52:55], v[208:211], v[224:227], v[52:55]
	v_mfma_f32_16x16x32_bf16 v[48:51], v[216:219], v[224:227], v[48:51]
	v_mfma_f32_16x16x32_bf16 v[36:39], v[208:211], v[232:235], v[36:39]
	v_mfma_f32_16x16x32_bf16 v[32:35], v[216:219], v[232:235], v[32:35]
	v_mfma_f32_16x16x32_bf16 v[20:23], v[208:211], v[240:243], v[20:23]
	v_mfma_f32_16x16x32_bf16 v[16:19], v[216:219], v[240:243], v[16:19]
	v_mfma_f32_16x16x32_bf16 v[4:7], v[208:211], v[248:251], v[4:7]
	v_mfma_f32_16x16x32_bf16 v[0:3], v[216:219], v[248:251], v[0:3]
	s_barrier
	v_add_u32_e32 v144, 0x18000, v160
	ds_read_b128 v[138:141], v144
	ds_read_b128 v[154:157], v144 offset:1024
	ds_read_b128 v[172:175], v144 offset:2048
	ds_read_b128 v[176:179], v144 offset:3072
	v_add_u32_e32 v144, 0x1c000, v160
	ds_read_b128 v[204:207], v144
	ds_read_b128 v[208:211], v144 offset:1024
	ds_read_b128 v[212:215], v144 offset:2048
	ds_read_b128 v[216:219], v144 offset:3072
	ds_read_b128 v[220:223], v170 offset:32768
	ds_read_b128 v[224:227], v170 offset:33792
	ds_read_b128 v[228:231], v170 offset:34816
	ds_read_b128 v[232:235], v170 offset:35840
	ds_read_b128 v[236:239], v170 offset:36864
	ds_read_b128 v[240:243], v170 offset:37888
	ds_read_b128 v[244:247], v170 offset:38912
	ds_read_b128 v[248:251], v170 offset:39936
	s_add_i32 s4, 0, 0x18000
	s_add_i32 s5, 0, 0x1c000
	s_add_u32 s60, s64, 0xb0000
	s_addc_u32 s61, s65, 0
	s_mov_b32 m0, s71
	v_lshl_add_u64 v[252:253], s[60:61], 0, v[128:129]
	global_load_lds_dwordx4 v[252:253], off
	v_lshl_add_u64 v[252:253], s[60:61], 0, v[130:131]
	s_mov_b32 m0, s72
	s_nop 0
	global_load_lds_dwordx4 v[252:253], off
	s_waitcnt vmcnt(8)
	s_waitcnt lgkmcnt(0)
	s_barrier
	v_mfma_f32_16x16x32_bf16 v[124:127], v[138:141], v[220:223], v[124:127]
	v_mfma_f32_16x16x32_bf16 v[120:123], v[172:175], v[220:223], v[120:123]
	v_mfma_f32_16x16x32_bf16 v[108:111], v[138:141], v[228:231], v[108:111]
	v_mfma_f32_16x16x32_bf16 v[104:107], v[172:175], v[228:231], v[104:107]
	v_mfma_f32_16x16x32_bf16 v[92:95], v[138:141], v[236:239], v[92:95]
	v_mfma_f32_16x16x32_bf16 v[88:91], v[172:175], v[236:239], v[88:91]
	v_mfma_f32_16x16x32_bf16 v[76:79], v[138:141], v[244:247], v[76:79]
	v_mfma_f32_16x16x32_bf16 v[72:75], v[172:175], v[244:247], v[72:75]
	v_mfma_f32_16x16x32_bf16 v[124:127], v[154:157], v[224:227], v[124:127]
	v_mfma_f32_16x16x32_bf16 v[120:123], v[176:179], v[224:227], v[120:123]
	v_mfma_f32_16x16x32_bf16 v[108:111], v[154:157], v[232:235], v[108:111]
	v_mfma_f32_16x16x32_bf16 v[104:107], v[176:179], v[232:235], v[104:107]
	v_mfma_f32_16x16x32_bf16 v[92:95], v[154:157], v[240:243], v[92:95]
	v_mfma_f32_16x16x32_bf16 v[88:91], v[176:179], v[240:243], v[88:91]
	v_mfma_f32_16x16x32_bf16 v[76:79], v[154:157], v[248:251], v[76:79]
	v_mfma_f32_16x16x32_bf16 v[72:75], v[176:179], v[248:251], v[72:75]
	v_mfma_f32_16x16x32_bf16 v[116:119], v[204:207], v[220:223], v[116:119]
	v_mfma_f32_16x16x32_bf16 v[112:115], v[212:215], v[220:223], v[112:115]
	v_mfma_f32_16x16x32_bf16 v[100:103], v[204:207], v[228:231], v[100:103]
	v_mfma_f32_16x16x32_bf16 v[96:99], v[212:215], v[228:231], v[96:99]
	v_mfma_f32_16x16x32_bf16 v[84:87], v[204:207], v[236:239], v[84:87]
	v_mfma_f32_16x16x32_bf16 v[80:83], v[212:215], v[236:239], v[80:83]
	v_mfma_f32_16x16x32_bf16 v[68:71], v[204:207], v[244:247], v[68:71]
	v_mfma_f32_16x16x32_bf16 v[64:67], v[212:215], v[244:247], v[64:67]
	v_mfma_f32_16x16x32_bf16 v[116:119], v[208:211], v[224:227], v[116:119]
	v_mfma_f32_16x16x32_bf16 v[112:115], v[216:219], v[224:227], v[112:115]
	v_mfma_f32_16x16x32_bf16 v[100:103], v[208:211], v[232:235], v[100:103]
	v_mfma_f32_16x16x32_bf16 v[96:99], v[216:219], v[232:235], v[96:99]
	v_mfma_f32_16x16x32_bf16 v[84:87], v[208:211], v[240:243], v[84:87]
	v_mfma_f32_16x16x32_bf16 v[80:83], v[216:219], v[240:243], v[80:83]
	v_mfma_f32_16x16x32_bf16 v[68:71], v[208:211], v[248:251], v[68:71]
	v_mfma_f32_16x16x32_bf16 v[64:67], v[216:219], v[248:251], v[64:67]
	s_barrier
	s_add_i32 s4, s4, s33
	v_lshl_add_u64 v[142:143], v[142:143], 0, s[26:27]
	s_mov_b32 m0, s4
	ds_read_b128 v[220:223], v170 offset:49152
	ds_read_b128 v[224:227], v170 offset:50176
	ds_read_b128 v[228:231], v170 offset:51200
	ds_read_b128 v[232:235], v170 offset:52224
	ds_read_b128 v[236:239], v170 offset:53248
	ds_read_b128 v[240:243], v170 offset:54272
	ds_read_b128 v[244:247], v170 offset:55296
	ds_read_b128 v[248:251], v170 offset:56320
	global_load_lds_dwordx4 v[142:143], off
	s_add_i32 m0, s4, 0x2000
	s_add_u32 s34, s34, 0xb0080
	v_lshl_add_u64 v[142:143], v[158:159], 0, s[26:27]
	s_addc_u32 s35, s35, 0
	s_add_i32 s4, s5, s33
	global_load_lds_dwordx4 v[142:143], off
	v_lshl_add_u64 v[142:143], s[34:35], 0, v[128:129]
	s_mov_b32 m0, s4
	s_nop 0
	global_load_lds_dwordx4 v[142:143], off
	v_lshl_add_u64 v[142:143], s[34:35], 0, v[130:131]
	s_add_i32 m0, s4, 0x2000
	s_nop 0
	global_load_lds_dwordx4 v[142:143], off
	v_lshl_add_u64 v[142:143], v[180:181], 0, s[26:27]
	s_mov_b32 m0, s73
	s_nop 0
	global_load_lds_dwordx4 v[142:143], off
	v_lshl_add_u64 v[142:143], v[202:203], 0, s[26:27]
	s_mov_b32 m0, s74
	s_nop 0
	global_load_lds_dwordx4 v[142:143], off
	s_add_i32 s29, s29, 2
	s_add_u32 s3, s3, 0x100
	s_addc_u32 s28, s28, 0
	s_cmp_gt_u32 s29, 41
	s_mov_b64 s[60:61], s[62:63]
	s_waitcnt vmcnt(8)
	s_waitcnt lgkmcnt(0)
	s_barrier
	v_mfma_f32_16x16x32_bf16 v[60:63], v[138:141], v[220:223], v[60:63]
	v_mfma_f32_16x16x32_bf16 v[56:59], v[172:175], v[220:223], v[56:59]
	v_mfma_f32_16x16x32_bf16 v[44:47], v[138:141], v[228:231], v[44:47]
	v_mfma_f32_16x16x32_bf16 v[40:43], v[172:175], v[228:231], v[40:43]
	v_mfma_f32_16x16x32_bf16 v[28:31], v[138:141], v[236:239], v[28:31]
	v_mfma_f32_16x16x32_bf16 v[24:27], v[172:175], v[236:239], v[24:27]
	v_mfma_f32_16x16x32_bf16 v[12:15], v[138:141], v[244:247], v[12:15]
	v_mfma_f32_16x16x32_bf16 v[8:11], v[172:175], v[244:247], v[8:11]
	v_mfma_f32_16x16x32_bf16 v[60:63], v[154:157], v[224:227], v[60:63]
	v_mfma_f32_16x16x32_bf16 v[56:59], v[176:179], v[224:227], v[56:59]
	v_mfma_f32_16x16x32_bf16 v[44:47], v[154:157], v[232:235], v[44:47]
	v_mfma_f32_16x16x32_bf16 v[40:43], v[176:179], v[232:235], v[40:43]
	v_mfma_f32_16x16x32_bf16 v[28:31], v[154:157], v[240:243], v[28:31]
	v_mfma_f32_16x16x32_bf16 v[24:27], v[176:179], v[240:243], v[24:27]
	v_mfma_f32_16x16x32_bf16 v[12:15], v[154:157], v[248:251], v[12:15]
	v_mfma_f32_16x16x32_bf16 v[8:11], v[176:179], v[248:251], v[8:11]
	v_mfma_f32_16x16x32_bf16 v[52:55], v[204:207], v[220:223], v[52:55]
	v_mfma_f32_16x16x32_bf16 v[48:51], v[212:215], v[220:223], v[48:51]
	v_mfma_f32_16x16x32_bf16 v[36:39], v[204:207], v[228:231], v[36:39]
	v_mfma_f32_16x16x32_bf16 v[32:35], v[212:215], v[228:231], v[32:35]
	v_mfma_f32_16x16x32_bf16 v[20:23], v[204:207], v[236:239], v[20:23]
	v_mfma_f32_16x16x32_bf16 v[16:19], v[212:215], v[236:239], v[16:19]
	v_mfma_f32_16x16x32_bf16 v[4:7], v[204:207], v[244:247], v[4:7]
	v_mfma_f32_16x16x32_bf16 v[0:3], v[212:215], v[244:247], v[0:3]
	v_mfma_f32_16x16x32_bf16 v[52:55], v[208:211], v[224:227], v[52:55]
	v_mfma_f32_16x16x32_bf16 v[48:51], v[216:219], v[224:227], v[48:51]
	v_mfma_f32_16x16x32_bf16 v[36:39], v[208:211], v[232:235], v[36:39]
	v_mfma_f32_16x16x32_bf16 v[32:35], v[216:219], v[232:235], v[32:35]
	v_mfma_f32_16x16x32_bf16 v[20:23], v[208:211], v[240:243], v[20:23]
	v_mfma_f32_16x16x32_bf16 v[16:19], v[216:219], v[240:243], v[16:19]
	v_mfma_f32_16x16x32_bf16 v[4:7], v[208:211], v[248:251], v[4:7]
	v_mfma_f32_16x16x32_bf16 v[0:3], v[216:219], v[248:251], v[0:3]
	s_barrier
	s_cbranch_scc0 .LBB0_406
	s_and_b64 vcc, exec, s[54:55]
	s_cbranch_vccz .LBB0_409
	s_barrier

.LBB0_456:
	v_add_u32_e32 v140, 0x10000, v166
	v_add_u32_e32 v144, 0x14000, v166
	ds_read_b128 v[128:131], v140
	ds_read_b128 v[132:135], v140 offset:1024
	ds_read_b128 v[136:139], v140 offset:2048
	ds_read_b128 v[140:143], v140 offset:3072
	ds_read_b128 v[178:181], v144
	ds_read_b128 v[204:207], v144 offset:1024
	ds_read_b128 v[208:211], v144 offset:2048
	ds_read_b128 v[212:215], v144 offset:3072
	ds_read_b128 v[216:219], v176
	ds_read_b128 v[220:223], v176 offset:1024
	ds_read_b128 v[224:227], v176 offset:2048
	ds_read_b128 v[228:231], v176 offset:3072
	ds_read_b128 v[232:235], v176 offset:4096
	ds_read_b128 v[236:239], v176 offset:5120
	ds_read_b128 v[240:243], v176 offset:6144
	ds_read_b128 v[244:247], v176 offset:7168
	s_add_u32 s60, s58, 0x100
	s_addc_u32 s61, s59, 0
	s_add_i32 s4, 0, 0x10000
	s_cmp_eq_u32 s51, 40
	s_cselect_b32 s63, s45, s61
	s_cselect_b32 s62, s44, s60
	s_cselect_b32 s35, s47, s29
	s_cselect_b32 s34, s46, s28
	s_add_i32 s5, 0, 0x14000
	v_lshl_add_u64 v[164:165], s[58:59], 0, v[160:161]
	s_add_i32 m0, s36, 0xc000
	s_nop 0
	global_load_lds_dwordx4 v[164:165], off
	v_lshl_add_u64 v[164:165], s[58:59], 0, v[162:163]
	s_add_i32 m0, s36, 0xe000
	s_nop 0
	global_load_lds_dwordx4 v[164:165], off
	s_waitcnt vmcnt(8)
	s_waitcnt lgkmcnt(0)
	s_barrier
	v_mfma_f32_16x16x32_bf16 v[124:127], v[128:131], v[216:219], v[124:127]
	v_mfma_f32_16x16x32_bf16 v[120:123], v[136:139], v[216:219], v[120:123]
	v_mfma_f32_16x16x32_bf16 v[108:111], v[128:131], v[224:227], v[108:111]
	v_mfma_f32_16x16x32_bf16 v[104:107], v[136:139], v[224:227], v[104:107]
	v_mfma_f32_16x16x32_bf16 v[92:95], v[128:131], v[232:235], v[92:95]
	v_mfma_f32_16x16x32_bf16 v[88:91], v[136:139], v[232:235], v[88:91]
	v_mfma_f32_16x16x32_bf16 v[76:79], v[128:131], v[240:243], v[76:79]
	v_mfma_f32_16x16x32_bf16 v[72:75], v[136:139], v[240:243], v[72:75]
	v_mfma_f32_16x16x32_bf16 v[124:127], v[132:135], v[220:223], v[124:127]
	v_mfma_f32_16x16x32_bf16 v[120:123], v[140:143], v[220:223], v[120:123]
	v_mfma_f32_16x16x32_bf16 v[108:111], v[132:135], v[228:231], v[108:111]
	v_mfma_f32_16x16x32_bf16 v[104:107], v[140:143], v[228:231], v[104:107]
	v_mfma_f32_16x16x32_bf16 v[92:95], v[132:135], v[236:239], v[92:95]
	v_mfma_f32_16x16x32_bf16 v[88:91], v[140:143], v[236:239], v[88:91]
	v_mfma_f32_16x16x32_bf16 v[76:79], v[132:135], v[244:247], v[76:79]
	v_mfma_f32_16x16x32_bf16 v[72:75], v[140:143], v[244:247], v[72:75]
	v_mfma_f32_16x16x32_bf16 v[116:119], v[178:181], v[216:219], v[116:119]
	v_mfma_f32_16x16x32_bf16 v[112:115], v[208:211], v[216:219], v[112:115]
	v_mfma_f32_16x16x32_bf16 v[100:103], v[178:181], v[224:227], v[100:103]
	v_mfma_f32_16x16x32_bf16 v[96:99], v[208:211], v[224:227], v[96:99]
	v_mfma_f32_16x16x32_bf16 v[84:87], v[178:181], v[232:235], v[84:87]
	v_mfma_f32_16x16x32_bf16 v[80:83], v[208:211], v[232:235], v[80:83]
	v_mfma_f32_16x16x32_bf16 v[68:71], v[178:181], v[240:243], v[68:71]
	v_mfma_f32_16x16x32_bf16 v[64:67], v[208:211], v[240:243], v[64:67]
	v_mfma_f32_16x16x32_bf16 v[116:119], v[204:207], v[220:223], v[116:119]
	v_mfma_f32_16x16x32_bf16 v[112:115], v[212:215], v[220:223], v[112:115]
	v_mfma_f32_16x16x32_bf16 v[100:103], v[204:207], v[228:231], v[100:103]
	v_mfma_f32_16x16x32_bf16 v[96:99], v[212:215], v[228:231], v[96:99]
	v_mfma_f32_16x16x32_bf16 v[84:87], v[204:207], v[236:239], v[84:87]
	v_mfma_f32_16x16x32_bf16 v[80:83], v[212:215], v[236:239], v[80:83]
	v_mfma_f32_16x16x32_bf16 v[68:71], v[204:207], v[244:247], v[68:71]
	v_mfma_f32_16x16x32_bf16 v[64:67], v[212:215], v[244:247], v[64:67]
	s_barrier
	s_add_i32 s4, s4, s33
	v_lshl_add_u64 v[164:165], s[34:35], 0, v[154:155]
	s_mov_b32 m0, s4
	ds_read_b128 v[216:219], v176 offset:16384
	ds_read_b128 v[220:223], v176 offset:17408
	ds_read_b128 v[224:227], v176 offset:18432
	ds_read_b128 v[228:231], v176 offset:19456
	ds_read_b128 v[232:235], v176 offset:20480
	ds_read_b128 v[236:239], v176 offset:21504
	ds_read_b128 v[240:243], v176 offset:22528
	ds_read_b128 v[244:247], v176 offset:23552
	global_load_lds_dwordx4 v[164:165], off
	s_add_i32 m0, s4, 0x2000
	s_add_u32 s58, s34, 0xb0000
	v_lshl_add_u64 v[248:249], s[34:35], 0, v[156:157]
	s_addc_u32 s59, s35, 0
	s_add_i32 s4, s5, s33
	global_load_lds_dwordx4 v[248:249], off
	v_lshl_add_u64 v[250:251], s[58:59], 0, v[154:155]
	s_mov_b32 m0, s4
	v_lshl_add_u64 v[252:253], s[62:63], 0, v[156:157]
	global_load_lds_dwordx4 v[250:251], off
	v_lshl_add_u64 v[250:251], s[58:59], 0, v[156:157]
	s_add_i32 m0, s4, 0x2000
	s_nop 0
	global_load_lds_dwordx4 v[250:251], off
	v_lshl_add_u64 v[250:251], s[62:63], 0, v[154:155]
	s_mov_b32 m0, s36
	s_nop 0
	global_load_lds_dwordx4 v[250:251], off
	s_mov_b32 m0, s64
	s_nop 0
	global_load_lds_dwordx4 v[252:253], off
	s_waitcnt vmcnt(8)
	s_waitcnt lgkmcnt(0)
	s_barrier
	v_mfma_f32_16x16x32_bf16 v[60:63], v[128:131], v[216:219], v[60:63]
	v_mfma_f32_16x16x32_bf16 v[56:59], v[136:139], v[216:219], v[56:59]
	v_mfma_f32_16x16x32_bf16 v[44:47], v[128:131], v[224:227], v[44:47]
	v_mfma_f32_16x16x32_bf16 v[40:43], v[136:139], v[224:227], v[40:43]
	v_mfma_f32_16x16x32_bf16 v[28:31], v[128:131], v[232:235], v[28:31]
	v_mfma_f32_16x16x32_bf16 v[24:27], v[136:139], v[232:235], v[24:27]
	v_mfma_f32_16x16x32_bf16 v[12:15], v[128:131], v[240:243], v[12:15]
	v_mfma_f32_16x16x32_bf16 v[8:11], v[136:139], v[240:243], v[8:11]
	v_mfma_f32_16x16x32_bf16 v[60:63], v[132:135], v[220:223], v[60:63]
	v_mfma_f32_16x16x32_bf16 v[56:59], v[140:143], v[220:223], v[56:59]
	v_mfma_f32_16x16x32_bf16 v[44:47], v[132:135], v[228:231], v[44:47]
	v_mfma_f32_16x16x32_bf16 v[40:43], v[140:143], v[228:231], v[40:43]
	v_mfma_f32_16x16x32_bf16 v[28:31], v[132:135], v[236:239], v[28:31]
	v_mfma_f32_16x16x32_bf16 v[24:27], v[140:143], v[236:239], v[24:27]
	v_mfma_f32_16x16x32_bf16 v[12:15], v[132:135], v[244:247], v[12:15]
	v_mfma_f32_16x16x32_bf16 v[8:11], v[140:143], v[244:247], v[8:11]
	v_mfma_f32_16x16x32_bf16 v[52:55], v[178:181], v[216:219], v[52:55]
	v_mfma_f32_16x16x32_bf16 v[48:51], v[208:211], v[216:219], v[48:51]
	v_mfma_f32_16x16x32_bf16 v[36:39], v[178:181], v[224:227], v[36:39]
	v_mfma_f32_16x16x32_bf16 v[32:35], v[208:211], v[224:227], v[32:35]
	v_mfma_f32_16x16x32_bf16 v[20:23], v[178:181], v[232:235], v[20:23]
	v_mfma_f32_16x16x32_bf16 v[16:19], v[208:211], v[232:235], v[16:19]
	v_mfma_f32_16x16x32_bf16 v[4:7], v[178:181], v[240:243], v[4:7]
	v_mfma_f32_16x16x32_bf16 v[0:3], v[208:211], v[240:243], v[0:3]
	v_mfma_f32_16x16x32_bf16 v[52:55], v[204:207], v[220:223], v[52:55]
	v_mfma_f32_16x16x32_bf16 v[48:51], v[212:215], v[220:223], v[48:51]
	v_mfma_f32_16x16x32_bf16 v[36:39], v[204:207], v[228:231], v[36:39]
	v_mfma_f32_16x16x32_bf16 v[32:35], v[212:215], v[228:231], v[32:35]
	v_mfma_f32_16x16x32_bf16 v[20:23], v[204:207], v[236:239], v[20:23]
	v_mfma_f32_16x16x32_bf16 v[16:19], v[212:215], v[236:239], v[16:19]
	v_mfma_f32_16x16x32_bf16 v[4:7], v[204:207], v[244:247], v[4:7]
	v_mfma_f32_16x16x32_bf16 v[0:3], v[212:215], v[244:247], v[0:3]
	s_barrier
	v_add_u32_e32 v140, 0x18000, v166
	v_add_u32_e32 v144, 0x1c000, v166
	ds_read_b128 v[128:131], v140
	ds_read_b128 v[132:135], v140 offset:1024
	ds_read_b128 v[136:139], v140 offset:2048
	ds_read_b128 v[140:143], v140 offset:3072
	ds_read_b128 v[178:181], v144
	ds_read_b128 v[204:207], v144 offset:1024
	ds_read_b128 v[208:211], v144 offset:2048
	ds_read_b128 v[212:215], v144 offset:3072
	ds_read_b128 v[216:219], v176 offset:32768
	ds_read_b128 v[220:223], v176 offset:33792
	ds_read_b128 v[224:227], v176 offset:34816
	ds_read_b128 v[228:231], v176 offset:35840
	ds_read_b128 v[232:235], v176 offset:36864
	ds_read_b128 v[236:239], v176 offset:37888
	ds_read_b128 v[240:243], v176 offset:38912
	ds_read_b128 v[244:247], v176 offset:39936
	s_add_i32 s4, 0, 0x18000
	s_add_i32 s5, 0, 0x1c000
	s_add_u32 s58, s62, 0xb0000
	s_addc_u32 s59, s63, 0
	s_mov_b32 m0, s65
	v_lshl_add_u64 v[202:203], s[58:59], 0, v[154:155]
	global_load_lds_dwordx4 v[202:203], off
	v_lshl_add_u64 v[202:203], s[58:59], 0, v[156:157]
	s_mov_b32 m0, s70
	s_nop 0
	global_load_lds_dwordx4 v[202:203], off
	s_waitcnt vmcnt(8)
	s_waitcnt lgkmcnt(0)
	s_barrier
	v_mfma_f32_16x16x32_bf16 v[124:127], v[128:131], v[216:219], v[124:127]
	v_mfma_f32_16x16x32_bf16 v[120:123], v[136:139], v[216:219], v[120:123]
	v_mfma_f32_16x16x32_bf16 v[108:111], v[128:131], v[224:227], v[108:111]
	v_mfma_f32_16x16x32_bf16 v[104:107], v[136:139], v[224:227], v[104:107]
	v_mfma_f32_16x16x32_bf16 v[92:95], v[128:131], v[232:235], v[92:95]
	v_mfma_f32_16x16x32_bf16 v[88:91], v[136:139], v[232:235], v[88:91]
	v_mfma_f32_16x16x32_bf16 v[76:79], v[128:131], v[240:243], v[76:79]
	v_mfma_f32_16x16x32_bf16 v[72:75], v[136:139], v[240:243], v[72:75]
	v_mfma_f32_16x16x32_bf16 v[124:127], v[132:135], v[220:223], v[124:127]
	v_mfma_f32_16x16x32_bf16 v[120:123], v[140:143], v[220:223], v[120:123]
	v_mfma_f32_16x16x32_bf16 v[108:111], v[132:135], v[228:231], v[108:111]
	v_mfma_f32_16x16x32_bf16 v[104:107], v[140:143], v[228:231], v[104:107]
	v_mfma_f32_16x16x32_bf16 v[92:95], v[132:135], v[236:239], v[92:95]
	v_mfma_f32_16x16x32_bf16 v[88:91], v[140:143], v[236:239], v[88:91]
	v_mfma_f32_16x16x32_bf16 v[76:79], v[132:135], v[244:247], v[76:79]
	v_mfma_f32_16x16x32_bf16 v[72:75], v[140:143], v[244:247], v[72:75]
	v_mfma_f32_16x16x32_bf16 v[116:119], v[178:181], v[216:219], v[116:119]
	v_mfma_f32_16x16x32_bf16 v[112:115], v[208:211], v[216:219], v[112:115]
	v_mfma_f32_16x16x32_bf16 v[100:103], v[178:181], v[224:227], v[100:103]
	v_mfma_f32_16x16x32_bf16 v[96:99], v[208:211], v[224:227], v[96:99]
	v_mfma_f32_16x16x32_bf16 v[84:87], v[178:181], v[232:235], v[84:87]
	v_mfma_f32_16x16x32_bf16 v[80:83], v[208:211], v[232:235], v[80:83]
	v_mfma_f32_16x16x32_bf16 v[68:71], v[178:181], v[240:243], v[68:71]
	v_mfma_f32_16x16x32_bf16 v[64:67], v[208:211], v[240:243], v[64:67]
	v_mfma_f32_16x16x32_bf16 v[116:119], v[204:207], v[220:223], v[116:119]
	v_mfma_f32_16x16x32_bf16 v[112:115], v[212:215], v[220:223], v[112:115]
	v_mfma_f32_16x16x32_bf16 v[100:103], v[204:207], v[228:231], v[100:103]
	v_mfma_f32_16x16x32_bf16 v[96:99], v[212:215], v[228:231], v[96:99]
	v_mfma_f32_16x16x32_bf16 v[84:87], v[204:207], v[236:239], v[84:87]
	v_mfma_f32_16x16x32_bf16 v[80:83], v[212:215], v[236:239], v[80:83]
	v_mfma_f32_16x16x32_bf16 v[68:71], v[204:207], v[244:247], v[68:71]
	v_mfma_f32_16x16x32_bf16 v[64:67], v[212:215], v[244:247], v[64:67]
	s_barrier
	s_add_i32 s4, s4, s33
	v_lshl_add_u64 v[164:165], v[164:165], 0, s[26:27]
	s_mov_b32 m0, s4
	ds_read_b128 v[216:219], v176 offset:49152
	ds_read_b128 v[220:223], v176 offset:50176
	ds_read_b128 v[224:227], v176 offset:51200
	ds_read_b128 v[228:231], v176 offset:52224
	ds_read_b128 v[232:235], v176 offset:53248
	ds_read_b128 v[236:239], v176 offset:54272
	ds_read_b128 v[240:243], v176 offset:55296
	ds_read_b128 v[244:247], v176 offset:56320
	global_load_lds_dwordx4 v[164:165], off
	s_add_i32 m0, s4, 0x2000
	s_add_u32 s34, s34, 0xb0080
	v_lshl_add_u64 v[164:165], v[248:249], 0, s[26:27]
	s_addc_u32 s35, s35, 0
	s_add_i32 s4, s5, s33
	global_load_lds_dwordx4 v[164:165], off
	v_lshl_add_u64 v[164:165], s[34:35], 0, v[154:155]
	s_mov_b32 m0, s4
	s_nop 0
	global_load_lds_dwordx4 v[164:165], off
	v_lshl_add_u64 v[164:165], s[34:35], 0, v[156:157]
	s_add_i32 m0, s4, 0x2000
	s_nop 0
	global_load_lds_dwordx4 v[164:165], off
	v_lshl_add_u64 v[164:165], v[250:251], 0, s[26:27]
	s_mov_b32 m0, s71
	s_nop 0
	global_load_lds_dwordx4 v[164:165], off
	v_lshl_add_u64 v[164:165], v[252:253], 0, s[26:27]
	s_mov_b32 m0, s72
	s_nop 0
	global_load_lds_dwordx4 v[164:165], off
	s_add_i32 s51, s51, 2
	s_add_u32 s28, s28, 0x100
	s_addc_u32 s29, s29, 0
	s_cmp_gt_u32 s51, 41
	s_mov_b64 s[58:59], s[60:61]
	s_waitcnt vmcnt(8)
	s_waitcnt lgkmcnt(0)
	s_barrier
	v_mfma_f32_16x16x32_bf16 v[60:63], v[128:131], v[216:219], v[60:63]
	v_mfma_f32_16x16x32_bf16 v[56:59], v[136:139], v[216:219], v[56:59]
	v_mfma_f32_16x16x32_bf16 v[44:47], v[128:131], v[224:227], v[44:47]
	v_mfma_f32_16x16x32_bf16 v[40:43], v[136:139], v[224:227], v[40:43]
	v_mfma_f32_16x16x32_bf16 v[28:31], v[128:131], v[232:235], v[28:31]
	v_mfma_f32_16x16x32_bf16 v[24:27], v[136:139], v[232:235], v[24:27]
	v_mfma_f32_16x16x32_bf16 v[12:15], v[128:131], v[240:243], v[12:15]
	v_mfma_f32_16x16x32_bf16 v[8:11], v[136:139], v[240:243], v[8:11]
	v_mfma_f32_16x16x32_bf16 v[60:63], v[132:135], v[220:223], v[60:63]
	v_mfma_f32_16x16x32_bf16 v[56:59], v[140:143], v[220:223], v[56:59]
	v_mfma_f32_16x16x32_bf16 v[44:47], v[132:135], v[228:231], v[44:47]
	v_mfma_f32_16x16x32_bf16 v[40:43], v[140:143], v[228:231], v[40:43]
	v_mfma_f32_16x16x32_bf16 v[28:31], v[132:135], v[236:239], v[28:31]
	v_mfma_f32_16x16x32_bf16 v[24:27], v[140:143], v[236:239], v[24:27]
	v_mfma_f32_16x16x32_bf16 v[12:15], v[132:135], v[244:247], v[12:15]
	v_mfma_f32_16x16x32_bf16 v[8:11], v[140:143], v[244:247], v[8:11]
	v_mfma_f32_16x16x32_bf16 v[52:55], v[178:181], v[216:219], v[52:55]
	v_mfma_f32_16x16x32_bf16 v[48:51], v[208:211], v[216:219], v[48:51]
	v_mfma_f32_16x16x32_bf16 v[36:39], v[178:181], v[224:227], v[36:39]
	v_mfma_f32_16x16x32_bf16 v[32:35], v[208:211], v[224:227], v[32:35]
	v_mfma_f32_16x16x32_bf16 v[20:23], v[178:181], v[232:235], v[20:23]
	v_mfma_f32_16x16x32_bf16 v[16:19], v[208:211], v[232:235], v[16:19]
	v_mfma_f32_16x16x32_bf16 v[4:7], v[178:181], v[240:243], v[4:7]
	v_mfma_f32_16x16x32_bf16 v[0:3], v[208:211], v[240:243], v[0:3]
	v_mfma_f32_16x16x32_bf16 v[52:55], v[204:207], v[220:223], v[52:55]
	v_mfma_f32_16x16x32_bf16 v[48:51], v[212:215], v[220:223], v[48:51]
	v_mfma_f32_16x16x32_bf16 v[36:39], v[204:207], v[228:231], v[36:39]
	v_mfma_f32_16x16x32_bf16 v[32:35], v[212:215], v[228:231], v[32:35]
	v_mfma_f32_16x16x32_bf16 v[20:23], v[204:207], v[236:239], v[20:23]
	v_mfma_f32_16x16x32_bf16 v[16:19], v[212:215], v[236:239], v[16:19]
	v_mfma_f32_16x16x32_bf16 v[4:7], v[204:207], v[244:247], v[4:7]
	v_mfma_f32_16x16x32_bf16 v[0:3], v[212:215], v[244:247], v[0:3]
	s_barrier
	s_cbranch_scc0 .LBB0_456
	s_and_b64 vcc, exec, s[54:55]
	s_cbranch_vccz .LBB0_459
	s_barrier

.LBB0_605:
	v_add_u32_e32 v140, 0x10000, v203
	v_add_u32_e32 v144, 0x14000, v203
	ds_read_b128 v[128:131], v140
	ds_read_b128 v[132:135], v140 offset:1024
	ds_read_b128 v[136:139], v140 offset:2048
	ds_read_b128 v[140:143], v140 offset:3072
	ds_read_b128 v[168:171], v144
	ds_read_b128 v[172:175], v144 offset:1024
	ds_read_b128 v[176:179], v144 offset:2048
	ds_read_b128 v[206:209], v144 offset:3072
	ds_read_b128 v[210:213], v205
	ds_read_b128 v[214:217], v205 offset:1024
	ds_read_b128 v[218:221], v205 offset:2048
	ds_read_b128 v[222:225], v205 offset:3072
	ds_read_b128 v[226:229], v205 offset:4096
	ds_read_b128 v[230:233], v205 offset:5120
	ds_read_b128 v[234:237], v205 offset:6144
	ds_read_b128 v[238:241], v205 offset:7168
	s_add_u32 s4, s0, 0xfffc0080
	s_addc_u32 s5, s1, -1
	s_add_i32 s89, 0, 0x10000
	s_cmp_eq_u32 s88, 12
	s_cselect_b32 s43, s3, s5
	s_cselect_b32 s42, s36, s4
	s_cselect_b32 s35, s39, s84
	s_cselect_b32 s34, s71, s79
	s_add_i32 s4, 0, 0x14000
	v_lshl_add_u64 v[180:181], s[0:1], 0, v[164:165]
	s_add_i32 m0, s69, 0xc000
	s_nop 0
	global_load_lds_dwordx4 v[180:181], off
	v_lshl_add_u64 v[180:181], s[0:1], 0, v[166:167]
	s_add_i32 m0, s69, 0xe000
	s_nop 0
	global_load_lds_dwordx4 v[180:181], off
	s_waitcnt vmcnt(8)
	s_waitcnt lgkmcnt(0)
	s_barrier
	v_mfma_f32_16x16x32_bf16 v[124:127], v[128:131], v[210:213], v[124:127]
	v_mfma_f32_16x16x32_bf16 v[120:123], v[136:139], v[210:213], v[120:123]
	v_mfma_f32_16x16x32_bf16 v[112:115], v[128:131], v[218:221], v[112:115]
	v_mfma_f32_16x16x32_bf16 v[108:111], v[136:139], v[218:221], v[108:111]
	v_mfma_f32_16x16x32_bf16 v[100:103], v[128:131], v[226:229], v[100:103]
	v_mfma_f32_16x16x32_bf16 v[92:95], v[136:139], v[226:229], v[92:95]
	v_mfma_f32_16x16x32_bf16 v[84:87], v[128:131], v[234:237], v[84:87]
	v_mfma_f32_16x16x32_bf16 v[76:79], v[136:139], v[234:237], v[76:79]
	v_mfma_f32_16x16x32_bf16 v[124:127], v[132:135], v[214:217], v[124:127]
	v_mfma_f32_16x16x32_bf16 v[120:123], v[140:143], v[214:217], v[120:123]
	v_mfma_f32_16x16x32_bf16 v[112:115], v[132:135], v[222:225], v[112:115]
	v_mfma_f32_16x16x32_bf16 v[108:111], v[140:143], v[222:225], v[108:111]
	v_mfma_f32_16x16x32_bf16 v[100:103], v[132:135], v[230:233], v[100:103]
	v_mfma_f32_16x16x32_bf16 v[92:95], v[140:143], v[230:233], v[92:95]
	v_mfma_f32_16x16x32_bf16 v[84:87], v[132:135], v[238:241], v[84:87]
	v_mfma_f32_16x16x32_bf16 v[76:79], v[140:143], v[238:241], v[76:79]
	v_mfma_f32_16x16x32_bf16 v[116:119], v[168:171], v[210:213], v[116:119]
	v_mfma_f32_16x16x32_bf16 v[104:107], v[176:179], v[210:213], v[104:107]
	v_mfma_f32_16x16x32_bf16 v[96:99], v[168:171], v[218:221], v[96:99]
	v_mfma_f32_16x16x32_bf16 v[88:91], v[176:179], v[218:221], v[88:91]
	v_mfma_f32_16x16x32_bf16 v[80:83], v[168:171], v[226:229], v[80:83]
	v_mfma_f32_16x16x32_bf16 v[72:75], v[176:179], v[226:229], v[72:75]
	v_mfma_f32_16x16x32_bf16 v[68:71], v[168:171], v[234:237], v[68:71]
	v_mfma_f32_16x16x32_bf16 v[64:67], v[176:179], v[234:237], v[64:67]
	v_mfma_f32_16x16x32_bf16 v[116:119], v[172:175], v[214:217], v[116:119]
	v_mfma_f32_16x16x32_bf16 v[104:107], v[206:209], v[214:217], v[104:107]
	v_mfma_f32_16x16x32_bf16 v[96:99], v[172:175], v[222:225], v[96:99]
	v_mfma_f32_16x16x32_bf16 v[88:91], v[206:209], v[222:225], v[88:91]
	v_mfma_f32_16x16x32_bf16 v[80:83], v[172:175], v[230:233], v[80:83]
	v_mfma_f32_16x16x32_bf16 v[72:75], v[206:209], v[230:233], v[72:75]
	v_mfma_f32_16x16x32_bf16 v[68:71], v[172:175], v[238:241], v[68:71]
	v_mfma_f32_16x16x32_bf16 v[64:67], v[206:209], v[238:241], v[64:67]
	s_barrier
	s_add_i32 s5, s89, s28
	v_lshl_add_u64 v[180:181], s[34:35], 0, v[156:157]
	s_mov_b32 m0, s5
	ds_read_b128 v[210:213], v205 offset:16384
	ds_read_b128 v[214:217], v205 offset:17408
	ds_read_b128 v[218:221], v205 offset:18432
	ds_read_b128 v[222:225], v205 offset:19456
	ds_read_b128 v[226:229], v205 offset:20480
	ds_read_b128 v[230:233], v205 offset:21504
	ds_read_b128 v[234:237], v205 offset:22528
	ds_read_b128 v[238:241], v205 offset:23552
	global_load_lds_dwordx4 v[180:181], off
	s_add_i32 m0, s5, 0x2000
	s_add_u32 s90, s34, 0x40000
	v_lshl_add_u64 v[242:243], s[34:35], 0, v[160:161]
	s_addc_u32 s91, s35, 0
	s_add_i32 s4, s4, s28
	global_load_lds_dwordx4 v[242:243], off
	v_lshl_add_u64 v[244:245], s[90:91], 0, v[156:157]
	s_mov_b32 m0, s4
	v_lshl_add_u64 v[246:247], s[42:43], 0, v[158:159]
	global_load_lds_dwordx4 v[244:245], off
	v_lshl_add_u64 v[244:245], s[90:91], 0, v[160:161]
	s_add_i32 m0, s4, 0x2000
	s_nop 0
	global_load_lds_dwordx4 v[244:245], off
	v_lshl_add_u64 v[244:245], s[42:43], 0, v[154:155]
	s_mov_b32 m0, s69
	s_nop 0
	global_load_lds_dwordx4 v[244:245], off
	s_mov_b32 m0, s62
	s_nop 0
	global_load_lds_dwordx4 v[246:247], off
	s_waitcnt vmcnt(8)
	s_waitcnt lgkmcnt(0)
	s_barrier
	v_mfma_f32_16x16x32_bf16 v[60:63], v[128:131], v[210:213], v[60:63]
	v_mfma_f32_16x16x32_bf16 v[56:59], v[136:139], v[210:213], v[56:59]
	v_mfma_f32_16x16x32_bf16 v[52:55], v[128:131], v[218:221], v[52:55]
	v_mfma_f32_16x16x32_bf16 v[44:47], v[136:139], v[218:221], v[44:47]
	v_mfma_f32_16x16x32_bf16 v[36:39], v[128:131], v[226:229], v[36:39]
	v_mfma_f32_16x16x32_bf16 v[28:31], v[136:139], v[226:229], v[28:31]
	v_mfma_f32_16x16x32_bf16 v[20:23], v[128:131], v[234:237], v[20:23]
	v_mfma_f32_16x16x32_bf16 v[12:15], v[136:139], v[234:237], v[12:15]
	v_mfma_f32_16x16x32_bf16 v[60:63], v[132:135], v[214:217], v[60:63]
	v_mfma_f32_16x16x32_bf16 v[56:59], v[140:143], v[214:217], v[56:59]
	v_mfma_f32_16x16x32_bf16 v[52:55], v[132:135], v[222:225], v[52:55]
	v_mfma_f32_16x16x32_bf16 v[44:47], v[140:143], v[222:225], v[44:47]
	v_mfma_f32_16x16x32_bf16 v[36:39], v[132:135], v[230:233], v[36:39]
	v_mfma_f32_16x16x32_bf16 v[28:31], v[140:143], v[230:233], v[28:31]
	v_mfma_f32_16x16x32_bf16 v[20:23], v[132:135], v[238:241], v[20:23]
	v_mfma_f32_16x16x32_bf16 v[12:15], v[140:143], v[238:241], v[12:15]
	v_mfma_f32_16x16x32_bf16 v[48:51], v[168:171], v[210:213], v[48:51]
	v_mfma_f32_16x16x32_bf16 v[40:43], v[176:179], v[210:213], v[40:43]
	v_mfma_f32_16x16x32_bf16 v[32:35], v[168:171], v[218:221], v[32:35]
	v_mfma_f32_16x16x32_bf16 v[24:27], v[176:179], v[218:221], v[24:27]
	v_mfma_f32_16x16x32_bf16 v[16:19], v[168:171], v[226:229], v[16:19]
	v_mfma_f32_16x16x32_bf16 v[8:11], v[176:179], v[226:229], v[8:11]
	v_mfma_f32_16x16x32_bf16 v[4:7], v[168:171], v[234:237], v[4:7]
	v_mfma_f32_16x16x32_bf16 v[0:3], v[176:179], v[234:237], v[0:3]
	v_mfma_f32_16x16x32_bf16 v[48:51], v[172:175], v[214:217], v[48:51]
	v_mfma_f32_16x16x32_bf16 v[40:43], v[206:209], v[214:217], v[40:43]
	v_mfma_f32_16x16x32_bf16 v[32:35], v[172:175], v[222:225], v[32:35]
	v_mfma_f32_16x16x32_bf16 v[24:27], v[206:209], v[222:225], v[24:27]
	v_mfma_f32_16x16x32_bf16 v[16:19], v[172:175], v[230:233], v[16:19]
	v_mfma_f32_16x16x32_bf16 v[8:11], v[206:209], v[230:233], v[8:11]
	v_mfma_f32_16x16x32_bf16 v[4:7], v[172:175], v[238:241], v[4:7]
	v_mfma_f32_16x16x32_bf16 v[0:3], v[206:209], v[238:241], v[0:3]
	s_barrier
	v_add_u32_e32 v140, 0x18000, v203
	v_add_u32_e32 v144, 0x1c000, v203
	ds_read_b128 v[128:131], v140
	ds_read_b128 v[132:135], v140 offset:1024
	ds_read_b128 v[136:139], v140 offset:2048
	ds_read_b128 v[140:143], v140 offset:3072
	ds_read_b128 v[168:171], v144
	ds_read_b128 v[172:175], v144 offset:1024
	ds_read_b128 v[176:179], v144 offset:2048
	ds_read_b128 v[206:209], v144 offset:3072
	ds_read_b128 v[210:213], v205 offset:32768
	ds_read_b128 v[214:217], v205 offset:33792
	ds_read_b128 v[218:221], v205 offset:34816
	ds_read_b128 v[222:225], v205 offset:35840
	ds_read_b128 v[226:229], v205 offset:36864
	ds_read_b128 v[230:233], v205 offset:37888
	ds_read_b128 v[234:237], v205 offset:38912
	ds_read_b128 v[238:241], v205 offset:39936
	s_add_i32 s4, 0, 0x18000
	s_add_i32 s5, 0, 0x1c000
	s_add_u32 s42, s42, 0x40000
	s_addc_u32 s43, s43, 0
	s_mov_b32 m0, s63
	v_lshl_add_u64 v[248:249], s[42:43], 0, v[154:155]
	global_load_lds_dwordx4 v[248:249], off
	v_lshl_add_u64 v[248:249], s[42:43], 0, v[158:159]
	s_mov_b32 m0, s50
	s_nop 0
	global_load_lds_dwordx4 v[248:249], off
	s_waitcnt vmcnt(8)
	s_waitcnt lgkmcnt(0)
	s_barrier
	v_mfma_f32_16x16x32_bf16 v[124:127], v[128:131], v[210:213], v[124:127]
	v_mfma_f32_16x16x32_bf16 v[120:123], v[136:139], v[210:213], v[120:123]
	v_mfma_f32_16x16x32_bf16 v[112:115], v[128:131], v[218:221], v[112:115]
	v_mfma_f32_16x16x32_bf16 v[108:111], v[136:139], v[218:221], v[108:111]
	v_mfma_f32_16x16x32_bf16 v[100:103], v[128:131], v[226:229], v[100:103]
	v_mfma_f32_16x16x32_bf16 v[92:95], v[136:139], v[226:229], v[92:95]
	v_mfma_f32_16x16x32_bf16 v[84:87], v[128:131], v[234:237], v[84:87]
	v_mfma_f32_16x16x32_bf16 v[76:79], v[136:139], v[234:237], v[76:79]
	v_mfma_f32_16x16x32_bf16 v[124:127], v[132:135], v[214:217], v[124:127]
	v_mfma_f32_16x16x32_bf16 v[120:123], v[140:143], v[214:217], v[120:123]
	v_mfma_f32_16x16x32_bf16 v[112:115], v[132:135], v[222:225], v[112:115]
	v_mfma_f32_16x16x32_bf16 v[108:111], v[140:143], v[222:225], v[108:111]
	v_mfma_f32_16x16x32_bf16 v[100:103], v[132:135], v[230:233], v[100:103]
	v_mfma_f32_16x16x32_bf16 v[92:95], v[140:143], v[230:233], v[92:95]
	v_mfma_f32_16x16x32_bf16 v[84:87], v[132:135], v[238:241], v[84:87]
	v_mfma_f32_16x16x32_bf16 v[76:79], v[140:143], v[238:241], v[76:79]
	v_mfma_f32_16x16x32_bf16 v[116:119], v[168:171], v[210:213], v[116:119]
	v_mfma_f32_16x16x32_bf16 v[104:107], v[176:179], v[210:213], v[104:107]
	v_mfma_f32_16x16x32_bf16 v[96:99], v[168:171], v[218:221], v[96:99]
	v_mfma_f32_16x16x32_bf16 v[88:91], v[176:179], v[218:221], v[88:91]
	v_mfma_f32_16x16x32_bf16 v[80:83], v[168:171], v[226:229], v[80:83]
	v_mfma_f32_16x16x32_bf16 v[72:75], v[176:179], v[226:229], v[72:75]
	v_mfma_f32_16x16x32_bf16 v[68:71], v[168:171], v[234:237], v[68:71]
	v_mfma_f32_16x16x32_bf16 v[64:67], v[176:179], v[234:237], v[64:67]
	v_mfma_f32_16x16x32_bf16 v[116:119], v[172:175], v[214:217], v[116:119]
	v_mfma_f32_16x16x32_bf16 v[104:107], v[206:209], v[214:217], v[104:107]
	v_mfma_f32_16x16x32_bf16 v[96:99], v[172:175], v[222:225], v[96:99]
	v_mfma_f32_16x16x32_bf16 v[88:91], v[206:209], v[222:225], v[88:91]
	v_mfma_f32_16x16x32_bf16 v[80:83], v[172:175], v[230:233], v[80:83]
	v_mfma_f32_16x16x32_bf16 v[72:75], v[206:209], v[230:233], v[72:75]
	v_mfma_f32_16x16x32_bf16 v[68:71], v[172:175], v[238:241], v[68:71]
	v_mfma_f32_16x16x32_bf16 v[64:67], v[206:209], v[238:241], v[64:67]
	s_barrier
	s_add_i32 s4, s4, s28
	v_lshl_add_u64 v[180:181], v[180:181], 0, s[26:27]
	s_mov_b32 m0, s4
	ds_read_b128 v[210:213], v205 offset:49152
	ds_read_b128 v[214:217], v205 offset:50176
	ds_read_b128 v[218:221], v205 offset:51200
	ds_read_b128 v[222:225], v205 offset:52224
	ds_read_b128 v[226:229], v205 offset:53248
	ds_read_b128 v[230:233], v205 offset:54272
	ds_read_b128 v[234:237], v205 offset:55296
	ds_read_b128 v[238:241], v205 offset:56320
	global_load_lds_dwordx4 v[180:181], off
	s_add_i32 m0, s4, 0x2000
	s_add_u32 s34, s34, 0x40080
	v_lshl_add_u64 v[180:181], v[242:243], 0, s[26:27]
	s_addc_u32 s35, s35, 0
	s_add_i32 s4, s5, s28
	global_load_lds_dwordx4 v[180:181], off
	v_lshl_add_u64 v[180:181], s[34:35], 0, v[156:157]
	s_mov_b32 m0, s4
	s_nop 0
	global_load_lds_dwordx4 v[180:181], off
	v_lshl_add_u64 v[180:181], s[34:35], 0, v[160:161]
	s_add_i32 m0, s4, 0x2000
	s_nop 0
	global_load_lds_dwordx4 v[180:181], off
	v_lshl_add_u64 v[180:181], v[244:245], 0, s[26:27]
	s_mov_b32 m0, s51
	s_nop 0
	global_load_lds_dwordx4 v[180:181], off
	v_lshl_add_u64 v[180:181], v[246:247], 0, s[26:27]
	s_mov_b32 m0, s64
	s_nop 0
	global_load_lds_dwordx4 v[180:181], off
	s_add_i32 s88, s88, 2
	s_add_u32 s0, s0, 0x100
	s_addc_u32 s1, s1, 0
	s_add_u32 s79, s79, 0x100
	s_addc_u32 s84, s84, 0
	s_cmp_gt_u32 s88, 13
	s_waitcnt vmcnt(8)
	s_waitcnt lgkmcnt(0)
	s_barrier
	v_mfma_f32_16x16x32_bf16 v[60:63], v[128:131], v[210:213], v[60:63]
	v_mfma_f32_16x16x32_bf16 v[56:59], v[136:139], v[210:213], v[56:59]
	v_mfma_f32_16x16x32_bf16 v[52:55], v[128:131], v[218:221], v[52:55]
	v_mfma_f32_16x16x32_bf16 v[44:47], v[136:139], v[218:221], v[44:47]
	v_mfma_f32_16x16x32_bf16 v[36:39], v[128:131], v[226:229], v[36:39]
	v_mfma_f32_16x16x32_bf16 v[28:31], v[136:139], v[226:229], v[28:31]
	v_mfma_f32_16x16x32_bf16 v[20:23], v[128:131], v[234:237], v[20:23]
	v_mfma_f32_16x16x32_bf16 v[12:15], v[136:139], v[234:237], v[12:15]
	v_mfma_f32_16x16x32_bf16 v[60:63], v[132:135], v[214:217], v[60:63]
	v_mfma_f32_16x16x32_bf16 v[56:59], v[140:143], v[214:217], v[56:59]
	v_mfma_f32_16x16x32_bf16 v[52:55], v[132:135], v[222:225], v[52:55]
	v_mfma_f32_16x16x32_bf16 v[44:47], v[140:143], v[222:225], v[44:47]
	v_mfma_f32_16x16x32_bf16 v[36:39], v[132:135], v[230:233], v[36:39]
	v_mfma_f32_16x16x32_bf16 v[28:31], v[140:143], v[230:233], v[28:31]
	v_mfma_f32_16x16x32_bf16 v[20:23], v[132:135], v[238:241], v[20:23]
	v_mfma_f32_16x16x32_bf16 v[12:15], v[140:143], v[238:241], v[12:15]
	v_mfma_f32_16x16x32_bf16 v[48:51], v[168:171], v[210:213], v[48:51]
	v_mfma_f32_16x16x32_bf16 v[40:43], v[176:179], v[210:213], v[40:43]
	v_mfma_f32_16x16x32_bf16 v[32:35], v[168:171], v[218:221], v[32:35]
	v_mfma_f32_16x16x32_bf16 v[24:27], v[176:179], v[218:221], v[24:27]
	v_mfma_f32_16x16x32_bf16 v[16:19], v[168:171], v[226:229], v[16:19]
	v_mfma_f32_16x16x32_bf16 v[8:11], v[176:179], v[226:229], v[8:11]
	v_mfma_f32_16x16x32_bf16 v[4:7], v[168:171], v[234:237], v[4:7]
	v_mfma_f32_16x16x32_bf16 v[0:3], v[176:179], v[234:237], v[0:3]
	v_mfma_f32_16x16x32_bf16 v[48:51], v[172:175], v[214:217], v[48:51]
	v_mfma_f32_16x16x32_bf16 v[40:43], v[206:209], v[214:217], v[40:43]
	v_mfma_f32_16x16x32_bf16 v[32:35], v[172:175], v[222:225], v[32:35]
	v_mfma_f32_16x16x32_bf16 v[24:27], v[206:209], v[222:225], v[24:27]
	v_mfma_f32_16x16x32_bf16 v[16:19], v[172:175], v[230:233], v[16:19]
	v_mfma_f32_16x16x32_bf16 v[8:11], v[206:209], v[230:233], v[8:11]
	v_mfma_f32_16x16x32_bf16 v[4:7], v[172:175], v[238:241], v[4:7]
	v_mfma_f32_16x16x32_bf16 v[0:3], v[206:209], v[238:241], v[0:3]
	s_barrier
	s_cbranch_scc0 .LBB0_605
	s_and_b64 vcc, exec, s[66:67]
	s_cbranch_vccz .LBB0_608
	s_barrier

.LBB0_1005:
	v_add_u32_e32 v138, 0x10000, v141
	ds_read_b128 v[154:157], v138
	ds_read_b128 v[158:161], v138 offset:1024
	ds_read_b128 v[162:165], v138 offset:2048
	ds_read_b128 v[166:169], v138 offset:3072
	v_add_u32_e32 v138, 0x14000, v141
	ds_read_b128 v[170:173], v138
	ds_read_b128 v[174:177], v138 offset:1024
	ds_read_b128 v[178:181], v138 offset:2048
	ds_read_b128 v[204:207], v138 offset:3072
	ds_read_b128 v[208:211], v143
	ds_read_b128 v[212:215], v143 offset:1024
	ds_read_b128 v[216:219], v143 offset:2048
	ds_read_b128 v[220:223], v143 offset:3072
	ds_read_b128 v[224:227], v143 offset:4096
	ds_read_b128 v[228:231], v143 offset:5120
	ds_read_b128 v[232:235], v143 offset:6144
	ds_read_b128 v[236:239], v143 offset:7168
	s_add_u32 s4, s54, 0xfffe0080
	s_addc_u32 s5, s55, -1
	s_add_i32 s72, 0, 0x10000
	s_cmp_eq_u32 s71, 4
	s_cselect_b32 s59, s29, s5
	s_cselect_b32 s58, s47, s4
	s_cselect_b32 s35, s45, s70
	s_cselect_b32 s34, s68, s69
	s_add_i32 s73, 0, 0x14000
	v_lshl_add_u64 v[138:139], s[54:55], 0, v[134:135]
	s_add_i32 m0, s53, 0xc000
	s_nop 0
	global_load_lds_dwordx4 v[138:139], off
	v_lshl_add_u64 v[138:139], s[54:55], 0, v[136:137]
	s_add_i32 m0, s53, 0xe000
	s_nop 0
	global_load_lds_dwordx4 v[138:139], off
	s_waitcnt vmcnt(8)
	s_waitcnt lgkmcnt(0)
	s_barrier
	v_mfma_f32_16x16x32_bf16 v[120:123], v[154:157], v[208:211], v[120:123]
	v_mfma_f32_16x16x32_bf16 v[124:127], v[162:165], v[208:211], v[124:127]
	v_mfma_f32_16x16x32_bf16 v[104:107], v[154:157], v[216:219], v[104:107]
	v_mfma_f32_16x16x32_bf16 v[108:111], v[162:165], v[216:219], v[108:111]
	v_mfma_f32_16x16x32_bf16 v[88:91], v[154:157], v[224:227], v[88:91]
	v_mfma_f32_16x16x32_bf16 v[92:95], v[162:165], v[224:227], v[92:95]
	v_mfma_f32_16x16x32_bf16 v[72:75], v[154:157], v[232:235], v[72:75]
	v_mfma_f32_16x16x32_bf16 v[76:79], v[162:165], v[232:235], v[76:79]
	v_mfma_f32_16x16x32_bf16 v[120:123], v[158:161], v[212:215], v[120:123]
	v_mfma_f32_16x16x32_bf16 v[124:127], v[166:169], v[212:215], v[124:127]
	v_mfma_f32_16x16x32_bf16 v[104:107], v[158:161], v[220:223], v[104:107]
	v_mfma_f32_16x16x32_bf16 v[108:111], v[166:169], v[220:223], v[108:111]
	v_mfma_f32_16x16x32_bf16 v[88:91], v[158:161], v[228:231], v[88:91]
	v_mfma_f32_16x16x32_bf16 v[92:95], v[166:169], v[228:231], v[92:95]
	v_mfma_f32_16x16x32_bf16 v[72:75], v[158:161], v[236:239], v[72:75]
	v_mfma_f32_16x16x32_bf16 v[76:79], v[166:169], v[236:239], v[76:79]
	v_mfma_f32_16x16x32_bf16 v[112:115], v[170:173], v[208:211], v[112:115]
	v_mfma_f32_16x16x32_bf16 v[116:119], v[178:181], v[208:211], v[116:119]
	v_mfma_f32_16x16x32_bf16 v[96:99], v[170:173], v[216:219], v[96:99]
	v_mfma_f32_16x16x32_bf16 v[100:103], v[178:181], v[216:219], v[100:103]
	v_mfma_f32_16x16x32_bf16 v[80:83], v[170:173], v[224:227], v[80:83]
	v_mfma_f32_16x16x32_bf16 v[84:87], v[178:181], v[224:227], v[84:87]
	v_mfma_f32_16x16x32_bf16 v[64:67], v[170:173], v[232:235], v[64:67]
	v_mfma_f32_16x16x32_bf16 v[68:71], v[178:181], v[232:235], v[68:71]
	v_mfma_f32_16x16x32_bf16 v[112:115], v[174:177], v[212:215], v[112:115]
	v_mfma_f32_16x16x32_bf16 v[116:119], v[204:207], v[212:215], v[116:119]
	v_mfma_f32_16x16x32_bf16 v[96:99], v[174:177], v[220:223], v[96:99]
	v_mfma_f32_16x16x32_bf16 v[100:103], v[204:207], v[220:223], v[100:103]
	v_mfma_f32_16x16x32_bf16 v[80:83], v[174:177], v[228:231], v[80:83]
	v_mfma_f32_16x16x32_bf16 v[84:87], v[204:207], v[228:231], v[84:87]
	v_mfma_f32_16x16x32_bf16 v[64:67], v[174:177], v[236:239], v[64:67]
	v_mfma_f32_16x16x32_bf16 v[68:71], v[204:207], v[236:239], v[68:71]
	s_barrier
	s_add_i32 s4, s72, s30
	v_lshl_add_u64 v[138:139], s[34:35], 0, v[144:145]
	s_mov_b32 m0, s4
	ds_read_b128 v[208:211], v143 offset:16384
	ds_read_b128 v[212:215], v143 offset:17408
	ds_read_b128 v[216:219], v143 offset:18432
	ds_read_b128 v[220:223], v143 offset:19456
	ds_read_b128 v[224:227], v143 offset:20480
	ds_read_b128 v[228:231], v143 offset:21504
	ds_read_b128 v[232:235], v143 offset:22528
	ds_read_b128 v[236:239], v143 offset:23552
	global_load_lds_dwordx4 v[138:139], off
	s_add_i32 m0, s4, 0x2000
	s_add_u32 s4, s34, 0x20000
	v_lshl_add_u64 v[202:203], s[34:35], 0, v[132:133]
	s_addc_u32 s5, s35, 0
	s_add_i32 s72, s73, s30
	global_load_lds_dwordx4 v[202:203], off
	v_lshl_add_u64 v[240:241], s[4:5], 0, v[144:145]
	s_mov_b32 m0, s72
	v_lshl_add_u64 v[242:243], s[58:59], 0, v[130:131]
	global_load_lds_dwordx4 v[240:241], off
	v_lshl_add_u64 v[240:241], s[4:5], 0, v[132:133]
	s_add_i32 m0, s72, 0x2000
	s_nop 0
	global_load_lds_dwordx4 v[240:241], off
	v_lshl_add_u64 v[240:241], s[58:59], 0, v[128:129]
	s_mov_b32 m0, s53
	s_nop 0
	global_load_lds_dwordx4 v[240:241], off
	s_mov_b32 m0, s62
	s_nop 0
	global_load_lds_dwordx4 v[242:243], off
	s_waitcnt vmcnt(8)
	s_waitcnt lgkmcnt(0)
	s_barrier
	v_mfma_f32_16x16x32_bf16 v[56:59], v[154:157], v[208:211], v[56:59]
	v_mfma_f32_16x16x32_bf16 v[60:63], v[162:165], v[208:211], v[60:63]
	v_mfma_f32_16x16x32_bf16 v[40:43], v[154:157], v[216:219], v[40:43]
	v_mfma_f32_16x16x32_bf16 v[44:47], v[162:165], v[216:219], v[44:47]
	v_mfma_f32_16x16x32_bf16 v[24:27], v[154:157], v[224:227], v[24:27]
	v_mfma_f32_16x16x32_bf16 v[28:31], v[162:165], v[224:227], v[28:31]
	v_mfma_f32_16x16x32_bf16 v[8:11], v[154:157], v[232:235], v[8:11]
	v_mfma_f32_16x16x32_bf16 v[12:15], v[162:165], v[232:235], v[12:15]
	v_mfma_f32_16x16x32_bf16 v[56:59], v[158:161], v[212:215], v[56:59]
	v_mfma_f32_16x16x32_bf16 v[60:63], v[166:169], v[212:215], v[60:63]
	v_mfma_f32_16x16x32_bf16 v[40:43], v[158:161], v[220:223], v[40:43]
	v_mfma_f32_16x16x32_bf16 v[44:47], v[166:169], v[220:223], v[44:47]
	v_mfma_f32_16x16x32_bf16 v[24:27], v[158:161], v[228:231], v[24:27]
	v_mfma_f32_16x16x32_bf16 v[28:31], v[166:169], v[228:231], v[28:31]
	v_mfma_f32_16x16x32_bf16 v[8:11], v[158:161], v[236:239], v[8:11]
	v_mfma_f32_16x16x32_bf16 v[12:15], v[166:169], v[236:239], v[12:15]
	v_mfma_f32_16x16x32_bf16 v[48:51], v[170:173], v[208:211], v[48:51]
	v_mfma_f32_16x16x32_bf16 v[52:55], v[178:181], v[208:211], v[52:55]
	v_mfma_f32_16x16x32_bf16 v[32:35], v[170:173], v[216:219], v[32:35]
	v_mfma_f32_16x16x32_bf16 v[36:39], v[178:181], v[216:219], v[36:39]
	v_mfma_f32_16x16x32_bf16 v[16:19], v[170:173], v[224:227], v[16:19]
	v_mfma_f32_16x16x32_bf16 v[20:23], v[178:181], v[224:227], v[20:23]
	v_mfma_f32_16x16x32_bf16 v[0:3], v[170:173], v[232:235], v[0:3]
	v_mfma_f32_16x16x32_bf16 v[4:7], v[178:181], v[232:235], v[4:7]
	v_mfma_f32_16x16x32_bf16 v[48:51], v[174:177], v[212:215], v[48:51]
	v_mfma_f32_16x16x32_bf16 v[52:55], v[204:207], v[212:215], v[52:55]
	v_mfma_f32_16x16x32_bf16 v[32:35], v[174:177], v[220:223], v[32:35]
	v_mfma_f32_16x16x32_bf16 v[36:39], v[204:207], v[220:223], v[36:39]
	v_mfma_f32_16x16x32_bf16 v[16:19], v[174:177], v[228:231], v[16:19]
	v_mfma_f32_16x16x32_bf16 v[20:23], v[204:207], v[228:231], v[20:23]
	v_mfma_f32_16x16x32_bf16 v[0:3], v[174:177], v[236:239], v[0:3]
	v_mfma_f32_16x16x32_bf16 v[4:7], v[204:207], v[236:239], v[4:7]
	s_barrier
	v_add_u32_e32 v166, 0x18000, v141
	v_add_u32_e32 v204, 0x1c000, v141
	ds_read_b128 v[154:157], v166
	ds_read_b128 v[158:161], v166 offset:1024
	ds_read_b128 v[162:165], v166 offset:2048
	ds_read_b128 v[166:169], v166 offset:3072
	ds_read_b128 v[170:173], v204
	ds_read_b128 v[174:177], v204 offset:1024
	ds_read_b128 v[178:181], v204 offset:2048
	ds_read_b128 v[204:207], v204 offset:3072
	ds_read_b128 v[208:211], v143 offset:32768
	ds_read_b128 v[212:215], v143 offset:33792
	ds_read_b128 v[216:219], v143 offset:34816
	ds_read_b128 v[220:223], v143 offset:35840
	ds_read_b128 v[224:227], v143 offset:36864
	ds_read_b128 v[228:231], v143 offset:37888
	ds_read_b128 v[232:235], v143 offset:38912
	ds_read_b128 v[236:239], v143 offset:39936
	s_add_i32 s72, 0, 0x18000
	s_add_i32 s73, 0, 0x1c000
	s_add_u32 s4, s58, 0x20000
	s_addc_u32 s5, s59, 0
	s_mov_b32 m0, s63
	v_lshl_add_u64 v[244:245], s[4:5], 0, v[128:129]
	global_load_lds_dwordx4 v[244:245], off
	v_lshl_add_u64 v[244:245], s[4:5], 0, v[130:131]
	s_mov_b32 m0, s64
	s_nop 0
	global_load_lds_dwordx4 v[244:245], off
	s_waitcnt vmcnt(8)
	s_waitcnt lgkmcnt(0)
	s_barrier
	v_mfma_f32_16x16x32_bf16 v[120:123], v[154:157], v[208:211], v[120:123]
	v_mfma_f32_16x16x32_bf16 v[124:127], v[162:165], v[208:211], v[124:127]
	v_mfma_f32_16x16x32_bf16 v[104:107], v[154:157], v[216:219], v[104:107]
	v_mfma_f32_16x16x32_bf16 v[108:111], v[162:165], v[216:219], v[108:111]
	v_mfma_f32_16x16x32_bf16 v[88:91], v[154:157], v[224:227], v[88:91]
	v_mfma_f32_16x16x32_bf16 v[92:95], v[162:165], v[224:227], v[92:95]
	v_mfma_f32_16x16x32_bf16 v[72:75], v[154:157], v[232:235], v[72:75]
	v_mfma_f32_16x16x32_bf16 v[76:79], v[162:165], v[232:235], v[76:79]
	v_mfma_f32_16x16x32_bf16 v[120:123], v[158:161], v[212:215], v[120:123]
	v_mfma_f32_16x16x32_bf16 v[124:127], v[166:169], v[212:215], v[124:127]
	v_mfma_f32_16x16x32_bf16 v[104:107], v[158:161], v[220:223], v[104:107]
	v_mfma_f32_16x16x32_bf16 v[108:111], v[166:169], v[220:223], v[108:111]
	v_mfma_f32_16x16x32_bf16 v[88:91], v[158:161], v[228:231], v[88:91]
	v_mfma_f32_16x16x32_bf16 v[92:95], v[166:169], v[228:231], v[92:95]
	v_mfma_f32_16x16x32_bf16 v[72:75], v[158:161], v[236:239], v[72:75]
	v_mfma_f32_16x16x32_bf16 v[76:79], v[166:169], v[236:239], v[76:79]
	v_mfma_f32_16x16x32_bf16 v[112:115], v[170:173], v[208:211], v[112:115]
	v_mfma_f32_16x16x32_bf16 v[116:119], v[178:181], v[208:211], v[116:119]
	v_mfma_f32_16x16x32_bf16 v[96:99], v[170:173], v[216:219], v[96:99]
	v_mfma_f32_16x16x32_bf16 v[100:103], v[178:181], v[216:219], v[100:103]
	v_mfma_f32_16x16x32_bf16 v[80:83], v[170:173], v[224:227], v[80:83]
	v_mfma_f32_16x16x32_bf16 v[84:87], v[178:181], v[224:227], v[84:87]
	v_mfma_f32_16x16x32_bf16 v[64:67], v[170:173], v[232:235], v[64:67]
	v_mfma_f32_16x16x32_bf16 v[68:71], v[178:181], v[232:235], v[68:71]
	v_mfma_f32_16x16x32_bf16 v[112:115], v[174:177], v[212:215], v[112:115]
	v_mfma_f32_16x16x32_bf16 v[116:119], v[204:207], v[212:215], v[116:119]
	v_mfma_f32_16x16x32_bf16 v[96:99], v[174:177], v[220:223], v[96:99]
	v_mfma_f32_16x16x32_bf16 v[100:103], v[204:207], v[220:223], v[100:103]
	v_mfma_f32_16x16x32_bf16 v[80:83], v[174:177], v[228:231], v[80:83]
	v_mfma_f32_16x16x32_bf16 v[84:87], v[204:207], v[228:231], v[84:87]
	v_mfma_f32_16x16x32_bf16 v[64:67], v[174:177], v[236:239], v[64:67]
	v_mfma_f32_16x16x32_bf16 v[68:71], v[204:207], v[236:239], v[68:71]
	s_barrier
	s_add_i32 s4, s72, s30
	v_lshl_add_u64 v[138:139], v[138:139], 0, s[26:27]
	s_mov_b32 m0, s4
	ds_read_b128 v[208:211], v143 offset:49152
	ds_read_b128 v[212:215], v143 offset:50176
	ds_read_b128 v[216:219], v143 offset:51200
	ds_read_b128 v[220:223], v143 offset:52224
	ds_read_b128 v[224:227], v143 offset:53248
	ds_read_b128 v[228:231], v143 offset:54272
	ds_read_b128 v[232:235], v143 offset:55296
	ds_read_b128 v[236:239], v143 offset:56320
	global_load_lds_dwordx4 v[138:139], off
	s_add_i32 m0, s4, 0x2000
	s_add_u32 s4, s34, 0x20080
	v_lshl_add_u64 v[138:139], v[202:203], 0, s[26:27]
	s_addc_u32 s5, s35, 0
	s_add_i32 s34, s73, s30
	global_load_lds_dwordx4 v[138:139], off
	v_lshl_add_u64 v[138:139], s[4:5], 0, v[144:145]
	s_mov_b32 m0, s34
	s_nop 0
	global_load_lds_dwordx4 v[138:139], off
	v_lshl_add_u64 v[138:139], s[4:5], 0, v[132:133]
	s_add_i32 m0, s34, 0x2000
	s_nop 0
	global_load_lds_dwordx4 v[138:139], off
	v_lshl_add_u64 v[138:139], v[240:241], 0, s[26:27]
	s_mov_b32 m0, s65
	s_nop 0
	global_load_lds_dwordx4 v[138:139], off
	v_lshl_add_u64 v[138:139], v[242:243], 0, s[26:27]
	s_mov_b32 m0, s66
	s_nop 0
	global_load_lds_dwordx4 v[138:139], off
	s_add_i32 s71, s71, 2
	s_add_u32 s54, s54, 0x100
	s_addc_u32 s55, s55, 0
	s_add_u32 s69, s69, 0x100
	s_addc_u32 s70, s70, 0
	s_cmp_gt_u32 s71, 5
	s_waitcnt vmcnt(8)
	s_waitcnt lgkmcnt(0)
	s_barrier
	v_mfma_f32_16x16x32_bf16 v[56:59], v[154:157], v[208:211], v[56:59]
	v_mfma_f32_16x16x32_bf16 v[60:63], v[162:165], v[208:211], v[60:63]
	v_mfma_f32_16x16x32_bf16 v[40:43], v[154:157], v[216:219], v[40:43]
	v_mfma_f32_16x16x32_bf16 v[44:47], v[162:165], v[216:219], v[44:47]
	v_mfma_f32_16x16x32_bf16 v[24:27], v[154:157], v[224:227], v[24:27]
	v_mfma_f32_16x16x32_bf16 v[28:31], v[162:165], v[224:227], v[28:31]
	v_mfma_f32_16x16x32_bf16 v[8:11], v[154:157], v[232:235], v[8:11]
	v_mfma_f32_16x16x32_bf16 v[12:15], v[162:165], v[232:235], v[12:15]
	v_mfma_f32_16x16x32_bf16 v[56:59], v[158:161], v[212:215], v[56:59]
	v_mfma_f32_16x16x32_bf16 v[60:63], v[166:169], v[212:215], v[60:63]
	v_mfma_f32_16x16x32_bf16 v[40:43], v[158:161], v[220:223], v[40:43]
	v_mfma_f32_16x16x32_bf16 v[44:47], v[166:169], v[220:223], v[44:47]
	v_mfma_f32_16x16x32_bf16 v[24:27], v[158:161], v[228:231], v[24:27]
	v_mfma_f32_16x16x32_bf16 v[28:31], v[166:169], v[228:231], v[28:31]
	v_mfma_f32_16x16x32_bf16 v[8:11], v[158:161], v[236:239], v[8:11]
	v_mfma_f32_16x16x32_bf16 v[12:15], v[166:169], v[236:239], v[12:15]
	v_mfma_f32_16x16x32_bf16 v[48:51], v[170:173], v[208:211], v[48:51]
	v_mfma_f32_16x16x32_bf16 v[52:55], v[178:181], v[208:211], v[52:55]
	v_mfma_f32_16x16x32_bf16 v[32:35], v[170:173], v[216:219], v[32:35]
	v_mfma_f32_16x16x32_bf16 v[36:39], v[178:181], v[216:219], v[36:39]
	v_mfma_f32_16x16x32_bf16 v[16:19], v[170:173], v[224:227], v[16:19]
	v_mfma_f32_16x16x32_bf16 v[20:23], v[178:181], v[224:227], v[20:23]
	v_mfma_f32_16x16x32_bf16 v[0:3], v[170:173], v[232:235], v[0:3]
	v_mfma_f32_16x16x32_bf16 v[4:7], v[178:181], v[232:235], v[4:7]
	v_mfma_f32_16x16x32_bf16 v[48:51], v[174:177], v[212:215], v[48:51]
	v_mfma_f32_16x16x32_bf16 v[52:55], v[204:207], v[212:215], v[52:55]
	v_mfma_f32_16x16x32_bf16 v[32:35], v[174:177], v[220:223], v[32:35]
	v_mfma_f32_16x16x32_bf16 v[36:39], v[204:207], v[220:223], v[36:39]
	v_mfma_f32_16x16x32_bf16 v[16:19], v[174:177], v[228:231], v[16:19]
	v_mfma_f32_16x16x32_bf16 v[20:23], v[204:207], v[228:231], v[20:23]
	v_mfma_f32_16x16x32_bf16 v[0:3], v[174:177], v[236:239], v[0:3]
	v_mfma_f32_16x16x32_bf16 v[4:7], v[204:207], v[236:239], v[4:7]
	s_barrier
	s_cbranch_scc0 .LBB0_1005
	v_readlane_b32 s68, v255, 7
	s_and_b64 vcc, exec, s[42:43]
	v_readlane_b32 s69, v255, 8
	s_cbranch_vccz .LBB0_1008
	s_barrier

.LBB0_1093:
	v_add_u32_e32 v164, 0x10000, v143
	v_add_u32_e32 v180, 0x14000, v143
	ds_read_b128 v[138:141], v164
	ds_read_b128 v[156:159], v164 offset:1024
	ds_read_b128 v[160:163], v164 offset:2048
	ds_read_b128 v[164:167], v164 offset:3072
	ds_read_b128 v[168:171], v180
	ds_read_b128 v[172:175], v180 offset:1024
	ds_read_b128 v[176:179], v180 offset:2048
	ds_read_b128 v[204:207], v180 offset:3072
	ds_read_b128 v[208:211], v155
	ds_read_b128 v[212:215], v155 offset:1024
	ds_read_b128 v[216:219], v155 offset:2048
	ds_read_b128 v[220:223], v155 offset:3072
	ds_read_b128 v[224:227], v155 offset:4096
	ds_read_b128 v[228:231], v155 offset:5120
	ds_read_b128 v[232:235], v155 offset:6144
	ds_read_b128 v[236:239], v155 offset:7168
	s_add_u32 s4, s58, 0xfffe0080
	s_addc_u32 s5, s59, -1
	s_add_i32 s74, 0, 0x10000
	s_cmp_eq_u32 s73, 4
	s_cselect_b32 s61, s33, s5
	s_cselect_b32 s60, s36, s4
	s_cselect_b32 s35, s49, s72
	s_cselect_b32 s34, s51, s71
	s_add_i32 s75, 0, 0x14000
	v_lshl_add_u64 v[180:181], s[58:59], 0, v[134:135]
	s_add_i32 m0, s64, 0xc000
	s_nop 0
	global_load_lds_dwordx4 v[180:181], off
	v_lshl_add_u64 v[180:181], s[58:59], 0, v[136:137]
	s_add_i32 m0, s64, 0xe000
	s_nop 0
	global_load_lds_dwordx4 v[180:181], off
	s_waitcnt vmcnt(8)
	s_waitcnt lgkmcnt(0)
	s_barrier
	v_mfma_f32_16x16x32_bf16 v[124:127], v[138:141], v[208:211], v[124:127]
	v_mfma_f32_16x16x32_bf16 v[120:123], v[160:163], v[208:211], v[120:123]
	v_mfma_f32_16x16x32_bf16 v[108:111], v[138:141], v[216:219], v[108:111]
	v_mfma_f32_16x16x32_bf16 v[104:107], v[160:163], v[216:219], v[104:107]
	v_mfma_f32_16x16x32_bf16 v[92:95], v[138:141], v[224:227], v[92:95]
	v_mfma_f32_16x16x32_bf16 v[88:91], v[160:163], v[224:227], v[88:91]
	v_mfma_f32_16x16x32_bf16 v[76:79], v[138:141], v[232:235], v[76:79]
	v_mfma_f32_16x16x32_bf16 v[72:75], v[160:163], v[232:235], v[72:75]
	v_mfma_f32_16x16x32_bf16 v[124:127], v[156:159], v[212:215], v[124:127]
	v_mfma_f32_16x16x32_bf16 v[120:123], v[164:167], v[212:215], v[120:123]
	v_mfma_f32_16x16x32_bf16 v[108:111], v[156:159], v[220:223], v[108:111]
	v_mfma_f32_16x16x32_bf16 v[104:107], v[164:167], v[220:223], v[104:107]
	v_mfma_f32_16x16x32_bf16 v[92:95], v[156:159], v[228:231], v[92:95]
	v_mfma_f32_16x16x32_bf16 v[88:91], v[164:167], v[228:231], v[88:91]
	v_mfma_f32_16x16x32_bf16 v[76:79], v[156:159], v[236:239], v[76:79]
	v_mfma_f32_16x16x32_bf16 v[72:75], v[164:167], v[236:239], v[72:75]
	v_mfma_f32_16x16x32_bf16 v[116:119], v[168:171], v[208:211], v[116:119]
	v_mfma_f32_16x16x32_bf16 v[112:115], v[176:179], v[208:211], v[112:115]
	v_mfma_f32_16x16x32_bf16 v[100:103], v[168:171], v[216:219], v[100:103]
	v_mfma_f32_16x16x32_bf16 v[96:99], v[176:179], v[216:219], v[96:99]
	v_mfma_f32_16x16x32_bf16 v[84:87], v[168:171], v[224:227], v[84:87]
	v_mfma_f32_16x16x32_bf16 v[80:83], v[176:179], v[224:227], v[80:83]
	v_mfma_f32_16x16x32_bf16 v[68:71], v[168:171], v[232:235], v[68:71]
	v_mfma_f32_16x16x32_bf16 v[64:67], v[176:179], v[232:235], v[64:67]
	v_mfma_f32_16x16x32_bf16 v[116:119], v[172:175], v[212:215], v[116:119]
	v_mfma_f32_16x16x32_bf16 v[112:115], v[204:207], v[212:215], v[112:115]
	v_mfma_f32_16x16x32_bf16 v[100:103], v[172:175], v[220:223], v[100:103]
	v_mfma_f32_16x16x32_bf16 v[96:99], v[204:207], v[220:223], v[96:99]
	v_mfma_f32_16x16x32_bf16 v[84:87], v[172:175], v[228:231], v[84:87]
	v_mfma_f32_16x16x32_bf16 v[80:83], v[204:207], v[228:231], v[80:83]
	v_mfma_f32_16x16x32_bf16 v[68:71], v[172:175], v[236:239], v[68:71]
	v_mfma_f32_16x16x32_bf16 v[64:67], v[204:207], v[236:239], v[64:67]
	s_barrier
	s_add_i32 s4, s74, s28
	v_lshl_add_u64 v[180:181], s[34:35], 0, v[144:145]
	s_mov_b32 m0, s4
	ds_read_b128 v[208:211], v155 offset:16384
	ds_read_b128 v[212:215], v155 offset:17408
	ds_read_b128 v[216:219], v155 offset:18432
	ds_read_b128 v[220:223], v155 offset:19456
	ds_read_b128 v[224:227], v155 offset:20480
	ds_read_b128 v[228:231], v155 offset:21504
	ds_read_b128 v[232:235], v155 offset:22528
	ds_read_b128 v[236:239], v155 offset:23552
	global_load_lds_dwordx4 v[180:181], off
	s_add_i32 m0, s4, 0x2000
	s_add_u32 s4, s34, 0x20000
	v_lshl_add_u64 v[202:203], s[34:35], 0, v[132:133]
	s_addc_u32 s5, s35, 0
	s_add_i32 s74, s75, s28
	global_load_lds_dwordx4 v[202:203], off
	v_lshl_add_u64 v[240:241], s[4:5], 0, v[144:145]
	s_mov_b32 m0, s74
	v_lshl_add_u64 v[242:243], s[60:61], 0, v[130:131]
	global_load_lds_dwordx4 v[240:241], off
	v_lshl_add_u64 v[240:241], s[4:5], 0, v[132:133]
	s_add_i32 m0, s74, 0x2000
	s_nop 0
	global_load_lds_dwordx4 v[240:241], off
	v_lshl_add_u64 v[240:241], s[60:61], 0, v[128:129]
	s_mov_b32 m0, s64
	s_nop 0
	global_load_lds_dwordx4 v[240:241], off
	s_mov_b32 m0, s65
	s_nop 0
	global_load_lds_dwordx4 v[242:243], off
	s_waitcnt vmcnt(8)
	s_waitcnt lgkmcnt(0)
	s_barrier
	v_mfma_f32_16x16x32_bf16 v[60:63], v[138:141], v[208:211], v[60:63]
	v_mfma_f32_16x16x32_bf16 v[56:59], v[160:163], v[208:211], v[56:59]
	v_mfma_f32_16x16x32_bf16 v[44:47], v[138:141], v[216:219], v[44:47]
	v_mfma_f32_16x16x32_bf16 v[40:43], v[160:163], v[216:219], v[40:43]
	v_mfma_f32_16x16x32_bf16 v[28:31], v[138:141], v[224:227], v[28:31]
	v_mfma_f32_16x16x32_bf16 v[24:27], v[160:163], v[224:227], v[24:27]
	v_mfma_f32_16x16x32_bf16 v[12:15], v[138:141], v[232:235], v[12:15]
	v_mfma_f32_16x16x32_bf16 v[8:11], v[160:163], v[232:235], v[8:11]
	v_mfma_f32_16x16x32_bf16 v[60:63], v[156:159], v[212:215], v[60:63]
	v_mfma_f32_16x16x32_bf16 v[56:59], v[164:167], v[212:215], v[56:59]
	v_mfma_f32_16x16x32_bf16 v[44:47], v[156:159], v[220:223], v[44:47]
	v_mfma_f32_16x16x32_bf16 v[40:43], v[164:167], v[220:223], v[40:43]
	v_mfma_f32_16x16x32_bf16 v[28:31], v[156:159], v[228:231], v[28:31]
	v_mfma_f32_16x16x32_bf16 v[24:27], v[164:167], v[228:231], v[24:27]
	v_mfma_f32_16x16x32_bf16 v[12:15], v[156:159], v[236:239], v[12:15]
	v_mfma_f32_16x16x32_bf16 v[8:11], v[164:167], v[236:239], v[8:11]
	v_mfma_f32_16x16x32_bf16 v[52:55], v[168:171], v[208:211], v[52:55]
	v_mfma_f32_16x16x32_bf16 v[48:51], v[176:179], v[208:211], v[48:51]
	v_mfma_f32_16x16x32_bf16 v[36:39], v[168:171], v[216:219], v[36:39]
	v_mfma_f32_16x16x32_bf16 v[32:35], v[176:179], v[216:219], v[32:35]
	v_mfma_f32_16x16x32_bf16 v[20:23], v[168:171], v[224:227], v[20:23]
	v_mfma_f32_16x16x32_bf16 v[16:19], v[176:179], v[224:227], v[16:19]
	v_mfma_f32_16x16x32_bf16 v[4:7], v[168:171], v[232:235], v[4:7]
	v_mfma_f32_16x16x32_bf16 v[0:3], v[176:179], v[232:235], v[0:3]
	v_mfma_f32_16x16x32_bf16 v[52:55], v[172:175], v[212:215], v[52:55]
	v_mfma_f32_16x16x32_bf16 v[48:51], v[204:207], v[212:215], v[48:51]
	v_mfma_f32_16x16x32_bf16 v[36:39], v[172:175], v[220:223], v[36:39]
	v_mfma_f32_16x16x32_bf16 v[32:35], v[204:207], v[220:223], v[32:35]
	v_mfma_f32_16x16x32_bf16 v[20:23], v[172:175], v[228:231], v[20:23]
	v_mfma_f32_16x16x32_bf16 v[16:19], v[204:207], v[228:231], v[16:19]
	v_mfma_f32_16x16x32_bf16 v[4:7], v[172:175], v[236:239], v[4:7]
	v_mfma_f32_16x16x32_bf16 v[0:3], v[204:207], v[236:239], v[0:3]
	s_barrier
	v_add_u32_e32 v164, 0x18000, v143
	v_add_u32_e32 v204, 0x1c000, v143
	ds_read_b128 v[138:141], v164
	ds_read_b128 v[156:159], v164 offset:1024
	ds_read_b128 v[160:163], v164 offset:2048
	ds_read_b128 v[164:167], v164 offset:3072
	ds_read_b128 v[168:171], v204
	ds_read_b128 v[172:175], v204 offset:1024
	ds_read_b128 v[176:179], v204 offset:2048
	ds_read_b128 v[204:207], v204 offset:3072
	ds_read_b128 v[208:211], v155 offset:32768
	ds_read_b128 v[212:215], v155 offset:33792
	ds_read_b128 v[216:219], v155 offset:34816
	ds_read_b128 v[220:223], v155 offset:35840
	ds_read_b128 v[224:227], v155 offset:36864
	ds_read_b128 v[228:231], v155 offset:37888
	ds_read_b128 v[232:235], v155 offset:38912
	ds_read_b128 v[236:239], v155 offset:39936
	s_add_i32 s74, 0, 0x18000
	s_add_i32 s75, 0, 0x1c000
	s_add_u32 s4, s60, 0x20000
	s_addc_u32 s5, s61, 0
	s_mov_b32 m0, s66
	v_lshl_add_u64 v[244:245], s[4:5], 0, v[128:129]
	global_load_lds_dwordx4 v[244:245], off
	v_lshl_add_u64 v[244:245], s[4:5], 0, v[130:131]
	s_mov_b32 m0, s67
	s_nop 0
	global_load_lds_dwordx4 v[244:245], off
	s_waitcnt vmcnt(8)
	s_waitcnt lgkmcnt(0)
	s_barrier
	v_mfma_f32_16x16x32_bf16 v[124:127], v[138:141], v[208:211], v[124:127]
	v_mfma_f32_16x16x32_bf16 v[120:123], v[160:163], v[208:211], v[120:123]
	v_mfma_f32_16x16x32_bf16 v[108:111], v[138:141], v[216:219], v[108:111]
	v_mfma_f32_16x16x32_bf16 v[104:107], v[160:163], v[216:219], v[104:107]
	v_mfma_f32_16x16x32_bf16 v[92:95], v[138:141], v[224:227], v[92:95]
	v_mfma_f32_16x16x32_bf16 v[88:91], v[160:163], v[224:227], v[88:91]
	v_mfma_f32_16x16x32_bf16 v[76:79], v[138:141], v[232:235], v[76:79]
	v_mfma_f32_16x16x32_bf16 v[72:75], v[160:163], v[232:235], v[72:75]
	v_mfma_f32_16x16x32_bf16 v[124:127], v[156:159], v[212:215], v[124:127]
	v_mfma_f32_16x16x32_bf16 v[120:123], v[164:167], v[212:215], v[120:123]
	v_mfma_f32_16x16x32_bf16 v[108:111], v[156:159], v[220:223], v[108:111]
	v_mfma_f32_16x16x32_bf16 v[104:107], v[164:167], v[220:223], v[104:107]
	v_mfma_f32_16x16x32_bf16 v[92:95], v[156:159], v[228:231], v[92:95]
	v_mfma_f32_16x16x32_bf16 v[88:91], v[164:167], v[228:231], v[88:91]
	v_mfma_f32_16x16x32_bf16 v[76:79], v[156:159], v[236:239], v[76:79]
	v_mfma_f32_16x16x32_bf16 v[72:75], v[164:167], v[236:239], v[72:75]
	v_mfma_f32_16x16x32_bf16 v[116:119], v[168:171], v[208:211], v[116:119]
	v_mfma_f32_16x16x32_bf16 v[112:115], v[176:179], v[208:211], v[112:115]
	v_mfma_f32_16x16x32_bf16 v[100:103], v[168:171], v[216:219], v[100:103]
	v_mfma_f32_16x16x32_bf16 v[96:99], v[176:179], v[216:219], v[96:99]
	v_mfma_f32_16x16x32_bf16 v[84:87], v[168:171], v[224:227], v[84:87]
	v_mfma_f32_16x16x32_bf16 v[80:83], v[176:179], v[224:227], v[80:83]
	v_mfma_f32_16x16x32_bf16 v[68:71], v[168:171], v[232:235], v[68:71]
	v_mfma_f32_16x16x32_bf16 v[64:67], v[176:179], v[232:235], v[64:67]
	v_mfma_f32_16x16x32_bf16 v[116:119], v[172:175], v[212:215], v[116:119]
	v_mfma_f32_16x16x32_bf16 v[112:115], v[204:207], v[212:215], v[112:115]
	v_mfma_f32_16x16x32_bf16 v[100:103], v[172:175], v[220:223], v[100:103]
	v_mfma_f32_16x16x32_bf16 v[96:99], v[204:207], v[220:223], v[96:99]
	v_mfma_f32_16x16x32_bf16 v[84:87], v[172:175], v[228:231], v[84:87]
	v_mfma_f32_16x16x32_bf16 v[80:83], v[204:207], v[228:231], v[80:83]
	v_mfma_f32_16x16x32_bf16 v[68:71], v[172:175], v[236:239], v[68:71]
	v_mfma_f32_16x16x32_bf16 v[64:67], v[204:207], v[236:239], v[64:67]
	s_barrier
	s_add_i32 s4, s74, s28
	v_lshl_add_u64 v[180:181], v[180:181], 0, s[26:27]
	s_mov_b32 m0, s4
	ds_read_b128 v[208:211], v155 offset:49152
	ds_read_b128 v[212:215], v155 offset:50176
	ds_read_b128 v[216:219], v155 offset:51200
	ds_read_b128 v[220:223], v155 offset:52224
	ds_read_b128 v[224:227], v155 offset:53248
	ds_read_b128 v[228:231], v155 offset:54272
	ds_read_b128 v[232:235], v155 offset:55296
	ds_read_b128 v[236:239], v155 offset:56320
	global_load_lds_dwordx4 v[180:181], off
	s_add_i32 m0, s4, 0x2000
	s_add_u32 s4, s34, 0x20080
	v_lshl_add_u64 v[180:181], v[202:203], 0, s[26:27]
	s_addc_u32 s5, s35, 0
	s_add_i32 s34, s75, s28
	global_load_lds_dwordx4 v[180:181], off
	v_lshl_add_u64 v[180:181], s[4:5], 0, v[144:145]
	s_mov_b32 m0, s34
	s_nop 0
	global_load_lds_dwordx4 v[180:181], off
	v_lshl_add_u64 v[180:181], s[4:5], 0, v[132:133]
	s_add_i32 m0, s34, 0x2000
	s_nop 0
	global_load_lds_dwordx4 v[180:181], off
	v_lshl_add_u64 v[180:181], v[240:241], 0, s[26:27]
	s_mov_b32 m0, s68
	s_nop 0
	global_load_lds_dwordx4 v[180:181], off
	v_lshl_add_u64 v[180:181], v[242:243], 0, s[26:27]
	s_mov_b32 m0, s69
	s_nop 0
	global_load_lds_dwordx4 v[180:181], off
	s_add_i32 s73, s73, 2
	s_add_u32 s58, s58, 0x100
	s_addc_u32 s59, s59, 0
	s_add_u32 s71, s71, 0x100
	s_addc_u32 s72, s72, 0
	s_cmp_gt_u32 s73, 5
	s_waitcnt vmcnt(8)
	s_waitcnt lgkmcnt(0)
	s_barrier
	v_mfma_f32_16x16x32_bf16 v[60:63], v[138:141], v[208:211], v[60:63]
	v_mfma_f32_16x16x32_bf16 v[56:59], v[160:163], v[208:211], v[56:59]
	v_mfma_f32_16x16x32_bf16 v[44:47], v[138:141], v[216:219], v[44:47]
	v_mfma_f32_16x16x32_bf16 v[40:43], v[160:163], v[216:219], v[40:43]
	v_mfma_f32_16x16x32_bf16 v[28:31], v[138:141], v[224:227], v[28:31]
	v_mfma_f32_16x16x32_bf16 v[24:27], v[160:163], v[224:227], v[24:27]
	v_mfma_f32_16x16x32_bf16 v[12:15], v[138:141], v[232:235], v[12:15]
	v_mfma_f32_16x16x32_bf16 v[8:11], v[160:163], v[232:235], v[8:11]
	v_mfma_f32_16x16x32_bf16 v[60:63], v[156:159], v[212:215], v[60:63]
	v_mfma_f32_16x16x32_bf16 v[56:59], v[164:167], v[212:215], v[56:59]
	v_mfma_f32_16x16x32_bf16 v[44:47], v[156:159], v[220:223], v[44:47]
	v_mfma_f32_16x16x32_bf16 v[40:43], v[164:167], v[220:223], v[40:43]
	v_mfma_f32_16x16x32_bf16 v[28:31], v[156:159], v[228:231], v[28:31]
	v_mfma_f32_16x16x32_bf16 v[24:27], v[164:167], v[228:231], v[24:27]
	v_mfma_f32_16x16x32_bf16 v[12:15], v[156:159], v[236:239], v[12:15]
	v_mfma_f32_16x16x32_bf16 v[8:11], v[164:167], v[236:239], v[8:11]
	v_mfma_f32_16x16x32_bf16 v[52:55], v[168:171], v[208:211], v[52:55]
	v_mfma_f32_16x16x32_bf16 v[48:51], v[176:179], v[208:211], v[48:51]
	v_mfma_f32_16x16x32_bf16 v[36:39], v[168:171], v[216:219], v[36:39]
	v_mfma_f32_16x16x32_bf16 v[32:35], v[176:179], v[216:219], v[32:35]
	v_mfma_f32_16x16x32_bf16 v[20:23], v[168:171], v[224:227], v[20:23]
	v_mfma_f32_16x16x32_bf16 v[16:19], v[176:179], v[224:227], v[16:19]
	v_mfma_f32_16x16x32_bf16 v[4:7], v[168:171], v[232:235], v[4:7]
	v_mfma_f32_16x16x32_bf16 v[0:3], v[176:179], v[232:235], v[0:3]
	v_mfma_f32_16x16x32_bf16 v[52:55], v[172:175], v[212:215], v[52:55]
	v_mfma_f32_16x16x32_bf16 v[48:51], v[204:207], v[212:215], v[48:51]
	v_mfma_f32_16x16x32_bf16 v[36:39], v[172:175], v[220:223], v[36:39]
	v_mfma_f32_16x16x32_bf16 v[32:35], v[204:207], v[220:223], v[32:35]
	v_mfma_f32_16x16x32_bf16 v[20:23], v[172:175], v[228:231], v[20:23]
	v_mfma_f32_16x16x32_bf16 v[16:19], v[204:207], v[228:231], v[16:19]
	v_mfma_f32_16x16x32_bf16 v[4:7], v[172:175], v[236:239], v[4:7]
	v_mfma_f32_16x16x32_bf16 v[0:3], v[204:207], v[236:239], v[0:3]
	s_barrier
	s_cbranch_scc0 .LBB0_1093
	s_and_b64 vcc, exec, s[46:47]
	s_cbranch_vccz .LBB0_1096
	s_barrier

.LBB0_1117:
	v_add_u32_e32 v164, 0x10000, v143
	v_add_u32_e32 v180, 0x14000, v143
	ds_read_b128 v[138:141], v164
	ds_read_b128 v[156:159], v164 offset:1024
	ds_read_b128 v[160:163], v164 offset:2048
	ds_read_b128 v[164:167], v164 offset:3072
	ds_read_b128 v[168:171], v180
	ds_read_b128 v[172:175], v180 offset:1024
	ds_read_b128 v[176:179], v180 offset:2048
	ds_read_b128 v[204:207], v180 offset:3072
	ds_read_b128 v[208:211], v155
	ds_read_b128 v[212:215], v155 offset:1024
	ds_read_b128 v[216:219], v155 offset:2048
	ds_read_b128 v[220:223], v155 offset:3072
	ds_read_b128 v[224:227], v155 offset:4096
	ds_read_b128 v[228:231], v155 offset:5120
	ds_read_b128 v[232:235], v155 offset:6144
	ds_read_b128 v[236:239], v155 offset:7168
	s_add_u32 s4, s54, 0xfffe0080
	s_addc_u32 s5, s55, -1
	s_add_i32 s74, 0, 0x10000
	s_cmp_eq_u32 s73, 4
	s_cselect_b32 s59, s33, s5
	s_cselect_b32 s58, s36, s4
	s_cselect_b32 s35, s47, s72
	s_cselect_b32 s34, s49, s71
	s_add_i32 s75, 0, 0x14000
	v_lshl_add_u64 v[180:181], s[54:55], 0, v[134:135]
	s_add_i32 m0, s64, 0xc000
	s_nop 0
	global_load_lds_dwordx4 v[180:181], off
	v_lshl_add_u64 v[180:181], s[54:55], 0, v[136:137]
	s_add_i32 m0, s64, 0xe000
	s_nop 0
	global_load_lds_dwordx4 v[180:181], off
	s_waitcnt vmcnt(8)
	s_waitcnt lgkmcnt(0)
	s_barrier
	v_mfma_f32_16x16x32_bf16 v[124:127], v[138:141], v[208:211], v[124:127]
	v_mfma_f32_16x16x32_bf16 v[120:123], v[160:163], v[208:211], v[120:123]
	v_mfma_f32_16x16x32_bf16 v[108:111], v[138:141], v[216:219], v[108:111]
	v_mfma_f32_16x16x32_bf16 v[104:107], v[160:163], v[216:219], v[104:107]
	v_mfma_f32_16x16x32_bf16 v[92:95], v[138:141], v[224:227], v[92:95]
	v_mfma_f32_16x16x32_bf16 v[88:91], v[160:163], v[224:227], v[88:91]
	v_mfma_f32_16x16x32_bf16 v[76:79], v[138:141], v[232:235], v[76:79]
	v_mfma_f32_16x16x32_bf16 v[72:75], v[160:163], v[232:235], v[72:75]
	v_mfma_f32_16x16x32_bf16 v[124:127], v[156:159], v[212:215], v[124:127]
	v_mfma_f32_16x16x32_bf16 v[120:123], v[164:167], v[212:215], v[120:123]
	v_mfma_f32_16x16x32_bf16 v[108:111], v[156:159], v[220:223], v[108:111]
	v_mfma_f32_16x16x32_bf16 v[104:107], v[164:167], v[220:223], v[104:107]
	v_mfma_f32_16x16x32_bf16 v[92:95], v[156:159], v[228:231], v[92:95]
	v_mfma_f32_16x16x32_bf16 v[88:91], v[164:167], v[228:231], v[88:91]
	v_mfma_f32_16x16x32_bf16 v[76:79], v[156:159], v[236:239], v[76:79]
	v_mfma_f32_16x16x32_bf16 v[72:75], v[164:167], v[236:239], v[72:75]
	v_mfma_f32_16x16x32_bf16 v[116:119], v[168:171], v[208:211], v[116:119]
	v_mfma_f32_16x16x32_bf16 v[112:115], v[176:179], v[208:211], v[112:115]
	v_mfma_f32_16x16x32_bf16 v[100:103], v[168:171], v[216:219], v[100:103]
	v_mfma_f32_16x16x32_bf16 v[96:99], v[176:179], v[216:219], v[96:99]
	v_mfma_f32_16x16x32_bf16 v[84:87], v[168:171], v[224:227], v[84:87]
	v_mfma_f32_16x16x32_bf16 v[80:83], v[176:179], v[224:227], v[80:83]
	v_mfma_f32_16x16x32_bf16 v[68:71], v[168:171], v[232:235], v[68:71]
	v_mfma_f32_16x16x32_bf16 v[64:67], v[176:179], v[232:235], v[64:67]
	v_mfma_f32_16x16x32_bf16 v[116:119], v[172:175], v[212:215], v[116:119]
	v_mfma_f32_16x16x32_bf16 v[112:115], v[204:207], v[212:215], v[112:115]
	v_mfma_f32_16x16x32_bf16 v[100:103], v[172:175], v[220:223], v[100:103]
	v_mfma_f32_16x16x32_bf16 v[96:99], v[204:207], v[220:223], v[96:99]
	v_mfma_f32_16x16x32_bf16 v[84:87], v[172:175], v[228:231], v[84:87]
	v_mfma_f32_16x16x32_bf16 v[80:83], v[204:207], v[228:231], v[80:83]
	v_mfma_f32_16x16x32_bf16 v[68:71], v[172:175], v[236:239], v[68:71]
	v_mfma_f32_16x16x32_bf16 v[64:67], v[204:207], v[236:239], v[64:67]
	s_barrier
	s_add_i32 s4, s74, s63
	v_lshl_add_u64 v[180:181], s[34:35], 0, v[144:145]
	s_mov_b32 m0, s4
	ds_read_b128 v[208:211], v155 offset:16384
	ds_read_b128 v[212:215], v155 offset:17408
	ds_read_b128 v[216:219], v155 offset:18432
	ds_read_b128 v[220:223], v155 offset:19456
	ds_read_b128 v[224:227], v155 offset:20480
	ds_read_b128 v[228:231], v155 offset:21504
	ds_read_b128 v[232:235], v155 offset:22528
	ds_read_b128 v[236:239], v155 offset:23552
	global_load_lds_dwordx4 v[180:181], off
	s_add_i32 m0, s4, 0x2000
	s_add_u32 s4, s34, 0x20000
	v_lshl_add_u64 v[202:203], s[34:35], 0, v[132:133]
	s_addc_u32 s5, s35, 0
	s_add_i32 s74, s75, s63
	global_load_lds_dwordx4 v[202:203], off
	v_lshl_add_u64 v[240:241], s[4:5], 0, v[144:145]
	s_mov_b32 m0, s74
	v_lshl_add_u64 v[242:243], s[58:59], 0, v[130:131]
	global_load_lds_dwordx4 v[240:241], off
	v_lshl_add_u64 v[240:241], s[4:5], 0, v[132:133]
	s_add_i32 m0, s74, 0x2000
	s_nop 0
	global_load_lds_dwordx4 v[240:241], off
	v_lshl_add_u64 v[240:241], s[58:59], 0, v[128:129]
	s_mov_b32 m0, s64
	s_nop 0
	global_load_lds_dwordx4 v[240:241], off
	s_mov_b32 m0, s65
	s_nop 0
	global_load_lds_dwordx4 v[242:243], off
	s_waitcnt vmcnt(8)
	s_waitcnt lgkmcnt(0)
	s_barrier
	v_mfma_f32_16x16x32_bf16 v[60:63], v[138:141], v[208:211], v[60:63]
	v_mfma_f32_16x16x32_bf16 v[56:59], v[160:163], v[208:211], v[56:59]
	v_mfma_f32_16x16x32_bf16 v[44:47], v[138:141], v[216:219], v[44:47]
	v_mfma_f32_16x16x32_bf16 v[40:43], v[160:163], v[216:219], v[40:43]
	v_mfma_f32_16x16x32_bf16 v[28:31], v[138:141], v[224:227], v[28:31]
	v_mfma_f32_16x16x32_bf16 v[24:27], v[160:163], v[224:227], v[24:27]
	v_mfma_f32_16x16x32_bf16 v[12:15], v[138:141], v[232:235], v[12:15]
	v_mfma_f32_16x16x32_bf16 v[8:11], v[160:163], v[232:235], v[8:11]
	v_mfma_f32_16x16x32_bf16 v[60:63], v[156:159], v[212:215], v[60:63]
	v_mfma_f32_16x16x32_bf16 v[56:59], v[164:167], v[212:215], v[56:59]
	v_mfma_f32_16x16x32_bf16 v[44:47], v[156:159], v[220:223], v[44:47]
	v_mfma_f32_16x16x32_bf16 v[40:43], v[164:167], v[220:223], v[40:43]
	v_mfma_f32_16x16x32_bf16 v[28:31], v[156:159], v[228:231], v[28:31]
	v_mfma_f32_16x16x32_bf16 v[24:27], v[164:167], v[228:231], v[24:27]
	v_mfma_f32_16x16x32_bf16 v[12:15], v[156:159], v[236:239], v[12:15]
	v_mfma_f32_16x16x32_bf16 v[8:11], v[164:167], v[236:239], v[8:11]
	v_mfma_f32_16x16x32_bf16 v[52:55], v[168:171], v[208:211], v[52:55]
	v_mfma_f32_16x16x32_bf16 v[48:51], v[176:179], v[208:211], v[48:51]
	v_mfma_f32_16x16x32_bf16 v[36:39], v[168:171], v[216:219], v[36:39]
	v_mfma_f32_16x16x32_bf16 v[32:35], v[176:179], v[216:219], v[32:35]
	v_mfma_f32_16x16x32_bf16 v[20:23], v[168:171], v[224:227], v[20:23]
	v_mfma_f32_16x16x32_bf16 v[16:19], v[176:179], v[224:227], v[16:19]
	v_mfma_f32_16x16x32_bf16 v[4:7], v[168:171], v[232:235], v[4:7]
	v_mfma_f32_16x16x32_bf16 v[0:3], v[176:179], v[232:235], v[0:3]
	v_mfma_f32_16x16x32_bf16 v[52:55], v[172:175], v[212:215], v[52:55]
	v_mfma_f32_16x16x32_bf16 v[48:51], v[204:207], v[212:215], v[48:51]
	v_mfma_f32_16x16x32_bf16 v[36:39], v[172:175], v[220:223], v[36:39]
	v_mfma_f32_16x16x32_bf16 v[32:35], v[204:207], v[220:223], v[32:35]
	v_mfma_f32_16x16x32_bf16 v[20:23], v[172:175], v[228:231], v[20:23]
	v_mfma_f32_16x16x32_bf16 v[16:19], v[204:207], v[228:231], v[16:19]
	v_mfma_f32_16x16x32_bf16 v[4:7], v[172:175], v[236:239], v[4:7]
	v_mfma_f32_16x16x32_bf16 v[0:3], v[204:207], v[236:239], v[0:3]
	s_barrier
	v_add_u32_e32 v164, 0x18000, v143
	v_add_u32_e32 v204, 0x1c000, v143
	ds_read_b128 v[138:141], v164
	ds_read_b128 v[156:159], v164 offset:1024
	ds_read_b128 v[160:163], v164 offset:2048
	ds_read_b128 v[164:167], v164 offset:3072
	ds_read_b128 v[168:171], v204
	ds_read_b128 v[172:175], v204 offset:1024
	ds_read_b128 v[176:179], v204 offset:2048
	ds_read_b128 v[204:207], v204 offset:3072
	ds_read_b128 v[208:211], v155 offset:32768
	ds_read_b128 v[212:215], v155 offset:33792
	ds_read_b128 v[216:219], v155 offset:34816
	ds_read_b128 v[220:223], v155 offset:35840
	ds_read_b128 v[224:227], v155 offset:36864
	ds_read_b128 v[228:231], v155 offset:37888
	ds_read_b128 v[232:235], v155 offset:38912
	ds_read_b128 v[236:239], v155 offset:39936
	s_add_i32 s74, 0, 0x18000
	s_add_i32 s75, 0, 0x1c000
	s_add_u32 s4, s58, 0x20000
	s_addc_u32 s5, s59, 0
	s_mov_b32 m0, s66
	v_lshl_add_u64 v[244:245], s[4:5], 0, v[128:129]
	global_load_lds_dwordx4 v[244:245], off
	v_lshl_add_u64 v[244:245], s[4:5], 0, v[130:131]
	s_mov_b32 m0, s67
	s_nop 0
	global_load_lds_dwordx4 v[244:245], off
	s_waitcnt vmcnt(8)
	s_waitcnt lgkmcnt(0)
	s_barrier
	v_mfma_f32_16x16x32_bf16 v[124:127], v[138:141], v[208:211], v[124:127]
	v_mfma_f32_16x16x32_bf16 v[120:123], v[160:163], v[208:211], v[120:123]
	v_mfma_f32_16x16x32_bf16 v[108:111], v[138:141], v[216:219], v[108:111]
	v_mfma_f32_16x16x32_bf16 v[104:107], v[160:163], v[216:219], v[104:107]
	v_mfma_f32_16x16x32_bf16 v[92:95], v[138:141], v[224:227], v[92:95]
	v_mfma_f32_16x16x32_bf16 v[88:91], v[160:163], v[224:227], v[88:91]
	v_mfma_f32_16x16x32_bf16 v[76:79], v[138:141], v[232:235], v[76:79]
	v_mfma_f32_16x16x32_bf16 v[72:75], v[160:163], v[232:235], v[72:75]
	v_mfma_f32_16x16x32_bf16 v[124:127], v[156:159], v[212:215], v[124:127]
	v_mfma_f32_16x16x32_bf16 v[120:123], v[164:167], v[212:215], v[120:123]
	v_mfma_f32_16x16x32_bf16 v[108:111], v[156:159], v[220:223], v[108:111]
	v_mfma_f32_16x16x32_bf16 v[104:107], v[164:167], v[220:223], v[104:107]
	v_mfma_f32_16x16x32_bf16 v[92:95], v[156:159], v[228:231], v[92:95]
	v_mfma_f32_16x16x32_bf16 v[88:91], v[164:167], v[228:231], v[88:91]
	v_mfma_f32_16x16x32_bf16 v[76:79], v[156:159], v[236:239], v[76:79]
	v_mfma_f32_16x16x32_bf16 v[72:75], v[164:167], v[236:239], v[72:75]
	v_mfma_f32_16x16x32_bf16 v[116:119], v[168:171], v[208:211], v[116:119]
	v_mfma_f32_16x16x32_bf16 v[112:115], v[176:179], v[208:211], v[112:115]
	v_mfma_f32_16x16x32_bf16 v[100:103], v[168:171], v[216:219], v[100:103]
	v_mfma_f32_16x16x32_bf16 v[96:99], v[176:179], v[216:219], v[96:99]
	v_mfma_f32_16x16x32_bf16 v[84:87], v[168:171], v[224:227], v[84:87]
	v_mfma_f32_16x16x32_bf16 v[80:83], v[176:179], v[224:227], v[80:83]
	v_mfma_f32_16x16x32_bf16 v[68:71], v[168:171], v[232:235], v[68:71]
	v_mfma_f32_16x16x32_bf16 v[64:67], v[176:179], v[232:235], v[64:67]
	v_mfma_f32_16x16x32_bf16 v[116:119], v[172:175], v[212:215], v[116:119]
	v_mfma_f32_16x16x32_bf16 v[112:115], v[204:207], v[212:215], v[112:115]
	v_mfma_f32_16x16x32_bf16 v[100:103], v[172:175], v[220:223], v[100:103]
	v_mfma_f32_16x16x32_bf16 v[96:99], v[204:207], v[220:223], v[96:99]
	v_mfma_f32_16x16x32_bf16 v[84:87], v[172:175], v[228:231], v[84:87]
	v_mfma_f32_16x16x32_bf16 v[80:83], v[204:207], v[228:231], v[80:83]
	v_mfma_f32_16x16x32_bf16 v[68:71], v[172:175], v[236:239], v[68:71]
	v_mfma_f32_16x16x32_bf16 v[64:67], v[204:207], v[236:239], v[64:67]
	s_barrier
	s_add_i32 s4, s74, s63
	v_lshl_add_u64 v[180:181], v[180:181], 0, s[26:27]
	s_mov_b32 m0, s4
	ds_read_b128 v[208:211], v155 offset:49152
	ds_read_b128 v[212:215], v155 offset:50176
	ds_read_b128 v[216:219], v155 offset:51200
	ds_read_b128 v[220:223], v155 offset:52224
	ds_read_b128 v[224:227], v155 offset:53248
	ds_read_b128 v[228:231], v155 offset:54272
	ds_read_b128 v[232:235], v155 offset:55296
	ds_read_b128 v[236:239], v155 offset:56320
	global_load_lds_dwordx4 v[180:181], off
	s_add_i32 m0, s4, 0x2000
	s_add_u32 s4, s34, 0x20080
	v_lshl_add_u64 v[180:181], v[202:203], 0, s[26:27]
	s_addc_u32 s5, s35, 0
	s_add_i32 s34, s75, s63
	global_load_lds_dwordx4 v[180:181], off
	v_lshl_add_u64 v[180:181], s[4:5], 0, v[144:145]
	s_mov_b32 m0, s34
	s_nop 0
	global_load_lds_dwordx4 v[180:181], off
	v_lshl_add_u64 v[180:181], s[4:5], 0, v[132:133]
	s_add_i32 m0, s34, 0x2000
	s_nop 0
	global_load_lds_dwordx4 v[180:181], off
	v_lshl_add_u64 v[180:181], v[240:241], 0, s[26:27]
	s_mov_b32 m0, s68
	s_nop 0
	global_load_lds_dwordx4 v[180:181], off
	v_lshl_add_u64 v[180:181], v[242:243], 0, s[26:27]
	s_mov_b32 m0, s69
	s_nop 0
	global_load_lds_dwordx4 v[180:181], off
	s_add_i32 s73, s73, 2
	s_add_u32 s54, s54, 0x100
	s_addc_u32 s55, s55, 0
	s_add_u32 s71, s71, 0x100
	s_addc_u32 s72, s72, 0
	s_cmp_gt_u32 s73, 5
	s_waitcnt vmcnt(8)
	s_waitcnt lgkmcnt(0)
	s_barrier
	v_mfma_f32_16x16x32_bf16 v[60:63], v[138:141], v[208:211], v[60:63]
	v_mfma_f32_16x16x32_bf16 v[56:59], v[160:163], v[208:211], v[56:59]
	v_mfma_f32_16x16x32_bf16 v[44:47], v[138:141], v[216:219], v[44:47]
	v_mfma_f32_16x16x32_bf16 v[40:43], v[160:163], v[216:219], v[40:43]
	v_mfma_f32_16x16x32_bf16 v[28:31], v[138:141], v[224:227], v[28:31]
	v_mfma_f32_16x16x32_bf16 v[24:27], v[160:163], v[224:227], v[24:27]
	v_mfma_f32_16x16x32_bf16 v[12:15], v[138:141], v[232:235], v[12:15]
	v_mfma_f32_16x16x32_bf16 v[8:11], v[160:163], v[232:235], v[8:11]
	v_mfma_f32_16x16x32_bf16 v[60:63], v[156:159], v[212:215], v[60:63]
	v_mfma_f32_16x16x32_bf16 v[56:59], v[164:167], v[212:215], v[56:59]
	v_mfma_f32_16x16x32_bf16 v[44:47], v[156:159], v[220:223], v[44:47]
	v_mfma_f32_16x16x32_bf16 v[40:43], v[164:167], v[220:223], v[40:43]
	v_mfma_f32_16x16x32_bf16 v[28:31], v[156:159], v[228:231], v[28:31]
	v_mfma_f32_16x16x32_bf16 v[24:27], v[164:167], v[228:231], v[24:27]
	v_mfma_f32_16x16x32_bf16 v[12:15], v[156:159], v[236:239], v[12:15]
	v_mfma_f32_16x16x32_bf16 v[8:11], v[164:167], v[236:239], v[8:11]
	v_mfma_f32_16x16x32_bf16 v[52:55], v[168:171], v[208:211], v[52:55]
	v_mfma_f32_16x16x32_bf16 v[48:51], v[176:179], v[208:211], v[48:51]
	v_mfma_f32_16x16x32_bf16 v[36:39], v[168:171], v[216:219], v[36:39]
	v_mfma_f32_16x16x32_bf16 v[32:35], v[176:179], v[216:219], v[32:35]
	v_mfma_f32_16x16x32_bf16 v[20:23], v[168:171], v[224:227], v[20:23]
	v_mfma_f32_16x16x32_bf16 v[16:19], v[176:179], v[224:227], v[16:19]
	v_mfma_f32_16x16x32_bf16 v[4:7], v[168:171], v[232:235], v[4:7]
	v_mfma_f32_16x16x32_bf16 v[0:3], v[176:179], v[232:235], v[0:3]
	v_mfma_f32_16x16x32_bf16 v[52:55], v[172:175], v[212:215], v[52:55]
	v_mfma_f32_16x16x32_bf16 v[48:51], v[204:207], v[212:215], v[48:51]
	v_mfma_f32_16x16x32_bf16 v[36:39], v[172:175], v[220:223], v[36:39]
	v_mfma_f32_16x16x32_bf16 v[32:35], v[204:207], v[220:223], v[32:35]
	v_mfma_f32_16x16x32_bf16 v[20:23], v[172:175], v[228:231], v[20:23]
	v_mfma_f32_16x16x32_bf16 v[16:19], v[204:207], v[228:231], v[16:19]
	v_mfma_f32_16x16x32_bf16 v[4:7], v[172:175], v[236:239], v[4:7]
	v_mfma_f32_16x16x32_bf16 v[0:3], v[204:207], v[236:239], v[0:3]
	s_barrier
	s_cbranch_scc0 .LBB0_1117
	s_and_b64 vcc, exec, s[44:45]
	s_cbranch_vccz .LBB0_1120
	s_barrier

.LBB0_1207:
	v_add_u32_e32 v142, 0x10000, v160
	ds_read_b128 v[138:141], v142
	ds_read_b128 v[154:157], v142 offset:1024
	ds_read_b128 v[172:175], v142 offset:2048
	ds_read_b128 v[176:179], v142 offset:3072
	v_add_u32_e32 v142, 0x14000, v160
	ds_read_b128 v[204:207], v142
	ds_read_b128 v[208:211], v142 offset:1024
	ds_read_b128 v[212:215], v142 offset:2048
	ds_read_b128 v[216:219], v142 offset:3072
	ds_read_b128 v[220:223], v170
	ds_read_b128 v[224:227], v170 offset:1024
	ds_read_b128 v[228:231], v170 offset:2048
	ds_read_b128 v[232:235], v170 offset:3072
	ds_read_b128 v[236:239], v170 offset:4096
	ds_read_b128 v[240:243], v170 offset:5120
	ds_read_b128 v[244:247], v170 offset:6144
	ds_read_b128 v[248:251], v170 offset:7168
	s_add_u32 s62, s60, 0x100
	s_addc_u32 s63, s61, 0
	s_add_i32 s4, 0, 0x10000
	s_cmp_eq_u32 s29, 12
	s_cselect_b32 s65, s55, s63
	s_cselect_b32 s64, s54, s62
	s_cselect_b32 s35, s59, s28
	s_cselect_b32 s34, s58, s3
	s_add_i32 s45, 0, 0x14000
	v_lshl_add_u64 v[142:143], s[60:61], 0, v[134:135]
	s_add_i32 m0, s69, 0xc000
	s_nop 0
	global_load_lds_dwordx4 v[142:143], off
	v_lshl_add_u64 v[142:143], s[60:61], 0, v[136:137]
	s_add_i32 m0, s69, 0xe000
	s_nop 0
	global_load_lds_dwordx4 v[142:143], off
	s_waitcnt vmcnt(8)
	s_waitcnt lgkmcnt(0)
	s_barrier
	v_mfma_f32_16x16x32_bf16 v[124:127], v[138:141], v[220:223], v[124:127]
	v_mfma_f32_16x16x32_bf16 v[120:123], v[172:175], v[220:223], v[120:123]
	v_mfma_f32_16x16x32_bf16 v[108:111], v[138:141], v[228:231], v[108:111]
	v_mfma_f32_16x16x32_bf16 v[104:107], v[172:175], v[228:231], v[104:107]
	v_mfma_f32_16x16x32_bf16 v[92:95], v[138:141], v[236:239], v[92:95]
	v_mfma_f32_16x16x32_bf16 v[88:91], v[172:175], v[236:239], v[88:91]
	v_mfma_f32_16x16x32_bf16 v[76:79], v[138:141], v[244:247], v[76:79]
	v_mfma_f32_16x16x32_bf16 v[72:75], v[172:175], v[244:247], v[72:75]
	v_mfma_f32_16x16x32_bf16 v[124:127], v[154:157], v[224:227], v[124:127]
	v_mfma_f32_16x16x32_bf16 v[120:123], v[176:179], v[224:227], v[120:123]
	v_mfma_f32_16x16x32_bf16 v[108:111], v[154:157], v[232:235], v[108:111]
	v_mfma_f32_16x16x32_bf16 v[104:107], v[176:179], v[232:235], v[104:107]
	v_mfma_f32_16x16x32_bf16 v[92:95], v[154:157], v[240:243], v[92:95]
	v_mfma_f32_16x16x32_bf16 v[88:91], v[176:179], v[240:243], v[88:91]
	v_mfma_f32_16x16x32_bf16 v[76:79], v[154:157], v[248:251], v[76:79]
	v_mfma_f32_16x16x32_bf16 v[72:75], v[176:179], v[248:251], v[72:75]
	v_mfma_f32_16x16x32_bf16 v[116:119], v[204:207], v[220:223], v[116:119]
	v_mfma_f32_16x16x32_bf16 v[112:115], v[212:215], v[220:223], v[112:115]
	v_mfma_f32_16x16x32_bf16 v[100:103], v[204:207], v[228:231], v[100:103]
	v_mfma_f32_16x16x32_bf16 v[96:99], v[212:215], v[228:231], v[96:99]
	v_mfma_f32_16x16x32_bf16 v[84:87], v[204:207], v[236:239], v[84:87]
	v_mfma_f32_16x16x32_bf16 v[80:83], v[212:215], v[236:239], v[80:83]
	v_mfma_f32_16x16x32_bf16 v[68:71], v[204:207], v[244:247], v[68:71]
	v_mfma_f32_16x16x32_bf16 v[64:67], v[212:215], v[244:247], v[64:67]
	v_mfma_f32_16x16x32_bf16 v[116:119], v[208:211], v[224:227], v[116:119]
	v_mfma_f32_16x16x32_bf16 v[112:115], v[216:219], v[224:227], v[112:115]
	v_mfma_f32_16x16x32_bf16 v[100:103], v[208:211], v[232:235], v[100:103]
	v_mfma_f32_16x16x32_bf16 v[96:99], v[216:219], v[232:235], v[96:99]
	v_mfma_f32_16x16x32_bf16 v[84:87], v[208:211], v[240:243], v[84:87]
	v_mfma_f32_16x16x32_bf16 v[80:83], v[216:219], v[240:243], v[80:83]
	v_mfma_f32_16x16x32_bf16 v[68:71], v[208:211], v[248:251], v[68:71]
	v_mfma_f32_16x16x32_bf16 v[64:67], v[216:219], v[248:251], v[64:67]
	s_barrier
	s_add_i32 s4, s4, s33
	v_lshl_add_u64 v[142:143], s[34:35], 0, v[128:129]
	s_mov_b32 m0, s4
	ds_read_b128 v[220:223], v170 offset:16384
	ds_read_b128 v[224:227], v170 offset:17408
	ds_read_b128 v[228:231], v170 offset:18432
	ds_read_b128 v[232:235], v170 offset:19456
	ds_read_b128 v[236:239], v170 offset:20480
	ds_read_b128 v[240:243], v170 offset:21504
	ds_read_b128 v[244:247], v170 offset:22528
	ds_read_b128 v[248:251], v170 offset:23552
	global_load_lds_dwordx4 v[142:143], off
	s_add_i32 m0, s4, 0x2000
	s_add_u32 s4, s34, 0x40000
	v_lshl_add_u64 v[158:159], s[34:35], 0, v[130:131]
	s_addc_u32 s5, s35, 0
	s_add_i32 s45, s45, s33
	global_load_lds_dwordx4 v[158:159], off
	v_lshl_add_u64 v[180:181], s[4:5], 0, v[128:129]
	s_mov_b32 m0, s45
	v_lshl_add_u64 v[202:203], s[64:65], 0, v[130:131]
	global_load_lds_dwordx4 v[180:181], off
	v_lshl_add_u64 v[180:181], s[4:5], 0, v[130:131]
	s_add_i32 m0, s45, 0x2000
	s_nop 0
	global_load_lds_dwordx4 v[180:181], off
	v_lshl_add_u64 v[180:181], s[64:65], 0, v[128:129]
	s_mov_b32 m0, s69
	s_nop 0
	global_load_lds_dwordx4 v[180:181], off
	s_mov_b32 m0, s70
	s_nop 0
	global_load_lds_dwordx4 v[202:203], off
	s_waitcnt vmcnt(8)
	s_waitcnt lgkmcnt(0)
	s_barrier
	v_mfma_f32_16x16x32_bf16 v[60:63], v[138:141], v[220:223], v[60:63]
	v_mfma_f32_16x16x32_bf16 v[56:59], v[172:175], v[220:223], v[56:59]
	v_mfma_f32_16x16x32_bf16 v[44:47], v[138:141], v[228:231], v[44:47]
	v_mfma_f32_16x16x32_bf16 v[40:43], v[172:175], v[228:231], v[40:43]
	v_mfma_f32_16x16x32_bf16 v[28:31], v[138:141], v[236:239], v[28:31]
	v_mfma_f32_16x16x32_bf16 v[24:27], v[172:175], v[236:239], v[24:27]
	v_mfma_f32_16x16x32_bf16 v[12:15], v[138:141], v[244:247], v[12:15]
	v_mfma_f32_16x16x32_bf16 v[8:11], v[172:175], v[244:247], v[8:11]
	v_mfma_f32_16x16x32_bf16 v[60:63], v[154:157], v[224:227], v[60:63]
	v_mfma_f32_16x16x32_bf16 v[56:59], v[176:179], v[224:227], v[56:59]
	v_mfma_f32_16x16x32_bf16 v[44:47], v[154:157], v[232:235], v[44:47]
	v_mfma_f32_16x16x32_bf16 v[40:43], v[176:179], v[232:235], v[40:43]
	v_mfma_f32_16x16x32_bf16 v[28:31], v[154:157], v[240:243], v[28:31]
	v_mfma_f32_16x16x32_bf16 v[24:27], v[176:179], v[240:243], v[24:27]
	v_mfma_f32_16x16x32_bf16 v[12:15], v[154:157], v[248:251], v[12:15]
	v_mfma_f32_16x16x32_bf16 v[8:11], v[176:179], v[248:251], v[8:11]
	v_mfma_f32_16x16x32_bf16 v[52:55], v[204:207], v[220:223], v[52:55]
	v_mfma_f32_16x16x32_bf16 v[48:51], v[212:215], v[220:223], v[48:51]
	v_mfma_f32_16x16x32_bf16 v[36:39], v[204:207], v[228:231], v[36:39]
	v_mfma_f32_16x16x32_bf16 v[32:35], v[212:215], v[228:231], v[32:35]
	v_mfma_f32_16x16x32_bf16 v[20:23], v[204:207], v[236:239], v[20:23]
	v_mfma_f32_16x16x32_bf16 v[16:19], v[212:215], v[236:239], v[16:19]
	v_mfma_f32_16x16x32_bf16 v[4:7], v[204:207], v[244:247], v[4:7]
	v_mfma_f32_16x16x32_bf16 v[0:3], v[212:215], v[244:247], v[0:3]
	v_mfma_f32_16x16x32_bf16 v[52:55], v[208:211], v[224:227], v[52:55]
	v_mfma_f32_16x16x32_bf16 v[48:51], v[216:219], v[224:227], v[48:51]
	v_mfma_f32_16x16x32_bf16 v[36:39], v[208:211], v[232:235], v[36:39]
	v_mfma_f32_16x16x32_bf16 v[32:35], v[216:219], v[232:235], v[32:35]
	v_mfma_f32_16x16x32_bf16 v[20:23], v[208:211], v[240:243], v[20:23]
	v_mfma_f32_16x16x32_bf16 v[16:19], v[216:219], v[240:243], v[16:19]
	v_mfma_f32_16x16x32_bf16 v[4:7], v[208:211], v[248:251], v[4:7]
	v_mfma_f32_16x16x32_bf16 v[0:3], v[216:219], v[248:251], v[0:3]
	s_barrier
	v_add_u32_e32 v144, 0x18000, v160
	ds_read_b128 v[138:141], v144
	ds_read_b128 v[154:157], v144 offset:1024
	ds_read_b128 v[172:175], v144 offset:2048
	ds_read_b128 v[176:179], v144 offset:3072
	v_add_u32_e32 v144, 0x1c000, v160
	ds_read_b128 v[204:207], v144
	ds_read_b128 v[208:211], v144 offset:1024
	ds_read_b128 v[212:215], v144 offset:2048
	ds_read_b128 v[216:219], v144 offset:3072
	ds_read_b128 v[220:223], v170 offset:32768
	ds_read_b128 v[224:227], v170 offset:33792
	ds_read_b128 v[228:231], v170 offset:34816
	ds_read_b128 v[232:235], v170 offset:35840
	ds_read_b128 v[236:239], v170 offset:36864
	ds_read_b128 v[240:243], v170 offset:37888
	ds_read_b128 v[244:247], v170 offset:38912
	ds_read_b128 v[248:251], v170 offset:39936
	s_add_i32 s45, 0, 0x18000
	s_add_i32 s51, 0, 0x1c000
	s_add_u32 s4, s64, 0x40000
	s_addc_u32 s5, s65, 0
	s_mov_b32 m0, s71
	v_lshl_add_u64 v[252:253], s[4:5], 0, v[128:129]
	global_load_lds_dwordx4 v[252:253], off
	v_lshl_add_u64 v[252:253], s[4:5], 0, v[130:131]
	s_mov_b32 m0, s72
	s_nop 0
	global_load_lds_dwordx4 v[252:253], off
	s_waitcnt vmcnt(8)
	s_waitcnt lgkmcnt(0)
	s_barrier
	v_mfma_f32_16x16x32_bf16 v[124:127], v[138:141], v[220:223], v[124:127]
	v_mfma_f32_16x16x32_bf16 v[120:123], v[172:175], v[220:223], v[120:123]
	v_mfma_f32_16x16x32_bf16 v[108:111], v[138:141], v[228:231], v[108:111]
	v_mfma_f32_16x16x32_bf16 v[104:107], v[172:175], v[228:231], v[104:107]
	v_mfma_f32_16x16x32_bf16 v[92:95], v[138:141], v[236:239], v[92:95]
	v_mfma_f32_16x16x32_bf16 v[88:91], v[172:175], v[236:239], v[88:91]
	v_mfma_f32_16x16x32_bf16 v[76:79], v[138:141], v[244:247], v[76:79]
	v_mfma_f32_16x16x32_bf16 v[72:75], v[172:175], v[244:247], v[72:75]
	v_mfma_f32_16x16x32_bf16 v[124:127], v[154:157], v[224:227], v[124:127]
	v_mfma_f32_16x16x32_bf16 v[120:123], v[176:179], v[224:227], v[120:123]
	v_mfma_f32_16x16x32_bf16 v[108:111], v[154:157], v[232:235], v[108:111]
	v_mfma_f32_16x16x32_bf16 v[104:107], v[176:179], v[232:235], v[104:107]
	v_mfma_f32_16x16x32_bf16 v[92:95], v[154:157], v[240:243], v[92:95]
	v_mfma_f32_16x16x32_bf16 v[88:91], v[176:179], v[240:243], v[88:91]
	v_mfma_f32_16x16x32_bf16 v[76:79], v[154:157], v[248:251], v[76:79]
	v_mfma_f32_16x16x32_bf16 v[72:75], v[176:179], v[248:251], v[72:75]
	v_mfma_f32_16x16x32_bf16 v[116:119], v[204:207], v[220:223], v[116:119]
	v_mfma_f32_16x16x32_bf16 v[112:115], v[212:215], v[220:223], v[112:115]
	v_mfma_f32_16x16x32_bf16 v[100:103], v[204:207], v[228:231], v[100:103]
	v_mfma_f32_16x16x32_bf16 v[96:99], v[212:215], v[228:231], v[96:99]
	v_mfma_f32_16x16x32_bf16 v[84:87], v[204:207], v[236:239], v[84:87]
	v_mfma_f32_16x16x32_bf16 v[80:83], v[212:215], v[236:239], v[80:83]
	v_mfma_f32_16x16x32_bf16 v[68:71], v[204:207], v[244:247], v[68:71]
	v_mfma_f32_16x16x32_bf16 v[64:67], v[212:215], v[244:247], v[64:67]
	v_mfma_f32_16x16x32_bf16 v[116:119], v[208:211], v[224:227], v[116:119]
	v_mfma_f32_16x16x32_bf16 v[112:115], v[216:219], v[224:227], v[112:115]
	v_mfma_f32_16x16x32_bf16 v[100:103], v[208:211], v[232:235], v[100:103]
	v_mfma_f32_16x16x32_bf16 v[96:99], v[216:219], v[232:235], v[96:99]
	v_mfma_f32_16x16x32_bf16 v[84:87], v[208:211], v[240:243], v[84:87]
	v_mfma_f32_16x16x32_bf16 v[80:83], v[216:219], v[240:243], v[80:83]
	v_mfma_f32_16x16x32_bf16 v[68:71], v[208:211], v[248:251], v[68:71]
	v_mfma_f32_16x16x32_bf16 v[64:67], v[216:219], v[248:251], v[64:67]
	s_barrier
	s_add_i32 s4, s45, s33
	v_lshl_add_u64 v[142:143], v[142:143], 0, s[26:27]
	s_mov_b32 m0, s4
	ds_read_b128 v[220:223], v170 offset:49152
	ds_read_b128 v[224:227], v170 offset:50176
	ds_read_b128 v[228:231], v170 offset:51200
	ds_read_b128 v[232:235], v170 offset:52224
	ds_read_b128 v[236:239], v170 offset:53248
	ds_read_b128 v[240:243], v170 offset:54272
	ds_read_b128 v[244:247], v170 offset:55296
	ds_read_b128 v[248:251], v170 offset:56320
	global_load_lds_dwordx4 v[142:143], off
	s_add_i32 m0, s4, 0x2000
	s_add_u32 s4, s34, 0x40080
	v_lshl_add_u64 v[142:143], v[158:159], 0, s[26:27]
	s_addc_u32 s5, s35, 0
	s_add_i32 s34, s51, s33
	global_load_lds_dwordx4 v[142:143], off
	v_lshl_add_u64 v[142:143], s[4:5], 0, v[128:129]
	s_mov_b32 m0, s34
	s_nop 0
	global_load_lds_dwordx4 v[142:143], off
	v_lshl_add_u64 v[142:143], s[4:5], 0, v[130:131]
	s_add_i32 m0, s34, 0x2000
	s_nop 0
	global_load_lds_dwordx4 v[142:143], off
	v_lshl_add_u64 v[142:143], v[180:181], 0, s[26:27]
	s_mov_b32 m0, s73
	s_nop 0
	global_load_lds_dwordx4 v[142:143], off
	v_lshl_add_u64 v[142:143], v[202:203], 0, s[26:27]
	s_mov_b32 m0, s74
	s_nop 0
	global_load_lds_dwordx4 v[142:143], off
	s_add_i32 s29, s29, 2
	s_add_u32 s3, s3, 0x100
	s_addc_u32 s28, s28, 0
	s_cmp_gt_u32 s29, 13
	s_mov_b64 s[60:61], s[62:63]
	s_waitcnt vmcnt(8)
	s_waitcnt lgkmcnt(0)
	s_barrier
	v_mfma_f32_16x16x32_bf16 v[60:63], v[138:141], v[220:223], v[60:63]
	v_mfma_f32_16x16x32_bf16 v[56:59], v[172:175], v[220:223], v[56:59]
	v_mfma_f32_16x16x32_bf16 v[44:47], v[138:141], v[228:231], v[44:47]
	v_mfma_f32_16x16x32_bf16 v[40:43], v[172:175], v[228:231], v[40:43]
	v_mfma_f32_16x16x32_bf16 v[28:31], v[138:141], v[236:239], v[28:31]
	v_mfma_f32_16x16x32_bf16 v[24:27], v[172:175], v[236:239], v[24:27]
	v_mfma_f32_16x16x32_bf16 v[12:15], v[138:141], v[244:247], v[12:15]
	v_mfma_f32_16x16x32_bf16 v[8:11], v[172:175], v[244:247], v[8:11]
	v_mfma_f32_16x16x32_bf16 v[60:63], v[154:157], v[224:227], v[60:63]
	v_mfma_f32_16x16x32_bf16 v[56:59], v[176:179], v[224:227], v[56:59]
	v_mfma_f32_16x16x32_bf16 v[44:47], v[154:157], v[232:235], v[44:47]
	v_mfma_f32_16x16x32_bf16 v[40:43], v[176:179], v[232:235], v[40:43]
	v_mfma_f32_16x16x32_bf16 v[28:31], v[154:157], v[240:243], v[28:31]
	v_mfma_f32_16x16x32_bf16 v[24:27], v[176:179], v[240:243], v[24:27]
	v_mfma_f32_16x16x32_bf16 v[12:15], v[154:157], v[248:251], v[12:15]
	v_mfma_f32_16x16x32_bf16 v[8:11], v[176:179], v[248:251], v[8:11]
	v_mfma_f32_16x16x32_bf16 v[52:55], v[204:207], v[220:223], v[52:55]
	v_mfma_f32_16x16x32_bf16 v[48:51], v[212:215], v[220:223], v[48:51]
	v_mfma_f32_16x16x32_bf16 v[36:39], v[204:207], v[228:231], v[36:39]
	v_mfma_f32_16x16x32_bf16 v[32:35], v[212:215], v[228:231], v[32:35]
	v_mfma_f32_16x16x32_bf16 v[20:23], v[204:207], v[236:239], v[20:23]
	v_mfma_f32_16x16x32_bf16 v[16:19], v[212:215], v[236:239], v[16:19]
	v_mfma_f32_16x16x32_bf16 v[4:7], v[204:207], v[244:247], v[4:7]
	v_mfma_f32_16x16x32_bf16 v[0:3], v[212:215], v[244:247], v[0:3]
	v_mfma_f32_16x16x32_bf16 v[52:55], v[208:211], v[224:227], v[52:55]
	v_mfma_f32_16x16x32_bf16 v[48:51], v[216:219], v[224:227], v[48:51]
	v_mfma_f32_16x16x32_bf16 v[36:39], v[208:211], v[232:235], v[36:39]
	v_mfma_f32_16x16x32_bf16 v[32:35], v[216:219], v[232:235], v[32:35]
	v_mfma_f32_16x16x32_bf16 v[20:23], v[208:211], v[240:243], v[20:23]
	v_mfma_f32_16x16x32_bf16 v[16:19], v[216:219], v[240:243], v[16:19]
	v_mfma_f32_16x16x32_bf16 v[4:7], v[208:211], v[248:251], v[4:7]
	v_mfma_f32_16x16x32_bf16 v[0:3], v[216:219], v[248:251], v[0:3]
	s_barrier
	s_cbranch_scc0 .LBB0_1207
	s_and_b64 vcc, exec, s[48:49]
	s_cbranch_vccz .LBB0_1210
	s_barrier

.LBB0_1305:
	v_add_u32_e32 v164, 0x10000, v143
	v_add_u32_e32 v180, 0x14000, v143
	ds_read_b128 v[138:141], v164
	ds_read_b128 v[156:159], v164 offset:1024
	ds_read_b128 v[160:163], v164 offset:2048
	ds_read_b128 v[164:167], v164 offset:3072
	ds_read_b128 v[168:171], v180
	ds_read_b128 v[172:175], v180 offset:1024
	ds_read_b128 v[176:179], v180 offset:2048
	ds_read_b128 v[204:207], v180 offset:3072
	ds_read_b128 v[208:211], v155
	ds_read_b128 v[212:215], v155 offset:1024
	ds_read_b128 v[216:219], v155 offset:2048
	ds_read_b128 v[220:223], v155 offset:3072
	ds_read_b128 v[224:227], v155 offset:4096
	ds_read_b128 v[228:231], v155 offset:5120
	ds_read_b128 v[232:235], v155 offset:6144
	ds_read_b128 v[236:239], v155 offset:7168
	s_add_u32 s4, s2, 0xfffc0080
	s_addc_u32 s5, s3, -1
	s_add_i32 s74, 0, 0x10000
	s_cmp_eq_u32 s73, 12
	s_cselect_b32 s61, s36, s5
	s_cselect_b32 s60, s51, s4
	s_cselect_b32 s35, s49, s72
	s_cselect_b32 s34, s70, s71
	s_add_i32 s75, 0, 0x14000
	v_lshl_add_u64 v[180:181], s[2:3], 0, v[134:135]
	s_add_i32 m0, s59, 0xc000
	s_nop 0
	global_load_lds_dwordx4 v[180:181], off
	v_lshl_add_u64 v[180:181], s[2:3], 0, v[136:137]
	s_add_i32 m0, s59, 0xe000
	s_nop 0
	global_load_lds_dwordx4 v[180:181], off
	s_waitcnt vmcnt(8)
	s_waitcnt lgkmcnt(0)
	s_barrier
	v_mfma_f32_16x16x32_bf16 v[124:127], v[138:141], v[208:211], v[124:127]
	v_mfma_f32_16x16x32_bf16 v[120:123], v[160:163], v[208:211], v[120:123]
	v_mfma_f32_16x16x32_bf16 v[108:111], v[138:141], v[216:219], v[108:111]
	v_mfma_f32_16x16x32_bf16 v[104:107], v[160:163], v[216:219], v[104:107]
	v_mfma_f32_16x16x32_bf16 v[92:95], v[138:141], v[224:227], v[92:95]
	v_mfma_f32_16x16x32_bf16 v[88:91], v[160:163], v[224:227], v[88:91]
	v_mfma_f32_16x16x32_bf16 v[76:79], v[138:141], v[232:235], v[76:79]
	v_mfma_f32_16x16x32_bf16 v[72:75], v[160:163], v[232:235], v[72:75]
	v_mfma_f32_16x16x32_bf16 v[124:127], v[156:159], v[212:215], v[124:127]
	v_mfma_f32_16x16x32_bf16 v[120:123], v[164:167], v[212:215], v[120:123]
	v_mfma_f32_16x16x32_bf16 v[108:111], v[156:159], v[220:223], v[108:111]
	v_mfma_f32_16x16x32_bf16 v[104:107], v[164:167], v[220:223], v[104:107]
	v_mfma_f32_16x16x32_bf16 v[92:95], v[156:159], v[228:231], v[92:95]
	v_mfma_f32_16x16x32_bf16 v[88:91], v[164:167], v[228:231], v[88:91]
	v_mfma_f32_16x16x32_bf16 v[76:79], v[156:159], v[236:239], v[76:79]
	v_mfma_f32_16x16x32_bf16 v[72:75], v[164:167], v[236:239], v[72:75]
	v_mfma_f32_16x16x32_bf16 v[116:119], v[168:171], v[208:211], v[116:119]
	v_mfma_f32_16x16x32_bf16 v[112:115], v[176:179], v[208:211], v[112:115]
	v_mfma_f32_16x16x32_bf16 v[100:103], v[168:171], v[216:219], v[100:103]
	v_mfma_f32_16x16x32_bf16 v[96:99], v[176:179], v[216:219], v[96:99]
	v_mfma_f32_16x16x32_bf16 v[84:87], v[168:171], v[224:227], v[84:87]
	v_mfma_f32_16x16x32_bf16 v[80:83], v[176:179], v[224:227], v[80:83]
	v_mfma_f32_16x16x32_bf16 v[68:71], v[168:171], v[232:235], v[68:71]
	v_mfma_f32_16x16x32_bf16 v[64:67], v[176:179], v[232:235], v[64:67]
	v_mfma_f32_16x16x32_bf16 v[116:119], v[172:175], v[212:215], v[116:119]
	v_mfma_f32_16x16x32_bf16 v[112:115], v[204:207], v[212:215], v[112:115]
	v_mfma_f32_16x16x32_bf16 v[100:103], v[172:175], v[220:223], v[100:103]
	v_mfma_f32_16x16x32_bf16 v[96:99], v[204:207], v[220:223], v[96:99]
	v_mfma_f32_16x16x32_bf16 v[84:87], v[172:175], v[228:231], v[84:87]
	v_mfma_f32_16x16x32_bf16 v[80:83], v[204:207], v[228:231], v[80:83]
	v_mfma_f32_16x16x32_bf16 v[68:71], v[172:175], v[236:239], v[68:71]
	v_mfma_f32_16x16x32_bf16 v[64:67], v[204:207], v[236:239], v[64:67]
	s_barrier
	s_add_i32 s4, s74, s1
	v_lshl_add_u64 v[180:181], s[34:35], 0, v[144:145]
	s_mov_b32 m0, s4
	ds_read_b128 v[208:211], v155 offset:16384
	ds_read_b128 v[212:215], v155 offset:17408
	ds_read_b128 v[216:219], v155 offset:18432
	ds_read_b128 v[220:223], v155 offset:19456
	ds_read_b128 v[224:227], v155 offset:20480
	ds_read_b128 v[228:231], v155 offset:21504
	ds_read_b128 v[232:235], v155 offset:22528
	ds_read_b128 v[236:239], v155 offset:23552
	global_load_lds_dwordx4 v[180:181], off
	s_add_i32 m0, s4, 0x2000
	s_add_u32 s4, s34, 0x40000
	v_lshl_add_u64 v[202:203], s[34:35], 0, v[128:129]
	s_addc_u32 s5, s35, 0
	s_add_i32 s74, s75, s1
	global_load_lds_dwordx4 v[202:203], off
	v_lshl_add_u64 v[240:241], s[4:5], 0, v[144:145]
	s_mov_b32 m0, s74
	v_lshl_add_u64 v[242:243], s[60:61], 0, v[130:131]
	global_load_lds_dwordx4 v[240:241], off
	v_lshl_add_u64 v[240:241], s[4:5], 0, v[128:129]
	s_add_i32 m0, s74, 0x2000
	s_nop 0
	global_load_lds_dwordx4 v[240:241], off
	v_lshl_add_u64 v[240:241], s[60:61], 0, v[132:133]
	s_mov_b32 m0, s59
	s_nop 0
	global_load_lds_dwordx4 v[240:241], off
	s_mov_b32 m0, s64
	s_nop 0
	global_load_lds_dwordx4 v[242:243], off
	s_waitcnt vmcnt(8)
	s_waitcnt lgkmcnt(0)
	s_barrier
	v_mfma_f32_16x16x32_bf16 v[60:63], v[138:141], v[208:211], v[60:63]
	v_mfma_f32_16x16x32_bf16 v[56:59], v[160:163], v[208:211], v[56:59]
	v_mfma_f32_16x16x32_bf16 v[44:47], v[138:141], v[216:219], v[44:47]
	v_mfma_f32_16x16x32_bf16 v[40:43], v[160:163], v[216:219], v[40:43]
	v_mfma_f32_16x16x32_bf16 v[28:31], v[138:141], v[224:227], v[28:31]
	v_mfma_f32_16x16x32_bf16 v[24:27], v[160:163], v[224:227], v[24:27]
	v_mfma_f32_16x16x32_bf16 v[12:15], v[138:141], v[232:235], v[12:15]
	v_mfma_f32_16x16x32_bf16 v[8:11], v[160:163], v[232:235], v[8:11]
	v_mfma_f32_16x16x32_bf16 v[60:63], v[156:159], v[212:215], v[60:63]
	v_mfma_f32_16x16x32_bf16 v[56:59], v[164:167], v[212:215], v[56:59]
	v_mfma_f32_16x16x32_bf16 v[44:47], v[156:159], v[220:223], v[44:47]
	v_mfma_f32_16x16x32_bf16 v[40:43], v[164:167], v[220:223], v[40:43]
	v_mfma_f32_16x16x32_bf16 v[28:31], v[156:159], v[228:231], v[28:31]
	v_mfma_f32_16x16x32_bf16 v[24:27], v[164:167], v[228:231], v[24:27]
	v_mfma_f32_16x16x32_bf16 v[12:15], v[156:159], v[236:239], v[12:15]
	v_mfma_f32_16x16x32_bf16 v[8:11], v[164:167], v[236:239], v[8:11]
	v_mfma_f32_16x16x32_bf16 v[52:55], v[168:171], v[208:211], v[52:55]
	v_mfma_f32_16x16x32_bf16 v[48:51], v[176:179], v[208:211], v[48:51]
	v_mfma_f32_16x16x32_bf16 v[36:39], v[168:171], v[216:219], v[36:39]
	v_mfma_f32_16x16x32_bf16 v[32:35], v[176:179], v[216:219], v[32:35]
	v_mfma_f32_16x16x32_bf16 v[20:23], v[168:171], v[224:227], v[20:23]
	v_mfma_f32_16x16x32_bf16 v[16:19], v[176:179], v[224:227], v[16:19]
	v_mfma_f32_16x16x32_bf16 v[4:7], v[168:171], v[232:235], v[4:7]
	v_mfma_f32_16x16x32_bf16 v[0:3], v[176:179], v[232:235], v[0:3]
	v_mfma_f32_16x16x32_bf16 v[52:55], v[172:175], v[212:215], v[52:55]
	v_mfma_f32_16x16x32_bf16 v[48:51], v[204:207], v[212:215], v[48:51]
	v_mfma_f32_16x16x32_bf16 v[36:39], v[172:175], v[220:223], v[36:39]
	v_mfma_f32_16x16x32_bf16 v[32:35], v[204:207], v[220:223], v[32:35]
	v_mfma_f32_16x16x32_bf16 v[20:23], v[172:175], v[228:231], v[20:23]
	v_mfma_f32_16x16x32_bf16 v[16:19], v[204:207], v[228:231], v[16:19]
	v_mfma_f32_16x16x32_bf16 v[4:7], v[172:175], v[236:239], v[4:7]
	v_mfma_f32_16x16x32_bf16 v[0:3], v[204:207], v[236:239], v[0:3]
	s_barrier
	v_add_u32_e32 v164, 0x18000, v143
	v_add_u32_e32 v204, 0x1c000, v143
	ds_read_b128 v[138:141], v164
	ds_read_b128 v[156:159], v164 offset:1024
	ds_read_b128 v[160:163], v164 offset:2048
	ds_read_b128 v[164:167], v164 offset:3072
	ds_read_b128 v[168:171], v204
	ds_read_b128 v[172:175], v204 offset:1024
	ds_read_b128 v[176:179], v204 offset:2048
	ds_read_b128 v[204:207], v204 offset:3072
	ds_read_b128 v[208:211], v155 offset:32768
	ds_read_b128 v[212:215], v155 offset:33792
	ds_read_b128 v[216:219], v155 offset:34816
	ds_read_b128 v[220:223], v155 offset:35840
	ds_read_b128 v[224:227], v155 offset:36864
	ds_read_b128 v[228:231], v155 offset:37888
	ds_read_b128 v[232:235], v155 offset:38912
	ds_read_b128 v[236:239], v155 offset:39936
	s_add_i32 s74, 0, 0x18000
	s_add_i32 s75, 0, 0x1c000
	s_add_u32 s4, s60, 0x40000
	s_addc_u32 s5, s61, 0
	s_mov_b32 m0, s65
	v_lshl_add_u64 v[244:245], s[4:5], 0, v[132:133]
	global_load_lds_dwordx4 v[244:245], off
	v_lshl_add_u64 v[244:245], s[4:5], 0, v[130:131]
	s_mov_b32 m0, s66
	s_nop 0
	global_load_lds_dwordx4 v[244:245], off
	s_waitcnt vmcnt(8)
	s_waitcnt lgkmcnt(0)
	s_barrier
	v_mfma_f32_16x16x32_bf16 v[124:127], v[138:141], v[208:211], v[124:127]
	v_mfma_f32_16x16x32_bf16 v[120:123], v[160:163], v[208:211], v[120:123]
	v_mfma_f32_16x16x32_bf16 v[108:111], v[138:141], v[216:219], v[108:111]
	v_mfma_f32_16x16x32_bf16 v[104:107], v[160:163], v[216:219], v[104:107]
	v_mfma_f32_16x16x32_bf16 v[92:95], v[138:141], v[224:227], v[92:95]
	v_mfma_f32_16x16x32_bf16 v[88:91], v[160:163], v[224:227], v[88:91]
	v_mfma_f32_16x16x32_bf16 v[76:79], v[138:141], v[232:235], v[76:79]
	v_mfma_f32_16x16x32_bf16 v[72:75], v[160:163], v[232:235], v[72:75]
	v_mfma_f32_16x16x32_bf16 v[124:127], v[156:159], v[212:215], v[124:127]
	v_mfma_f32_16x16x32_bf16 v[120:123], v[164:167], v[212:215], v[120:123]
	v_mfma_f32_16x16x32_bf16 v[108:111], v[156:159], v[220:223], v[108:111]
	v_mfma_f32_16x16x32_bf16 v[104:107], v[164:167], v[220:223], v[104:107]
	v_mfma_f32_16x16x32_bf16 v[92:95], v[156:159], v[228:231], v[92:95]
	v_mfma_f32_16x16x32_bf16 v[88:91], v[164:167], v[228:231], v[88:91]
	v_mfma_f32_16x16x32_bf16 v[76:79], v[156:159], v[236:239], v[76:79]
	v_mfma_f32_16x16x32_bf16 v[72:75], v[164:167], v[236:239], v[72:75]
	v_mfma_f32_16x16x32_bf16 v[116:119], v[168:171], v[208:211], v[116:119]
	v_mfma_f32_16x16x32_bf16 v[112:115], v[176:179], v[208:211], v[112:115]
	v_mfma_f32_16x16x32_bf16 v[100:103], v[168:171], v[216:219], v[100:103]
	v_mfma_f32_16x16x32_bf16 v[96:99], v[176:179], v[216:219], v[96:99]
	v_mfma_f32_16x16x32_bf16 v[84:87], v[168:171], v[224:227], v[84:87]
	v_mfma_f32_16x16x32_bf16 v[80:83], v[176:179], v[224:227], v[80:83]
	v_mfma_f32_16x16x32_bf16 v[68:71], v[168:171], v[232:235], v[68:71]
	v_mfma_f32_16x16x32_bf16 v[64:67], v[176:179], v[232:235], v[64:67]
	v_mfma_f32_16x16x32_bf16 v[116:119], v[172:175], v[212:215], v[116:119]
	v_mfma_f32_16x16x32_bf16 v[112:115], v[204:207], v[212:215], v[112:115]
	v_mfma_f32_16x16x32_bf16 v[100:103], v[172:175], v[220:223], v[100:103]
	v_mfma_f32_16x16x32_bf16 v[96:99], v[204:207], v[220:223], v[96:99]
	v_mfma_f32_16x16x32_bf16 v[84:87], v[172:175], v[228:231], v[84:87]
	v_mfma_f32_16x16x32_bf16 v[80:83], v[204:207], v[228:231], v[80:83]
	v_mfma_f32_16x16x32_bf16 v[68:71], v[172:175], v[236:239], v[68:71]
	v_mfma_f32_16x16x32_bf16 v[64:67], v[204:207], v[236:239], v[64:67]
	s_barrier
	s_add_i32 s4, s74, s1
	v_lshl_add_u64 v[180:181], v[180:181], 0, s[26:27]
	s_mov_b32 m0, s4
	ds_read_b128 v[208:211], v155 offset:49152
	ds_read_b128 v[212:215], v155 offset:50176
	ds_read_b128 v[216:219], v155 offset:51200
	ds_read_b128 v[220:223], v155 offset:52224
	ds_read_b128 v[224:227], v155 offset:53248
	ds_read_b128 v[228:231], v155 offset:54272
	ds_read_b128 v[232:235], v155 offset:55296
	ds_read_b128 v[236:239], v155 offset:56320
	global_load_lds_dwordx4 v[180:181], off
	s_add_i32 m0, s4, 0x2000
	s_add_u32 s4, s34, 0x40080
	v_lshl_add_u64 v[180:181], v[202:203], 0, s[26:27]
	s_addc_u32 s5, s35, 0
	s_add_i32 s34, s75, s1
	global_load_lds_dwordx4 v[180:181], off
	v_lshl_add_u64 v[180:181], s[4:5], 0, v[144:145]
	s_mov_b32 m0, s34
	s_nop 0
	global_load_lds_dwordx4 v[180:181], off
	v_lshl_add_u64 v[180:181], s[4:5], 0, v[128:129]
	s_add_i32 m0, s34, 0x2000
	s_nop 0
	global_load_lds_dwordx4 v[180:181], off
	v_lshl_add_u64 v[180:181], v[240:241], 0, s[26:27]
	s_mov_b32 m0, s67
	s_nop 0
	global_load_lds_dwordx4 v[180:181], off
	v_lshl_add_u64 v[180:181], v[242:243], 0, s[26:27]
	s_mov_b32 m0, s68
	s_nop 0
	global_load_lds_dwordx4 v[180:181], off
	s_add_i32 s73, s73, 2
	s_add_u32 s2, s2, 0x100
	s_addc_u32 s3, s3, 0
	s_add_u32 s71, s71, 0x100
	s_addc_u32 s72, s72, 0
	s_cmp_gt_u32 s73, 13
	s_waitcnt vmcnt(8)
	s_waitcnt lgkmcnt(0)
	s_barrier
	v_mfma_f32_16x16x32_bf16 v[60:63], v[138:141], v[208:211], v[60:63]
	v_mfma_f32_16x16x32_bf16 v[56:59], v[160:163], v[208:211], v[56:59]
	v_mfma_f32_16x16x32_bf16 v[44:47], v[138:141], v[216:219], v[44:47]
	v_mfma_f32_16x16x32_bf16 v[40:43], v[160:163], v[216:219], v[40:43]
	v_mfma_f32_16x16x32_bf16 v[28:31], v[138:141], v[224:227], v[28:31]
	v_mfma_f32_16x16x32_bf16 v[24:27], v[160:163], v[224:227], v[24:27]
	v_mfma_f32_16x16x32_bf16 v[12:15], v[138:141], v[232:235], v[12:15]
	v_mfma_f32_16x16x32_bf16 v[8:11], v[160:163], v[232:235], v[8:11]
	v_mfma_f32_16x16x32_bf16 v[60:63], v[156:159], v[212:215], v[60:63]
	v_mfma_f32_16x16x32_bf16 v[56:59], v[164:167], v[212:215], v[56:59]
	v_mfma_f32_16x16x32_bf16 v[44:47], v[156:159], v[220:223], v[44:47]
	v_mfma_f32_16x16x32_bf16 v[40:43], v[164:167], v[220:223], v[40:43]
	v_mfma_f32_16x16x32_bf16 v[28:31], v[156:159], v[228:231], v[28:31]
	v_mfma_f32_16x16x32_bf16 v[24:27], v[164:167], v[228:231], v[24:27]
	v_mfma_f32_16x16x32_bf16 v[12:15], v[156:159], v[236:239], v[12:15]
	v_mfma_f32_16x16x32_bf16 v[8:11], v[164:167], v[236:239], v[8:11]
	v_mfma_f32_16x16x32_bf16 v[52:55], v[168:171], v[208:211], v[52:55]
	v_mfma_f32_16x16x32_bf16 v[48:51], v[176:179], v[208:211], v[48:51]
	v_mfma_f32_16x16x32_bf16 v[36:39], v[168:171], v[216:219], v[36:39]
	v_mfma_f32_16x16x32_bf16 v[32:35], v[176:179], v[216:219], v[32:35]
	v_mfma_f32_16x16x32_bf16 v[20:23], v[168:171], v[224:227], v[20:23]
	v_mfma_f32_16x16x32_bf16 v[16:19], v[176:179], v[224:227], v[16:19]
	v_mfma_f32_16x16x32_bf16 v[4:7], v[168:171], v[232:235], v[4:7]
	v_mfma_f32_16x16x32_bf16 v[0:3], v[176:179], v[232:235], v[0:3]
	v_mfma_f32_16x16x32_bf16 v[52:55], v[172:175], v[212:215], v[52:55]
	v_mfma_f32_16x16x32_bf16 v[48:51], v[204:207], v[212:215], v[48:51]
	v_mfma_f32_16x16x32_bf16 v[36:39], v[172:175], v[220:223], v[36:39]
	v_mfma_f32_16x16x32_bf16 v[32:35], v[204:207], v[220:223], v[32:35]
	v_mfma_f32_16x16x32_bf16 v[20:23], v[172:175], v[228:231], v[20:23]
	v_mfma_f32_16x16x32_bf16 v[16:19], v[204:207], v[228:231], v[16:19]
	v_mfma_f32_16x16x32_bf16 v[4:7], v[172:175], v[236:239], v[4:7]
	v_mfma_f32_16x16x32_bf16 v[0:3], v[204:207], v[236:239], v[0:3]
	s_barrier
	s_cbranch_scc0 .LBB0_1305
	v_lshl_add_u32 v140, s58, 8, v142
	v_ashrrev_i32_e32 v141, 31, v140
	v_lshl_add_u64 v[156:157], v[140:141], 4, s[44:45]
	global_load_dwordx4 v[208:211], v[156:157], off
	global_load_dwordx4 v[212:215], v[156:157], off offset:256
	global_load_dwordx4 v[216:219], v[156:157], off offset:512
	global_load_dwordx4 v[220:223], v[156:157], off offset:768
	global_load_dwordx4 v[224:227], v[156:157], off offset:2048
	global_load_dwordx4 v[228:231], v[156:157], off offset:2304
	global_load_dwordx4 v[232:235], v[156:157], off offset:2560
	global_load_dwordx4 v[236:239], v[156:157], off offset:2816
	s_and_b64 vcc, exec, s[46:47]
	s_cbranch_vccz .LBB0_1308
	s_barrier

.LBB0_1399:
	v_add_u32_e32 v142, 0x10000, v160
	ds_read_b128 v[138:141], v142
	ds_read_b128 v[154:157], v142 offset:1024
	ds_read_b128 v[172:175], v142 offset:2048
	ds_read_b128 v[176:179], v142 offset:3072
	v_add_u32_e32 v142, 0x14000, v160
	ds_read_b128 v[204:207], v142
	ds_read_b128 v[208:211], v142 offset:1024
	ds_read_b128 v[212:215], v142 offset:2048
	ds_read_b128 v[216:219], v142 offset:3072
	ds_read_b128 v[220:223], v170
	ds_read_b128 v[224:227], v170 offset:1024
	ds_read_b128 v[228:231], v170 offset:2048
	ds_read_b128 v[232:235], v170 offset:3072
	ds_read_b128 v[236:239], v170 offset:4096
	ds_read_b128 v[240:243], v170 offset:5120
	ds_read_b128 v[244:247], v170 offset:6144
	ds_read_b128 v[248:251], v170 offset:7168
	s_add_u32 s58, s54, 0x100
	s_addc_u32 s59, s55, 0
	s_add_i32 s4, 0, 0x10000
	s_cmp_eq_u32 s29, 40
	s_cselect_b32 s61, s45, s59
	s_cselect_b32 s60, s44, s58
	s_cselect_b32 s35, s53, s28
	s_cselect_b32 s34, s52, s3
	s_add_i32 s47, 0, 0x14000
	v_lshl_add_u64 v[142:143], s[54:55], 0, v[134:135]
	s_add_i32 m0, s65, 0xc000
	s_nop 0
	global_load_lds_dwordx4 v[142:143], off
	v_lshl_add_u64 v[142:143], s[54:55], 0, v[136:137]
	s_add_i32 m0, s65, 0xe000
	s_nop 0
	global_load_lds_dwordx4 v[142:143], off
	s_waitcnt vmcnt(8)
	s_waitcnt lgkmcnt(0)
	s_barrier
	v_mfma_f32_16x16x32_bf16 v[124:127], v[138:141], v[220:223], v[124:127]
	v_mfma_f32_16x16x32_bf16 v[120:123], v[172:175], v[220:223], v[120:123]
	v_mfma_f32_16x16x32_bf16 v[108:111], v[138:141], v[228:231], v[108:111]
	v_mfma_f32_16x16x32_bf16 v[104:107], v[172:175], v[228:231], v[104:107]
	v_mfma_f32_16x16x32_bf16 v[92:95], v[138:141], v[236:239], v[92:95]
	v_mfma_f32_16x16x32_bf16 v[88:91], v[172:175], v[236:239], v[88:91]
	v_mfma_f32_16x16x32_bf16 v[76:79], v[138:141], v[244:247], v[76:79]
	v_mfma_f32_16x16x32_bf16 v[72:75], v[172:175], v[244:247], v[72:75]
	v_mfma_f32_16x16x32_bf16 v[124:127], v[154:157], v[224:227], v[124:127]
	v_mfma_f32_16x16x32_bf16 v[120:123], v[176:179], v[224:227], v[120:123]
	v_mfma_f32_16x16x32_bf16 v[108:111], v[154:157], v[232:235], v[108:111]
	v_mfma_f32_16x16x32_bf16 v[104:107], v[176:179], v[232:235], v[104:107]
	v_mfma_f32_16x16x32_bf16 v[92:95], v[154:157], v[240:243], v[92:95]
	v_mfma_f32_16x16x32_bf16 v[88:91], v[176:179], v[240:243], v[88:91]
	v_mfma_f32_16x16x32_bf16 v[76:79], v[154:157], v[248:251], v[76:79]
	v_mfma_f32_16x16x32_bf16 v[72:75], v[176:179], v[248:251], v[72:75]
	v_mfma_f32_16x16x32_bf16 v[116:119], v[204:207], v[220:223], v[116:119]
	v_mfma_f32_16x16x32_bf16 v[112:115], v[212:215], v[220:223], v[112:115]
	v_mfma_f32_16x16x32_bf16 v[100:103], v[204:207], v[228:231], v[100:103]
	v_mfma_f32_16x16x32_bf16 v[96:99], v[212:215], v[228:231], v[96:99]
	v_mfma_f32_16x16x32_bf16 v[84:87], v[204:207], v[236:239], v[84:87]
	v_mfma_f32_16x16x32_bf16 v[80:83], v[212:215], v[236:239], v[80:83]
	v_mfma_f32_16x16x32_bf16 v[68:71], v[204:207], v[244:247], v[68:71]
	v_mfma_f32_16x16x32_bf16 v[64:67], v[212:215], v[244:247], v[64:67]
	v_mfma_f32_16x16x32_bf16 v[116:119], v[208:211], v[224:227], v[116:119]
	v_mfma_f32_16x16x32_bf16 v[112:115], v[216:219], v[224:227], v[112:115]
	v_mfma_f32_16x16x32_bf16 v[100:103], v[208:211], v[232:235], v[100:103]
	v_mfma_f32_16x16x32_bf16 v[96:99], v[216:219], v[232:235], v[96:99]
	v_mfma_f32_16x16x32_bf16 v[84:87], v[208:211], v[240:243], v[84:87]
	v_mfma_f32_16x16x32_bf16 v[80:83], v[216:219], v[240:243], v[80:83]
	v_mfma_f32_16x16x32_bf16 v[68:71], v[208:211], v[248:251], v[68:71]
	v_mfma_f32_16x16x32_bf16 v[64:67], v[216:219], v[248:251], v[64:67]
	s_barrier
	s_add_i32 s4, s4, s33
	v_lshl_add_u64 v[142:143], s[34:35], 0, v[128:129]
	s_mov_b32 m0, s4
	ds_read_b128 v[220:223], v170 offset:16384
	ds_read_b128 v[224:227], v170 offset:17408
	ds_read_b128 v[228:231], v170 offset:18432
	ds_read_b128 v[232:235], v170 offset:19456
	ds_read_b128 v[236:239], v170 offset:20480
	ds_read_b128 v[240:243], v170 offset:21504
	ds_read_b128 v[244:247], v170 offset:22528
	ds_read_b128 v[248:251], v170 offset:23552
	global_load_lds_dwordx4 v[142:143], off
	s_add_i32 m0, s4, 0x2000
	s_add_u32 s4, s34, 0xb0000
	v_lshl_add_u64 v[158:159], s[34:35], 0, v[130:131]
	s_addc_u32 s5, s35, 0
	s_add_i32 s47, s47, s33
	global_load_lds_dwordx4 v[158:159], off
	v_lshl_add_u64 v[180:181], s[4:5], 0, v[128:129]
	s_mov_b32 m0, s47
	v_lshl_add_u64 v[202:203], s[60:61], 0, v[130:131]
	global_load_lds_dwordx4 v[180:181], off
	v_lshl_add_u64 v[180:181], s[4:5], 0, v[130:131]
	s_add_i32 m0, s47, 0x2000
	s_nop 0
	global_load_lds_dwordx4 v[180:181], off
	v_lshl_add_u64 v[180:181], s[60:61], 0, v[128:129]
	s_mov_b32 m0, s65
	s_nop 0
	global_load_lds_dwordx4 v[180:181], off
	s_mov_b32 m0, s66
	s_nop 0
	global_load_lds_dwordx4 v[202:203], off
	s_waitcnt vmcnt(8)
	s_waitcnt lgkmcnt(0)
	s_barrier
	v_mfma_f32_16x16x32_bf16 v[60:63], v[138:141], v[220:223], v[60:63]
	v_mfma_f32_16x16x32_bf16 v[56:59], v[172:175], v[220:223], v[56:59]
	v_mfma_f32_16x16x32_bf16 v[44:47], v[138:141], v[228:231], v[44:47]
	v_mfma_f32_16x16x32_bf16 v[40:43], v[172:175], v[228:231], v[40:43]
	v_mfma_f32_16x16x32_bf16 v[28:31], v[138:141], v[236:239], v[28:31]
	v_mfma_f32_16x16x32_bf16 v[24:27], v[172:175], v[236:239], v[24:27]
	v_mfma_f32_16x16x32_bf16 v[12:15], v[138:141], v[244:247], v[12:15]
	v_mfma_f32_16x16x32_bf16 v[8:11], v[172:175], v[244:247], v[8:11]
	v_mfma_f32_16x16x32_bf16 v[60:63], v[154:157], v[224:227], v[60:63]
	v_mfma_f32_16x16x32_bf16 v[56:59], v[176:179], v[224:227], v[56:59]
	v_mfma_f32_16x16x32_bf16 v[44:47], v[154:157], v[232:235], v[44:47]
	v_mfma_f32_16x16x32_bf16 v[40:43], v[176:179], v[232:235], v[40:43]
	v_mfma_f32_16x16x32_bf16 v[28:31], v[154:157], v[240:243], v[28:31]
	v_mfma_f32_16x16x32_bf16 v[24:27], v[176:179], v[240:243], v[24:27]
	v_mfma_f32_16x16x32_bf16 v[12:15], v[154:157], v[248:251], v[12:15]
	v_mfma_f32_16x16x32_bf16 v[8:11], v[176:179], v[248:251], v[8:11]
	v_mfma_f32_16x16x32_bf16 v[52:55], v[204:207], v[220:223], v[52:55]
	v_mfma_f32_16x16x32_bf16 v[48:51], v[212:215], v[220:223], v[48:51]
	v_mfma_f32_16x16x32_bf16 v[36:39], v[204:207], v[228:231], v[36:39]
	v_mfma_f32_16x16x32_bf16 v[32:35], v[212:215], v[228:231], v[32:35]
	v_mfma_f32_16x16x32_bf16 v[20:23], v[204:207], v[236:239], v[20:23]
	v_mfma_f32_16x16x32_bf16 v[16:19], v[212:215], v[236:239], v[16:19]
	v_mfma_f32_16x16x32_bf16 v[4:7], v[204:207], v[244:247], v[4:7]
	v_mfma_f32_16x16x32_bf16 v[0:3], v[212:215], v[244:247], v[0:3]
	v_mfma_f32_16x16x32_bf16 v[52:55], v[208:211], v[224:227], v[52:55]
	v_mfma_f32_16x16x32_bf16 v[48:51], v[216:219], v[224:227], v[48:51]
	v_mfma_f32_16x16x32_bf16 v[36:39], v[208:211], v[232:235], v[36:39]
	v_mfma_f32_16x16x32_bf16 v[32:35], v[216:219], v[232:235], v[32:35]
	v_mfma_f32_16x16x32_bf16 v[20:23], v[208:211], v[240:243], v[20:23]
	v_mfma_f32_16x16x32_bf16 v[16:19], v[216:219], v[240:243], v[16:19]
	v_mfma_f32_16x16x32_bf16 v[4:7], v[208:211], v[248:251], v[4:7]
	v_mfma_f32_16x16x32_bf16 v[0:3], v[216:219], v[248:251], v[0:3]
	s_barrier
	v_add_u32_e32 v144, 0x18000, v160
	ds_read_b128 v[138:141], v144
	ds_read_b128 v[154:157], v144 offset:1024
	ds_read_b128 v[172:175], v144 offset:2048
	ds_read_b128 v[176:179], v144 offset:3072
	v_add_u32_e32 v144, 0x1c000, v160
	ds_read_b128 v[204:207], v144
	ds_read_b128 v[208:211], v144 offset:1024
	ds_read_b128 v[212:215], v144 offset:2048
	ds_read_b128 v[216:219], v144 offset:3072
	ds_read_b128 v[220:223], v170 offset:32768
	ds_read_b128 v[224:227], v170 offset:33792
	ds_read_b128 v[228:231], v170 offset:34816
	ds_read_b128 v[232:235], v170 offset:35840
	ds_read_b128 v[236:239], v170 offset:36864
	ds_read_b128 v[240:243], v170 offset:37888
	ds_read_b128 v[244:247], v170 offset:38912
	ds_read_b128 v[248:251], v170 offset:39936
	s_add_i32 s47, 0, 0x18000
	s_add_i32 s54, 0, 0x1c000
	s_add_u32 s4, s60, 0xb0000
	s_addc_u32 s5, s61, 0
	s_mov_b32 m0, s67
	v_lshl_add_u64 v[252:253], s[4:5], 0, v[128:129]
	global_load_lds_dwordx4 v[252:253], off
	v_lshl_add_u64 v[252:253], s[4:5], 0, v[130:131]
	s_mov_b32 m0, s68
	s_nop 0
	global_load_lds_dwordx4 v[252:253], off
	s_waitcnt vmcnt(8)
	s_waitcnt lgkmcnt(0)
	s_barrier
	v_mfma_f32_16x16x32_bf16 v[124:127], v[138:141], v[220:223], v[124:127]
	v_mfma_f32_16x16x32_bf16 v[120:123], v[172:175], v[220:223], v[120:123]
	v_mfma_f32_16x16x32_bf16 v[108:111], v[138:141], v[228:231], v[108:111]
	v_mfma_f32_16x16x32_bf16 v[104:107], v[172:175], v[228:231], v[104:107]
	v_mfma_f32_16x16x32_bf16 v[92:95], v[138:141], v[236:239], v[92:95]
	v_mfma_f32_16x16x32_bf16 v[88:91], v[172:175], v[236:239], v[88:91]
	v_mfma_f32_16x16x32_bf16 v[76:79], v[138:141], v[244:247], v[76:79]
	v_mfma_f32_16x16x32_bf16 v[72:75], v[172:175], v[244:247], v[72:75]
	v_mfma_f32_16x16x32_bf16 v[124:127], v[154:157], v[224:227], v[124:127]
	v_mfma_f32_16x16x32_bf16 v[120:123], v[176:179], v[224:227], v[120:123]
	v_mfma_f32_16x16x32_bf16 v[108:111], v[154:157], v[232:235], v[108:111]
	v_mfma_f32_16x16x32_bf16 v[104:107], v[176:179], v[232:235], v[104:107]
	v_mfma_f32_16x16x32_bf16 v[92:95], v[154:157], v[240:243], v[92:95]
	v_mfma_f32_16x16x32_bf16 v[88:91], v[176:179], v[240:243], v[88:91]
	v_mfma_f32_16x16x32_bf16 v[76:79], v[154:157], v[248:251], v[76:79]
	v_mfma_f32_16x16x32_bf16 v[72:75], v[176:179], v[248:251], v[72:75]
	v_mfma_f32_16x16x32_bf16 v[116:119], v[204:207], v[220:223], v[116:119]
	v_mfma_f32_16x16x32_bf16 v[112:115], v[212:215], v[220:223], v[112:115]
	v_mfma_f32_16x16x32_bf16 v[100:103], v[204:207], v[228:231], v[100:103]
	v_mfma_f32_16x16x32_bf16 v[96:99], v[212:215], v[228:231], v[96:99]
	v_mfma_f32_16x16x32_bf16 v[84:87], v[204:207], v[236:239], v[84:87]
	v_mfma_f32_16x16x32_bf16 v[80:83], v[212:215], v[236:239], v[80:83]
	v_mfma_f32_16x16x32_bf16 v[68:71], v[204:207], v[244:247], v[68:71]
	v_mfma_f32_16x16x32_bf16 v[64:67], v[212:215], v[244:247], v[64:67]
	v_mfma_f32_16x16x32_bf16 v[116:119], v[208:211], v[224:227], v[116:119]
	v_mfma_f32_16x16x32_bf16 v[112:115], v[216:219], v[224:227], v[112:115]
	v_mfma_f32_16x16x32_bf16 v[100:103], v[208:211], v[232:235], v[100:103]
	v_mfma_f32_16x16x32_bf16 v[96:99], v[216:219], v[232:235], v[96:99]
	v_mfma_f32_16x16x32_bf16 v[84:87], v[208:211], v[240:243], v[84:87]
	v_mfma_f32_16x16x32_bf16 v[80:83], v[216:219], v[240:243], v[80:83]
	v_mfma_f32_16x16x32_bf16 v[68:71], v[208:211], v[248:251], v[68:71]
	v_mfma_f32_16x16x32_bf16 v[64:67], v[216:219], v[248:251], v[64:67]
	s_barrier
	s_add_i32 s4, s47, s33
	v_lshl_add_u64 v[142:143], v[142:143], 0, s[26:27]
	s_mov_b32 m0, s4
	ds_read_b128 v[220:223], v170 offset:49152
	ds_read_b128 v[224:227], v170 offset:50176
	ds_read_b128 v[228:231], v170 offset:51200
	ds_read_b128 v[232:235], v170 offset:52224
	ds_read_b128 v[236:239], v170 offset:53248
	ds_read_b128 v[240:243], v170 offset:54272
	ds_read_b128 v[244:247], v170 offset:55296
	ds_read_b128 v[248:251], v170 offset:56320
	global_load_lds_dwordx4 v[142:143], off
	s_add_i32 m0, s4, 0x2000
	s_add_u32 s4, s34, 0xb0080
	v_lshl_add_u64 v[142:143], v[158:159], 0, s[26:27]
	s_addc_u32 s5, s35, 0
	s_add_i32 s34, s54, s33
	global_load_lds_dwordx4 v[142:143], off
	v_lshl_add_u64 v[142:143], s[4:5], 0, v[128:129]
	s_mov_b32 m0, s34
	s_nop 0
	global_load_lds_dwordx4 v[142:143], off
	v_lshl_add_u64 v[142:143], s[4:5], 0, v[130:131]
	s_add_i32 m0, s34, 0x2000
	s_nop 0
	global_load_lds_dwordx4 v[142:143], off
	v_lshl_add_u64 v[142:143], v[180:181], 0, s[26:27]
	s_mov_b32 m0, s69
	s_nop 0
	global_load_lds_dwordx4 v[142:143], off
	v_lshl_add_u64 v[142:143], v[202:203], 0, s[26:27]
	s_mov_b32 m0, s70
	s_nop 0
	global_load_lds_dwordx4 v[142:143], off
	s_add_i32 s29, s29, 2
	s_add_u32 s3, s3, 0x100
	s_addc_u32 s28, s28, 0
	s_cmp_gt_u32 s29, 41
	s_mov_b64 s[54:55], s[58:59]
	s_waitcnt vmcnt(8)
	s_waitcnt lgkmcnt(0)
	s_barrier
	v_mfma_f32_16x16x32_bf16 v[60:63], v[138:141], v[220:223], v[60:63]
	v_mfma_f32_16x16x32_bf16 v[56:59], v[172:175], v[220:223], v[56:59]
	v_mfma_f32_16x16x32_bf16 v[44:47], v[138:141], v[228:231], v[44:47]
	v_mfma_f32_16x16x32_bf16 v[40:43], v[172:175], v[228:231], v[40:43]
	v_mfma_f32_16x16x32_bf16 v[28:31], v[138:141], v[236:239], v[28:31]
	v_mfma_f32_16x16x32_bf16 v[24:27], v[172:175], v[236:239], v[24:27]
	v_mfma_f32_16x16x32_bf16 v[12:15], v[138:141], v[244:247], v[12:15]
	v_mfma_f32_16x16x32_bf16 v[8:11], v[172:175], v[244:247], v[8:11]
	v_mfma_f32_16x16x32_bf16 v[60:63], v[154:157], v[224:227], v[60:63]
	v_mfma_f32_16x16x32_bf16 v[56:59], v[176:179], v[224:227], v[56:59]
	v_mfma_f32_16x16x32_bf16 v[44:47], v[154:157], v[232:235], v[44:47]
	v_mfma_f32_16x16x32_bf16 v[40:43], v[176:179], v[232:235], v[40:43]
	v_mfma_f32_16x16x32_bf16 v[28:31], v[154:157], v[240:243], v[28:31]
	v_mfma_f32_16x16x32_bf16 v[24:27], v[176:179], v[240:243], v[24:27]
	v_mfma_f32_16x16x32_bf16 v[12:15], v[154:157], v[248:251], v[12:15]
	v_mfma_f32_16x16x32_bf16 v[8:11], v[176:179], v[248:251], v[8:11]
	v_mfma_f32_16x16x32_bf16 v[52:55], v[204:207], v[220:223], v[52:55]
	v_mfma_f32_16x16x32_bf16 v[48:51], v[212:215], v[220:223], v[48:51]
	v_mfma_f32_16x16x32_bf16 v[36:39], v[204:207], v[228:231], v[36:39]
	v_mfma_f32_16x16x32_bf16 v[32:35], v[212:215], v[228:231], v[32:35]
	v_mfma_f32_16x16x32_bf16 v[20:23], v[204:207], v[236:239], v[20:23]
	v_mfma_f32_16x16x32_bf16 v[16:19], v[212:215], v[236:239], v[16:19]
	v_mfma_f32_16x16x32_bf16 v[4:7], v[204:207], v[244:247], v[4:7]
	v_mfma_f32_16x16x32_bf16 v[0:3], v[212:215], v[244:247], v[0:3]
	v_mfma_f32_16x16x32_bf16 v[52:55], v[208:211], v[224:227], v[52:55]
	v_mfma_f32_16x16x32_bf16 v[48:51], v[216:219], v[224:227], v[48:51]
	v_mfma_f32_16x16x32_bf16 v[36:39], v[208:211], v[232:235], v[36:39]
	v_mfma_f32_16x16x32_bf16 v[32:35], v[216:219], v[232:235], v[32:35]
	v_mfma_f32_16x16x32_bf16 v[20:23], v[208:211], v[240:243], v[20:23]
	v_mfma_f32_16x16x32_bf16 v[16:19], v[216:219], v[240:243], v[16:19]
	v_mfma_f32_16x16x32_bf16 v[4:7], v[208:211], v[248:251], v[4:7]
	v_mfma_f32_16x16x32_bf16 v[0:3], v[216:219], v[248:251], v[0:3]
	s_barrier
	s_cbranch_scc0 .LBB0_1399
	s_and_b64 vcc, exec, s[50:51]
	s_cbranch_vccz .LBB0_1402
	s_barrier
